# gates GEMM epilogue: 8 XC tile loads hoisted to epilogue start, per-row-group vmcnt(0) waits removed
# baseline (speedup 1.0000x reference)
; __device__ __forceinline__ unsigned cvt_pk_bf16(float lo, float hi) { unsigned r; asm volatile("v_cvt_pk_bf16_f32 %0, %1, %2" : "=v"(r) : "v"(lo), "v"(hi)); return r; }
; __device__ __forceinline__ void x_half(KA a, int grp, int half, int lane, f32x4& acc, float& ss) {
;     ...
;     const int row0 = grp * 16, r = lane & 15, quad = lane >> 4, kbase = half * 1024;
;     const float* xr = x + (size_t)(row0 + r) * D_ + quad * 8 + kbase; bf16_t* br = XB + (size_t)(row0 + r) * D_ + quad * 8 + kbase;
;     const float* wp = W + (size_t)(kbase + quad * 8) * 6160 + 6144 + r; const float* gp = gmix + kbase + quad * 8;
;     acc = (f32x4){0.f, 0.f, 0.f, 0.f}; ss = 0.f;
; #pragma unroll 4
;     for (int k0 = 0; k0 < 1024; k0 += 32) {
;         const f32x4 a0 = *(const f32x4*)(xr + k0), a1 = *(const f32x4*)(xr + k0 + 4);
;         ss += (a0[0] * a0[0] + a0[1] * a0[1]) + (a0[2] * a0[2] + a0[3] * a0[3]) + (a1[0] * a1[0] + a1[1] * a1[1]) + (a1[2] * a1[2] + a1[3] * a1[3]);
;         u32x4 aw; aw.x = cvt_pk_bf16(a0[0], a0[1]); aw.y = cvt_pk_bf16(a0[2], a0[3]); aw.z = cvt_pk_bf16(a1[0], a1[1]); aw.w = cvt_pk_bf16(a1[2], a1[3]);
;         *(u32x4*)(br + k0) = aw;
;         const f32x4 g0 = *(const f32x4*)(gp + k0), g1 = *(const f32x4*)(gp + k0 + 4);
;         const float* w = wp + (size_t)k0 * 6160;
;         u32x4 bw; bw.x = cvt_pk_bf16(w[0] * g0[0], w[6160] * g0[1]); bw.y = cvt_pk_bf16(w[2 * 6160] * g0[2], w[3 * 6160] * g0[3]);
;         bw.z = cvt_pk_bf16(w[4 * 6160] * g1[0], w[5 * 6160] * g1[1]); bw.w = cvt_pk_bf16(w[6 * 6160] * g1[2], w[7 * 6160] * g1[3]);
;         acc = __builtin_amdgcn_mfma_f32_16x16x32_bf16(__builtin_bit_cast(bf16x8, aw), __builtin_bit_cast(bf16x8, bw), acc, 0, 0, 0);
;     }
.LBB0_9:
	v_ashrrev_i32_e32 v67, 31, v66
	v_lshlrev_b64 v[4:5], 13, v[66:67]
	v_lshlrev_b64 v[6:7], 12, v[66:67]
	v_lshl_add_u64 v[4:5], s[8:9], 0, v[4:5]
	v_lshl_add_u64 v[70:71], v[68:69], 0, v[6:7]
	s_movk_i32 s71, 0xffe0
	s_mov_b64 s[26:27], s[10:11]
	v_mov_b64_e32 v[72:73], v[62:63]
	v_mov_b32_e32 v2, 0
	v_mov_b32_e32 v6, 0
	v_mov_b32_e32 v7, v3
	v_mov_b32_e32 v8, v3
	v_mov_b32_e32 v9, v3
	s_load_dwordx2 s[28:29], s[92:93], 0x20
	v_lshl_add_u64 v[4:5], v[4:5], 0, v[64:65]
	v_lshrrev_b32_e32 v26, 4, v167
	v_mul_u32_u24_e32 v26, 0x30200, v26
	v_lshl_add_u32 v26, v79, 2, v26
	v_add_u32_e32 v27, 0x6040, v26
	v_add_u32_e32 v28, 0xc080, v26
	v_add_u32_e32 v29, 0x120c0, v26
	v_add_u32_e32 v30, 0x18100, v26
	v_add_u32_e32 v31, 0x1e140, v26
	v_add_u32_e32 v32, 0x24180, v26
	v_add_u32_e32 v33, 0x2a1c0, v26
	s_lshr_b32 s25, s46, 2
	s_mul_i32 s25, s25, 0x1810000
	s_add_i32 s25, s25, 0x6000
	s_waitcnt vmcnt(0) lgkmcnt(0)
	s_add_u32 s28, s28, s25
	s_addc_u32 s29, s29, 0
	global_load_dwordx4 v[100:103], v[4:5], off
	global_load_dwordx4 v[104:107], v[4:5], off offset:16
	global_load_dwordx4 v[108:111], v64, s[26:27]
	global_load_dwordx4 v[112:115], v64, s[26:27] offset:16
	global_load_dword v116, v26, s[28:29]
	global_load_dword v117, v27, s[28:29]
	global_load_dword v118, v28, s[28:29]
	global_load_dword v119, v29, s[28:29]
	global_load_dword v120, v30, s[28:29]
	global_load_dword v121, v31, s[28:29]
	global_load_dword v122, v32, s[28:29]
	global_load_dword v123, v33, s[28:29]
	s_add_u32 s28, s28, 0xc0800
	s_addc_u32 s29, s29, 0
	global_load_dwordx4 v[124:127], v[4:5], off offset:128
	global_load_dwordx4 v[128:131], v[4:5], off offset:144
	global_load_dwordx4 v[132:135], v64, s[26:27] offset:128
	global_load_dwordx4 v[136:139], v64, s[26:27] offset:144
	global_load_dword v140, v26, s[28:29]
	global_load_dword v141, v27, s[28:29]
	global_load_dword v142, v28, s[28:29]
	global_load_dword v143, v29, s[28:29]
	global_load_dword v144, v30, s[28:29]
	global_load_dword v145, v31, s[28:29]
	global_load_dword v146, v32, s[28:29]
	global_load_dword v147, v33, s[28:29]
	s_add_u32 s28, s28, 0xc0800
	s_addc_u32 s29, s29, 0
	global_load_dwordx4 v[168:171], v[4:5], off offset:256
	global_load_dwordx4 v[172:175], v[4:5], off offset:272
	global_load_dwordx4 v[176:179], v64, s[26:27] offset:256
	global_load_dwordx4 v[180:183], v64, s[26:27] offset:272
	global_load_dword v184, v26, s[28:29]
	global_load_dword v185, v27, s[28:29]
	global_load_dword v186, v28, s[28:29]
	global_load_dword v187, v29, s[28:29]
	global_load_dword v188, v30, s[28:29]
	global_load_dword v189, v31, s[28:29]
	global_load_dword v190, v32, s[28:29]
	global_load_dword v191, v33, s[28:29]
	s_add_u32 s28, s28, 0xc0800
	s_addc_u32 s29, s29, 0
	global_load_dwordx4 v[192:195], v[4:5], off offset:384
	global_load_dwordx4 v[196:199], v[4:5], off offset:400
	global_load_dwordx4 v[200:203], v64, s[26:27] offset:384
	global_load_dwordx4 v[204:207], v64, s[26:27] offset:400
	global_load_dword v208, v26, s[28:29]
	global_load_dword v209, v27, s[28:29]
	global_load_dword v210, v28, s[28:29]
	global_load_dword v211, v29, s[28:29]
	global_load_dword v212, v30, s[28:29]
	global_load_dword v213, v31, s[28:29]
	global_load_dword v214, v32, s[28:29]
	global_load_dword v215, v33, s[28:29]
	s_add_u32 s28, s28, 0xc0800
	s_addc_u32 s29, s29, 0
	s_waitcnt vmcnt(36)
	v_cvt_pk_bf16_f32 v10, v100, v101
	v_cvt_pk_bf16_f32 v11, v102, v103
	v_cvt_pk_bf16_f32 v12, v104, v105
	v_cvt_pk_bf16_f32 v13, v106, v107
	global_store_dwordx4 v[70:71], v[10:13], off offset:-128
	v_mul_f32_e32 v116, v116, v108
	v_mul_f32_e32 v117, v117, v109
	v_mul_f32_e32 v118, v118, v110
	v_mul_f32_e32 v119, v119, v111
	v_mul_f32_e32 v120, v120, v112
	v_mul_f32_e32 v121, v121, v113
	v_mul_f32_e32 v122, v122, v114
	v_mul_f32_e32 v123, v123, v115
	v_cvt_pk_bf16_f32 v14, v116, v117
	v_cvt_pk_bf16_f32 v15, v118, v119
	v_cvt_pk_bf16_f32 v16, v120, v121
	v_cvt_pk_bf16_f32 v17, v122, v123
	v_mul_f32_e32 v100, v100, v100
	v_mul_f32_e32 v101, v101, v101
	v_mul_f32_e32 v102, v102, v102
	v_mul_f32_e32 v103, v103, v103
	v_mul_f32_e32 v104, v104, v104
	v_mul_f32_e32 v105, v105, v105
	v_mul_f32_e32 v106, v106, v106
	v_mul_f32_e32 v107, v107, v107
	v_add_f32_e32 v100, v100, v101
	v_add_f32_e32 v102, v102, v103
	v_add_f32_e32 v100, v100, v102
	v_add_f32_e32 v104, v104, v105
	v_add_f32_e32 v100, v100, v104
	v_add_f32_e32 v106, v106, v107
	v_add_f32_e32 v100, v100, v106
	v_add_f32_e32 v2, v2, v100
	v_mfma_f32_16x16x32_bf16 v[6:9], v[10:13], v[14:17], v[6:9]
	global_load_dwordx4 v[100:103], v[4:5], off offset:512
	global_load_dwordx4 v[104:107], v[4:5], off offset:528
	global_load_dwordx4 v[108:111], v64, s[26:27] offset:512
	global_load_dwordx4 v[112:115], v64, s[26:27] offset:528
	global_load_dword v116, v26, s[28:29]
	global_load_dword v117, v27, s[28:29]
	global_load_dword v118, v28, s[28:29]
	global_load_dword v119, v29, s[28:29]
	global_load_dword v120, v30, s[28:29]
	global_load_dword v121, v31, s[28:29]
	global_load_dword v122, v32, s[28:29]
	global_load_dword v123, v33, s[28:29]
	s_add_u32 s28, s28, 0xc0800
	s_addc_u32 s29, s29, 0
	s_waitcnt vmcnt(36)
; __device__ __forceinline__ unsigned cvt_pk_bf16(float lo, float hi) { unsigned r; asm volatile("v_cvt_pk_bf16_f32 %0, %1, %2" : "=v"(r) : "v"(lo), "v"(hi)); return r; }
; __device__ __forceinline__ void x_half(KA a, int grp, int half, int lane, f32x4& acc, float& ss) {
;     ...
;     for (int k0 = 0; k0 < 1024; k0 += 32) {
;         const f32x4 a0 = *(const f32x4*)(xr + k0), a1 = *(const f32x4*)(xr + k0 + 4);
;         ss += (a0[0] * a0[0] + a0[1] * a0[1]) + (a0[2] * a0[2] + a0[3] * a0[3]) + (a1[0] * a1[0] + a1[1] * a1[1]) + (a1[2] * a1[2] + a1[3] * a1[3]);
;         u32x4 aw; aw.x = cvt_pk_bf16(a0[0], a0[1]); aw.y = cvt_pk_bf16(a0[2], a0[3]); aw.z = cvt_pk_bf16(a1[0], a1[1]); aw.w = cvt_pk_bf16(a1[2], a1[3]);
;         *(u32x4*)(br + k0) = aw;
;         const f32x4 g0 = *(const f32x4*)(gp + k0), g1 = *(const f32x4*)(gp + k0 + 4);
;         const float* w = wp + (size_t)k0 * 6160;
;         u32x4 bw; bw.x = cvt_pk_bf16(w[0] * g0[0], w[6160] * g0[1]); bw.y = cvt_pk_bf16(w[2 * 6160] * g0[2], w[3 * 6160] * g0[3]);
;         bw.z = cvt_pk_bf16(w[4 * 6160] * g1[0], w[5 * 6160] * g1[1]); bw.w = cvt_pk_bf16(w[6 * 6160] * g1[2], w[7 * 6160] * g1[3]);
;         acc = __builtin_amdgcn_mfma_f32_16x16x32_bf16(__builtin_bit_cast(bf16x8, aw), __builtin_bit_cast(bf16x8, bw), acc, 0, 0, 0);
;     }
	v_cvt_pk_bf16_f32 v18, v124, v125
	v_cvt_pk_bf16_f32 v19, v126, v127
	v_cvt_pk_bf16_f32 v20, v128, v129
	v_cvt_pk_bf16_f32 v21, v130, v131
	global_store_dwordx4 v[70:71], v[18:21], off offset:-64
	v_mul_f32_e32 v140, v140, v132
	v_mul_f32_e32 v141, v141, v133
	v_mul_f32_e32 v142, v142, v134
	v_mul_f32_e32 v143, v143, v135
	v_mul_f32_e32 v144, v144, v136
	v_mul_f32_e32 v145, v145, v137
	v_mul_f32_e32 v146, v146, v138
	v_mul_f32_e32 v147, v147, v139
	v_cvt_pk_bf16_f32 v22, v140, v141
	v_cvt_pk_bf16_f32 v23, v142, v143
	v_cvt_pk_bf16_f32 v24, v144, v145
	v_cvt_pk_bf16_f32 v25, v146, v147
	v_mul_f32_e32 v124, v124, v124
	v_mul_f32_e32 v125, v125, v125
	v_mul_f32_e32 v126, v126, v126
	v_mul_f32_e32 v127, v127, v127
	v_mul_f32_e32 v128, v128, v128
	v_mul_f32_e32 v129, v129, v129
	v_mul_f32_e32 v130, v130, v130
	v_mul_f32_e32 v131, v131, v131
	v_add_f32_e32 v124, v124, v125
	v_add_f32_e32 v126, v126, v127
	v_add_f32_e32 v124, v124, v126
	v_add_f32_e32 v128, v128, v129
	v_add_f32_e32 v124, v124, v128
	v_add_f32_e32 v130, v130, v131
	v_add_f32_e32 v124, v124, v130
	v_add_f32_e32 v2, v2, v124
	v_mfma_f32_16x16x32_bf16 v[6:9], v[18:21], v[22:25], v[6:9]
	global_load_dwordx4 v[124:127], v[4:5], off offset:640
	global_load_dwordx4 v[128:131], v[4:5], off offset:656
	global_load_dwordx4 v[132:135], v64, s[26:27] offset:640
	global_load_dwordx4 v[136:139], v64, s[26:27] offset:656
	global_load_dword v140, v26, s[28:29]
	global_load_dword v141, v27, s[28:29]
	global_load_dword v142, v28, s[28:29]
	global_load_dword v143, v29, s[28:29]
	global_load_dword v144, v30, s[28:29]
	global_load_dword v145, v31, s[28:29]
	global_load_dword v146, v32, s[28:29]
	global_load_dword v147, v33, s[28:29]
	s_add_u32 s28, s28, 0xc0800
	s_addc_u32 s29, s29, 0
	s_waitcnt vmcnt(36)
	v_cvt_pk_bf16_f32 v10, v168, v169
	v_cvt_pk_bf16_f32 v11, v170, v171
	v_cvt_pk_bf16_f32 v12, v172, v173
	v_cvt_pk_bf16_f32 v13, v174, v175
	global_store_dwordx4 v[70:71], v[10:13], off
	v_mul_f32_e32 v184, v184, v176
	v_mul_f32_e32 v185, v185, v177
	v_mul_f32_e32 v186, v186, v178
	v_mul_f32_e32 v187, v187, v179
	v_mul_f32_e32 v188, v188, v180
	v_mul_f32_e32 v189, v189, v181
	v_mul_f32_e32 v190, v190, v182
	v_mul_f32_e32 v191, v191, v183
	v_cvt_pk_bf16_f32 v14, v184, v185
	v_cvt_pk_bf16_f32 v15, v186, v187
	v_cvt_pk_bf16_f32 v16, v188, v189
	v_cvt_pk_bf16_f32 v17, v190, v191
	v_mul_f32_e32 v168, v168, v168
	v_mul_f32_e32 v169, v169, v169
	v_mul_f32_e32 v170, v170, v170
	v_mul_f32_e32 v171, v171, v171
	v_mul_f32_e32 v172, v172, v172
	v_mul_f32_e32 v173, v173, v173
	v_mul_f32_e32 v174, v174, v174
	v_mul_f32_e32 v175, v175, v175
	v_add_f32_e32 v168, v168, v169
	v_add_f32_e32 v170, v170, v171
	v_add_f32_e32 v168, v168, v170
	v_add_f32_e32 v172, v172, v173
	v_add_f32_e32 v168, v168, v172
	v_add_f32_e32 v174, v174, v175
	v_add_f32_e32 v168, v168, v174
	v_add_f32_e32 v2, v2, v168
	v_mfma_f32_16x16x32_bf16 v[6:9], v[10:13], v[14:17], v[6:9]
	global_load_dwordx4 v[168:171], v[4:5], off offset:768
	global_load_dwordx4 v[172:175], v[4:5], off offset:784
	global_load_dwordx4 v[176:179], v64, s[26:27] offset:768
	global_load_dwordx4 v[180:183], v64, s[26:27] offset:784
	global_load_dword v184, v26, s[28:29]
	global_load_dword v185, v27, s[28:29]
	global_load_dword v186, v28, s[28:29]
	global_load_dword v187, v29, s[28:29]
	global_load_dword v188, v30, s[28:29]
	global_load_dword v189, v31, s[28:29]
	global_load_dword v190, v32, s[28:29]
	global_load_dword v191, v33, s[28:29]
	s_add_u32 s28, s28, 0xc0800
	s_addc_u32 s29, s29, 0
	s_waitcnt vmcnt(36)
	v_cvt_pk_bf16_f32 v18, v192, v193
	v_cvt_pk_bf16_f32 v19, v194, v195
	v_cvt_pk_bf16_f32 v20, v196, v197
	v_cvt_pk_bf16_f32 v21, v198, v199
	global_store_dwordx4 v[70:71], v[18:21], off offset:64
	v_mul_f32_e32 v208, v208, v200
	v_mul_f32_e32 v209, v209, v201
	v_mul_f32_e32 v210, v210, v202
	v_mul_f32_e32 v211, v211, v203
	v_mul_f32_e32 v212, v212, v204
	v_mul_f32_e32 v213, v213, v205
	v_mul_f32_e32 v214, v214, v206
	v_mul_f32_e32 v215, v215, v207
	v_cvt_pk_bf16_f32 v22, v208, v209
	v_cvt_pk_bf16_f32 v23, v210, v211
	v_cvt_pk_bf16_f32 v24, v212, v213
	v_cvt_pk_bf16_f32 v25, v214, v215
	v_mul_f32_e32 v192, v192, v192
	v_mul_f32_e32 v193, v193, v193
	v_mul_f32_e32 v194, v194, v194
	v_mul_f32_e32 v195, v195, v195
	v_mul_f32_e32 v196, v196, v196
	v_mul_f32_e32 v197, v197, v197
	v_mul_f32_e32 v198, v198, v198
	v_mul_f32_e32 v199, v199, v199
	v_add_f32_e32 v192, v192, v193
	v_add_f32_e32 v194, v194, v195
	v_add_f32_e32 v192, v192, v194
	v_add_f32_e32 v196, v196, v197
	v_add_f32_e32 v192, v192, v196
	v_add_f32_e32 v198, v198, v199
	v_add_f32_e32 v192, v192, v198
	v_add_f32_e32 v2, v2, v192
	v_mfma_f32_16x16x32_bf16 v[6:9], v[18:21], v[22:25], v[6:9]
	global_load_dwordx4 v[192:195], v[4:5], off offset:896
	global_load_dwordx4 v[196:199], v[4:5], off offset:912
	global_load_dwordx4 v[200:203], v64, s[26:27] offset:896
	global_load_dwordx4 v[204:207], v64, s[26:27] offset:912
	global_load_dword v208, v26, s[28:29]
	global_load_dword v209, v27, s[28:29]
	global_load_dword v210, v28, s[28:29]
	global_load_dword v211, v29, s[28:29]
	global_load_dword v212, v30, s[28:29]
	global_load_dword v213, v31, s[28:29]
	global_load_dword v214, v32, s[28:29]
	global_load_dword v215, v33, s[28:29]
	s_add_u32 s28, s28, 0xc0800
	s_addc_u32 s29, s29, 0
	v_lshl_add_u64 v[4:5], v[4:5], 0, s[14:15]
	s_add_u32 s26, s26, 0x200
	s_addc_u32 s27, s27, 0
	v_lshl_add_u64 v[70:71], v[70:71], 0, s[22:23]
	s_waitcnt vmcnt(36)
; __device__ __forceinline__ unsigned cvt_pk_bf16(float lo, float hi) { unsigned r; asm volatile("v_cvt_pk_bf16_f32 %0, %1, %2" : "=v"(r) : "v"(lo), "v"(hi)); return r; }
; __device__ __forceinline__ void x_half(KA a, int grp, int half, int lane, f32x4& acc, float& ss) {
;     ...
;     for (int k0 = 0; k0 < 1024; k0 += 32) {
;         const f32x4 a0 = *(const f32x4*)(xr + k0), a1 = *(const f32x4*)(xr + k0 + 4);
;         ss += (a0[0] * a0[0] + a0[1] * a0[1]) + (a0[2] * a0[2] + a0[3] * a0[3]) + (a1[0] * a1[0] + a1[1] * a1[1]) + (a1[2] * a1[2] + a1[3] * a1[3]);
;         u32x4 aw; aw.x = cvt_pk_bf16(a0[0], a0[1]); aw.y = cvt_pk_bf16(a0[2], a0[3]); aw.z = cvt_pk_bf16(a1[0], a1[1]); aw.w = cvt_pk_bf16(a1[2], a1[3]);
;         *(u32x4*)(br + k0) = aw;
;         const f32x4 g0 = *(const f32x4*)(gp + k0), g1 = *(const f32x4*)(gp + k0 + 4);
;         const float* w = wp + (size_t)k0 * 6160;
;         u32x4 bw; bw.x = cvt_pk_bf16(w[0] * g0[0], w[6160] * g0[1]); bw.y = cvt_pk_bf16(w[2 * 6160] * g0[2], w[3 * 6160] * g0[3]);
;         bw.z = cvt_pk_bf16(w[4 * 6160] * g1[0], w[5 * 6160] * g1[1]); bw.w = cvt_pk_bf16(w[6 * 6160] * g1[2], w[7 * 6160] * g1[3]);
;         acc = __builtin_amdgcn_mfma_f32_16x16x32_bf16(__builtin_bit_cast(bf16x8, aw), __builtin_bit_cast(bf16x8, bw), acc, 0, 0, 0);
;     }
	v_cvt_pk_bf16_f32 v10, v100, v101
	v_cvt_pk_bf16_f32 v11, v102, v103
	v_cvt_pk_bf16_f32 v12, v104, v105
	v_cvt_pk_bf16_f32 v13, v106, v107
	global_store_dwordx4 v[70:71], v[10:13], off offset:-128
	v_mul_f32_e32 v116, v116, v108
	v_mul_f32_e32 v117, v117, v109
	v_mul_f32_e32 v118, v118, v110
	v_mul_f32_e32 v119, v119, v111
	v_mul_f32_e32 v120, v120, v112
	v_mul_f32_e32 v121, v121, v113
	v_mul_f32_e32 v122, v122, v114
	v_mul_f32_e32 v123, v123, v115
	v_cvt_pk_bf16_f32 v14, v116, v117
	v_cvt_pk_bf16_f32 v15, v118, v119
	v_cvt_pk_bf16_f32 v16, v120, v121
	v_cvt_pk_bf16_f32 v17, v122, v123
	v_mul_f32_e32 v100, v100, v100
	v_mul_f32_e32 v101, v101, v101
	v_mul_f32_e32 v102, v102, v102
	v_mul_f32_e32 v103, v103, v103
	v_mul_f32_e32 v104, v104, v104
	v_mul_f32_e32 v105, v105, v105
	v_mul_f32_e32 v106, v106, v106
	v_mul_f32_e32 v107, v107, v107
	v_add_f32_e32 v100, v100, v101
	v_add_f32_e32 v102, v102, v103
	v_add_f32_e32 v100, v100, v102
	v_add_f32_e32 v104, v104, v105
	v_add_f32_e32 v100, v100, v104
	v_add_f32_e32 v106, v106, v107
	v_add_f32_e32 v100, v100, v106
	v_add_f32_e32 v2, v2, v100
	v_mfma_f32_16x16x32_bf16 v[6:9], v[10:13], v[14:17], v[6:9]
	global_load_dwordx4 v[100:103], v[4:5], off offset:512
	global_load_dwordx4 v[104:107], v[4:5], off offset:528
	global_load_dwordx4 v[108:111], v64, s[26:27] offset:512
	global_load_dwordx4 v[112:115], v64, s[26:27] offset:528
	global_load_dword v116, v26, s[28:29]
	global_load_dword v117, v27, s[28:29]
	global_load_dword v118, v28, s[28:29]
	global_load_dword v119, v29, s[28:29]
	global_load_dword v120, v30, s[28:29]
	global_load_dword v121, v31, s[28:29]
	global_load_dword v122, v32, s[28:29]
	global_load_dword v123, v33, s[28:29]
	s_add_u32 s28, s28, 0xc0800
	s_addc_u32 s29, s29, 0
	s_waitcnt vmcnt(36)
	v_cvt_pk_bf16_f32 v18, v124, v125
	v_cvt_pk_bf16_f32 v19, v126, v127
	v_cvt_pk_bf16_f32 v20, v128, v129
	v_cvt_pk_bf16_f32 v21, v130, v131
	global_store_dwordx4 v[70:71], v[18:21], off offset:-64
	v_mul_f32_e32 v140, v140, v132
	v_mul_f32_e32 v141, v141, v133
	v_mul_f32_e32 v142, v142, v134
	v_mul_f32_e32 v143, v143, v135
	v_mul_f32_e32 v144, v144, v136
	v_mul_f32_e32 v145, v145, v137
	v_mul_f32_e32 v146, v146, v138
	v_mul_f32_e32 v147, v147, v139
	v_cvt_pk_bf16_f32 v22, v140, v141
	v_cvt_pk_bf16_f32 v23, v142, v143
	v_cvt_pk_bf16_f32 v24, v144, v145
	v_cvt_pk_bf16_f32 v25, v146, v147
	v_mul_f32_e32 v124, v124, v124
	v_mul_f32_e32 v125, v125, v125
	v_mul_f32_e32 v126, v126, v126
	v_mul_f32_e32 v127, v127, v127
	v_mul_f32_e32 v128, v128, v128
	v_mul_f32_e32 v129, v129, v129
	v_mul_f32_e32 v130, v130, v130
	v_mul_f32_e32 v131, v131, v131
	v_add_f32_e32 v124, v124, v125
	v_add_f32_e32 v126, v126, v127
	v_add_f32_e32 v124, v124, v126
	v_add_f32_e32 v128, v128, v129
	v_add_f32_e32 v124, v124, v128
	v_add_f32_e32 v130, v130, v131
	v_add_f32_e32 v124, v124, v130
	v_add_f32_e32 v2, v2, v124
	v_mfma_f32_16x16x32_bf16 v[6:9], v[18:21], v[22:25], v[6:9]
	global_load_dwordx4 v[124:127], v[4:5], off offset:640
	global_load_dwordx4 v[128:131], v[4:5], off offset:656
	global_load_dwordx4 v[132:135], v64, s[26:27] offset:640
	global_load_dwordx4 v[136:139], v64, s[26:27] offset:656
	global_load_dword v140, v26, s[28:29]
	global_load_dword v141, v27, s[28:29]
	global_load_dword v142, v28, s[28:29]
	global_load_dword v143, v29, s[28:29]
	global_load_dword v144, v30, s[28:29]
	global_load_dword v145, v31, s[28:29]
	global_load_dword v146, v32, s[28:29]
	global_load_dword v147, v33, s[28:29]
	s_add_u32 s28, s28, 0xc0800
	s_addc_u32 s29, s29, 0
	s_waitcnt vmcnt(36)
	v_cvt_pk_bf16_f32 v10, v168, v169
	v_cvt_pk_bf16_f32 v11, v170, v171
	v_cvt_pk_bf16_f32 v12, v172, v173
	v_cvt_pk_bf16_f32 v13, v174, v175
	global_store_dwordx4 v[70:71], v[10:13], off
	v_mul_f32_e32 v184, v184, v176
	v_mul_f32_e32 v185, v185, v177
	v_mul_f32_e32 v186, v186, v178
	v_mul_f32_e32 v187, v187, v179
	v_mul_f32_e32 v188, v188, v180
	v_mul_f32_e32 v189, v189, v181
	v_mul_f32_e32 v190, v190, v182
	v_mul_f32_e32 v191, v191, v183
	v_cvt_pk_bf16_f32 v14, v184, v185
	v_cvt_pk_bf16_f32 v15, v186, v187
	v_cvt_pk_bf16_f32 v16, v188, v189
	v_cvt_pk_bf16_f32 v17, v190, v191
	v_mul_f32_e32 v168, v168, v168
	v_mul_f32_e32 v169, v169, v169
	v_mul_f32_e32 v170, v170, v170
	v_mul_f32_e32 v171, v171, v171
	v_mul_f32_e32 v172, v172, v172
	v_mul_f32_e32 v173, v173, v173
	v_mul_f32_e32 v174, v174, v174
	v_mul_f32_e32 v175, v175, v175
	v_add_f32_e32 v168, v168, v169
	v_add_f32_e32 v170, v170, v171
	v_add_f32_e32 v168, v168, v170
	v_add_f32_e32 v172, v172, v173
	v_add_f32_e32 v168, v168, v172
	v_add_f32_e32 v174, v174, v175
	v_add_f32_e32 v168, v168, v174
	v_add_f32_e32 v2, v2, v168
	v_mfma_f32_16x16x32_bf16 v[6:9], v[10:13], v[14:17], v[6:9]
	global_load_dwordx4 v[168:171], v[4:5], off offset:768
	global_load_dwordx4 v[172:175], v[4:5], off offset:784
	global_load_dwordx4 v[176:179], v64, s[26:27] offset:768
	global_load_dwordx4 v[180:183], v64, s[26:27] offset:784
	global_load_dword v184, v26, s[28:29]
	global_load_dword v185, v27, s[28:29]
	global_load_dword v186, v28, s[28:29]
	global_load_dword v187, v29, s[28:29]
	global_load_dword v188, v30, s[28:29]
	global_load_dword v189, v31, s[28:29]
	global_load_dword v190, v32, s[28:29]
	global_load_dword v191, v33, s[28:29]
	s_add_u32 s28, s28, 0xc0800
	s_addc_u32 s29, s29, 0
	s_waitcnt vmcnt(36)
; __device__ __forceinline__ unsigned cvt_pk_bf16(float lo, float hi) { unsigned r; asm volatile("v_cvt_pk_bf16_f32 %0, %1, %2" : "=v"(r) : "v"(lo), "v"(hi)); return r; }
; __device__ __forceinline__ void x_half(KA a, int grp, int half, int lane, f32x4& acc, float& ss) {
;     ...
;     for (int k0 = 0; k0 < 1024; k0 += 32) {
;         const f32x4 a0 = *(const f32x4*)(xr + k0), a1 = *(const f32x4*)(xr + k0 + 4);
;         ss += (a0[0] * a0[0] + a0[1] * a0[1]) + (a0[2] * a0[2] + a0[3] * a0[3]) + (a1[0] * a1[0] + a1[1] * a1[1]) + (a1[2] * a1[2] + a1[3] * a1[3]);
;         u32x4 aw; aw.x = cvt_pk_bf16(a0[0], a0[1]); aw.y = cvt_pk_bf16(a0[2], a0[3]); aw.z = cvt_pk_bf16(a1[0], a1[1]); aw.w = cvt_pk_bf16(a1[2], a1[3]);
;         *(u32x4*)(br + k0) = aw;
;         const f32x4 g0 = *(const f32x4*)(gp + k0), g1 = *(const f32x4*)(gp + k0 + 4);
;         const float* w = wp + (size_t)k0 * 6160;
;         u32x4 bw; bw.x = cvt_pk_bf16(w[0] * g0[0], w[6160] * g0[1]); bw.y = cvt_pk_bf16(w[2 * 6160] * g0[2], w[3 * 6160] * g0[3]);
;         bw.z = cvt_pk_bf16(w[4 * 6160] * g1[0], w[5 * 6160] * g1[1]); bw.w = cvt_pk_bf16(w[6 * 6160] * g1[2], w[7 * 6160] * g1[3]);
;         acc = __builtin_amdgcn_mfma_f32_16x16x32_bf16(__builtin_bit_cast(bf16x8, aw), __builtin_bit_cast(bf16x8, bw), acc, 0, 0, 0);
;     }
	v_cvt_pk_bf16_f32 v18, v192, v193
	v_cvt_pk_bf16_f32 v19, v194, v195
	v_cvt_pk_bf16_f32 v20, v196, v197
	v_cvt_pk_bf16_f32 v21, v198, v199
	global_store_dwordx4 v[70:71], v[18:21], off offset:64
	v_mul_f32_e32 v208, v208, v200
	v_mul_f32_e32 v209, v209, v201
	v_mul_f32_e32 v210, v210, v202
	v_mul_f32_e32 v211, v211, v203
	v_mul_f32_e32 v212, v212, v204
	v_mul_f32_e32 v213, v213, v205
	v_mul_f32_e32 v214, v214, v206
	v_mul_f32_e32 v215, v215, v207
	v_cvt_pk_bf16_f32 v22, v208, v209
	v_cvt_pk_bf16_f32 v23, v210, v211
	v_cvt_pk_bf16_f32 v24, v212, v213
	v_cvt_pk_bf16_f32 v25, v214, v215
	v_mul_f32_e32 v192, v192, v192
	v_mul_f32_e32 v193, v193, v193
	v_mul_f32_e32 v194, v194, v194
	v_mul_f32_e32 v195, v195, v195
	v_mul_f32_e32 v196, v196, v196
	v_mul_f32_e32 v197, v197, v197
	v_mul_f32_e32 v198, v198, v198
	v_mul_f32_e32 v199, v199, v199
	v_add_f32_e32 v192, v192, v193
	v_add_f32_e32 v194, v194, v195
	v_add_f32_e32 v192, v192, v194
	v_add_f32_e32 v196, v196, v197
	v_add_f32_e32 v192, v192, v196
	v_add_f32_e32 v198, v198, v199
	v_add_f32_e32 v192, v192, v198
	v_add_f32_e32 v2, v2, v192
	v_mfma_f32_16x16x32_bf16 v[6:9], v[18:21], v[22:25], v[6:9]
	global_load_dwordx4 v[192:195], v[4:5], off offset:896
	global_load_dwordx4 v[196:199], v[4:5], off offset:912
	global_load_dwordx4 v[200:203], v64, s[26:27] offset:896
	global_load_dwordx4 v[204:207], v64, s[26:27] offset:912
	global_load_dword v208, v26, s[28:29]
	global_load_dword v209, v27, s[28:29]
	global_load_dword v210, v28, s[28:29]
	global_load_dword v211, v29, s[28:29]
	global_load_dword v212, v30, s[28:29]
	global_load_dword v213, v31, s[28:29]
	global_load_dword v214, v32, s[28:29]
	global_load_dword v215, v33, s[28:29]
	s_add_u32 s28, s28, 0xc0800
	s_addc_u32 s29, s29, 0
	v_lshl_add_u64 v[4:5], v[4:5], 0, s[14:15]
	s_add_u32 s26, s26, 0x200
	s_addc_u32 s27, s27, 0
	v_lshl_add_u64 v[70:71], v[70:71], 0, s[22:23]
	s_waitcnt vmcnt(36)
	v_cvt_pk_bf16_f32 v10, v100, v101
	v_cvt_pk_bf16_f32 v11, v102, v103
	v_cvt_pk_bf16_f32 v12, v104, v105
	v_cvt_pk_bf16_f32 v13, v106, v107
	global_store_dwordx4 v[70:71], v[10:13], off offset:-128
	v_mul_f32_e32 v116, v116, v108
	v_mul_f32_e32 v117, v117, v109
	v_mul_f32_e32 v118, v118, v110
	v_mul_f32_e32 v119, v119, v111
	v_mul_f32_e32 v120, v120, v112
	v_mul_f32_e32 v121, v121, v113
	v_mul_f32_e32 v122, v122, v114
	v_mul_f32_e32 v123, v123, v115
	v_cvt_pk_bf16_f32 v14, v116, v117
	v_cvt_pk_bf16_f32 v15, v118, v119
	v_cvt_pk_bf16_f32 v16, v120, v121
	v_cvt_pk_bf16_f32 v17, v122, v123
	v_mul_f32_e32 v100, v100, v100
	v_mul_f32_e32 v101, v101, v101
	v_mul_f32_e32 v102, v102, v102
	v_mul_f32_e32 v103, v103, v103
	v_mul_f32_e32 v104, v104, v104
	v_mul_f32_e32 v105, v105, v105
	v_mul_f32_e32 v106, v106, v106
	v_mul_f32_e32 v107, v107, v107
	v_add_f32_e32 v100, v100, v101
	v_add_f32_e32 v102, v102, v103
	v_add_f32_e32 v100, v100, v102
	v_add_f32_e32 v104, v104, v105
	v_add_f32_e32 v100, v100, v104
	v_add_f32_e32 v106, v106, v107
	v_add_f32_e32 v100, v100, v106
	v_add_f32_e32 v2, v2, v100
	v_mfma_f32_16x16x32_bf16 v[6:9], v[10:13], v[14:17], v[6:9]
	global_load_dwordx4 v[100:103], v[4:5], off offset:512
	global_load_dwordx4 v[104:107], v[4:5], off offset:528
	global_load_dwordx4 v[108:111], v64, s[26:27] offset:512
	global_load_dwordx4 v[112:115], v64, s[26:27] offset:528
	global_load_dword v116, v26, s[28:29]
	global_load_dword v117, v27, s[28:29]
	global_load_dword v118, v28, s[28:29]
	global_load_dword v119, v29, s[28:29]
	global_load_dword v120, v30, s[28:29]
	global_load_dword v121, v31, s[28:29]
	global_load_dword v122, v32, s[28:29]
	global_load_dword v123, v33, s[28:29]
	s_add_u32 s28, s28, 0xc0800
	s_addc_u32 s29, s29, 0
	s_waitcnt vmcnt(36)
	v_cvt_pk_bf16_f32 v18, v124, v125
	v_cvt_pk_bf16_f32 v19, v126, v127
	v_cvt_pk_bf16_f32 v20, v128, v129
	v_cvt_pk_bf16_f32 v21, v130, v131
	global_store_dwordx4 v[70:71], v[18:21], off offset:-64
	v_mul_f32_e32 v140, v140, v132
	v_mul_f32_e32 v141, v141, v133
	v_mul_f32_e32 v142, v142, v134
	v_mul_f32_e32 v143, v143, v135
	v_mul_f32_e32 v144, v144, v136
	v_mul_f32_e32 v145, v145, v137
	v_mul_f32_e32 v146, v146, v138
	v_mul_f32_e32 v147, v147, v139
	v_cvt_pk_bf16_f32 v22, v140, v141
	v_cvt_pk_bf16_f32 v23, v142, v143
	v_cvt_pk_bf16_f32 v24, v144, v145
	v_cvt_pk_bf16_f32 v25, v146, v147
	v_mul_f32_e32 v124, v124, v124
	v_mul_f32_e32 v125, v125, v125
	v_mul_f32_e32 v126, v126, v126
	v_mul_f32_e32 v127, v127, v127
	v_mul_f32_e32 v128, v128, v128
	v_mul_f32_e32 v129, v129, v129
	v_mul_f32_e32 v130, v130, v130
	v_mul_f32_e32 v131, v131, v131
	v_add_f32_e32 v124, v124, v125
	v_add_f32_e32 v126, v126, v127
	v_add_f32_e32 v124, v124, v126
	v_add_f32_e32 v128, v128, v129
	v_add_f32_e32 v124, v124, v128
	v_add_f32_e32 v130, v130, v131
	v_add_f32_e32 v124, v124, v130
	v_add_f32_e32 v2, v2, v124
	v_mfma_f32_16x16x32_bf16 v[6:9], v[18:21], v[22:25], v[6:9]
	global_load_dwordx4 v[124:127], v[4:5], off offset:640
	global_load_dwordx4 v[128:131], v[4:5], off offset:656
	global_load_dwordx4 v[132:135], v64, s[26:27] offset:640
	global_load_dwordx4 v[136:139], v64, s[26:27] offset:656
	global_load_dword v140, v26, s[28:29]
	global_load_dword v141, v27, s[28:29]
	global_load_dword v142, v28, s[28:29]
	global_load_dword v143, v29, s[28:29]
	global_load_dword v144, v30, s[28:29]
	global_load_dword v145, v31, s[28:29]
	global_load_dword v146, v32, s[28:29]
	global_load_dword v147, v33, s[28:29]
	s_add_u32 s28, s28, 0xc0800
	s_addc_u32 s29, s29, 0
	s_waitcnt vmcnt(36)
; __device__ __forceinline__ unsigned cvt_pk_bf16(float lo, float hi) { unsigned r; asm volatile("v_cvt_pk_bf16_f32 %0, %1, %2" : "=v"(r) : "v"(lo), "v"(hi)); return r; }
; __device__ __forceinline__ void x_half(KA a, int grp, int half, int lane, f32x4& acc, float& ss) {
;     ...
;     for (int k0 = 0; k0 < 1024; k0 += 32) {
;         const f32x4 a0 = *(const f32x4*)(xr + k0), a1 = *(const f32x4*)(xr + k0 + 4);
;         ss += (a0[0] * a0[0] + a0[1] * a0[1]) + (a0[2] * a0[2] + a0[3] * a0[3]) + (a1[0] * a1[0] + a1[1] * a1[1]) + (a1[2] * a1[2] + a1[3] * a1[3]);
;         u32x4 aw; aw.x = cvt_pk_bf16(a0[0], a0[1]); aw.y = cvt_pk_bf16(a0[2], a0[3]); aw.z = cvt_pk_bf16(a1[0], a1[1]); aw.w = cvt_pk_bf16(a1[2], a1[3]);
;         *(u32x4*)(br + k0) = aw;
;         const f32x4 g0 = *(const f32x4*)(gp + k0), g1 = *(const f32x4*)(gp + k0 + 4);
;         const float* w = wp + (size_t)k0 * 6160;
;         u32x4 bw; bw.x = cvt_pk_bf16(w[0] * g0[0], w[6160] * g0[1]); bw.y = cvt_pk_bf16(w[2 * 6160] * g0[2], w[3 * 6160] * g0[3]);
;         bw.z = cvt_pk_bf16(w[4 * 6160] * g1[0], w[5 * 6160] * g1[1]); bw.w = cvt_pk_bf16(w[6 * 6160] * g1[2], w[7 * 6160] * g1[3]);
;         acc = __builtin_amdgcn_mfma_f32_16x16x32_bf16(__builtin_bit_cast(bf16x8, aw), __builtin_bit_cast(bf16x8, bw), acc, 0, 0, 0);
;     }
	v_cvt_pk_bf16_f32 v10, v168, v169
	v_cvt_pk_bf16_f32 v11, v170, v171
	v_cvt_pk_bf16_f32 v12, v172, v173
	v_cvt_pk_bf16_f32 v13, v174, v175
	global_store_dwordx4 v[70:71], v[10:13], off
	v_mul_f32_e32 v184, v184, v176
	v_mul_f32_e32 v185, v185, v177
	v_mul_f32_e32 v186, v186, v178
	v_mul_f32_e32 v187, v187, v179
	v_mul_f32_e32 v188, v188, v180
	v_mul_f32_e32 v189, v189, v181
	v_mul_f32_e32 v190, v190, v182
	v_mul_f32_e32 v191, v191, v183
	v_cvt_pk_bf16_f32 v14, v184, v185
	v_cvt_pk_bf16_f32 v15, v186, v187
	v_cvt_pk_bf16_f32 v16, v188, v189
	v_cvt_pk_bf16_f32 v17, v190, v191
	v_mul_f32_e32 v168, v168, v168
	v_mul_f32_e32 v169, v169, v169
	v_mul_f32_e32 v170, v170, v170
	v_mul_f32_e32 v171, v171, v171
	v_mul_f32_e32 v172, v172, v172
	v_mul_f32_e32 v173, v173, v173
	v_mul_f32_e32 v174, v174, v174
	v_mul_f32_e32 v175, v175, v175
	v_add_f32_e32 v168, v168, v169
	v_add_f32_e32 v170, v170, v171
	v_add_f32_e32 v168, v168, v170
	v_add_f32_e32 v172, v172, v173
	v_add_f32_e32 v168, v168, v172
	v_add_f32_e32 v174, v174, v175
	v_add_f32_e32 v168, v168, v174
	v_add_f32_e32 v2, v2, v168
	v_mfma_f32_16x16x32_bf16 v[6:9], v[10:13], v[14:17], v[6:9]
	global_load_dwordx4 v[168:171], v[4:5], off offset:768
	global_load_dwordx4 v[172:175], v[4:5], off offset:784
	global_load_dwordx4 v[176:179], v64, s[26:27] offset:768
	global_load_dwordx4 v[180:183], v64, s[26:27] offset:784
	global_load_dword v184, v26, s[28:29]
	global_load_dword v185, v27, s[28:29]
	global_load_dword v186, v28, s[28:29]
	global_load_dword v187, v29, s[28:29]
	global_load_dword v188, v30, s[28:29]
	global_load_dword v189, v31, s[28:29]
	global_load_dword v190, v32, s[28:29]
	global_load_dword v191, v33, s[28:29]
	s_add_u32 s28, s28, 0xc0800
	s_addc_u32 s29, s29, 0
	s_waitcnt vmcnt(36)
	v_cvt_pk_bf16_f32 v18, v192, v193
	v_cvt_pk_bf16_f32 v19, v194, v195
	v_cvt_pk_bf16_f32 v20, v196, v197
	v_cvt_pk_bf16_f32 v21, v198, v199
	global_store_dwordx4 v[70:71], v[18:21], off offset:64
	v_mul_f32_e32 v208, v208, v200
	v_mul_f32_e32 v209, v209, v201
	v_mul_f32_e32 v210, v210, v202
	v_mul_f32_e32 v211, v211, v203
	v_mul_f32_e32 v212, v212, v204
	v_mul_f32_e32 v213, v213, v205
	v_mul_f32_e32 v214, v214, v206
	v_mul_f32_e32 v215, v215, v207
	v_cvt_pk_bf16_f32 v22, v208, v209
	v_cvt_pk_bf16_f32 v23, v210, v211
	v_cvt_pk_bf16_f32 v24, v212, v213
	v_cvt_pk_bf16_f32 v25, v214, v215
	v_mul_f32_e32 v192, v192, v192
	v_mul_f32_e32 v193, v193, v193
	v_mul_f32_e32 v194, v194, v194
	v_mul_f32_e32 v195, v195, v195
	v_mul_f32_e32 v196, v196, v196
	v_mul_f32_e32 v197, v197, v197
	v_mul_f32_e32 v198, v198, v198
	v_mul_f32_e32 v199, v199, v199
	v_add_f32_e32 v192, v192, v193
	v_add_f32_e32 v194, v194, v195
	v_add_f32_e32 v192, v192, v194
	v_add_f32_e32 v196, v196, v197
	v_add_f32_e32 v192, v192, v196
	v_add_f32_e32 v198, v198, v199
	v_add_f32_e32 v192, v192, v198
	v_add_f32_e32 v2, v2, v192
	v_mfma_f32_16x16x32_bf16 v[6:9], v[18:21], v[22:25], v[6:9]
	global_load_dwordx4 v[192:195], v[4:5], off offset:896
	global_load_dwordx4 v[196:199], v[4:5], off offset:912
	global_load_dwordx4 v[200:203], v64, s[26:27] offset:896
	global_load_dwordx4 v[204:207], v64, s[26:27] offset:912
	global_load_dword v208, v26, s[28:29]
	global_load_dword v209, v27, s[28:29]
	global_load_dword v210, v28, s[28:29]
	global_load_dword v211, v29, s[28:29]
	global_load_dword v212, v30, s[28:29]
	global_load_dword v213, v31, s[28:29]
	global_load_dword v214, v32, s[28:29]
	global_load_dword v215, v33, s[28:29]
	s_add_u32 s28, s28, 0xc0800
	s_addc_u32 s29, s29, 0
	v_lshl_add_u64 v[4:5], v[4:5], 0, s[14:15]
	s_add_u32 s26, s26, 0x200
	s_addc_u32 s27, s27, 0
	v_lshl_add_u64 v[70:71], v[70:71], 0, s[22:23]
	s_waitcnt vmcnt(36)
	v_cvt_pk_bf16_f32 v10, v100, v101
	v_cvt_pk_bf16_f32 v11, v102, v103
	v_cvt_pk_bf16_f32 v12, v104, v105
	v_cvt_pk_bf16_f32 v13, v106, v107
	global_store_dwordx4 v[70:71], v[10:13], off offset:-128
	v_mul_f32_e32 v116, v116, v108
	v_mul_f32_e32 v117, v117, v109
	v_mul_f32_e32 v118, v118, v110
	v_mul_f32_e32 v119, v119, v111
	v_mul_f32_e32 v120, v120, v112
	v_mul_f32_e32 v121, v121, v113
	v_mul_f32_e32 v122, v122, v114
	v_mul_f32_e32 v123, v123, v115
	v_cvt_pk_bf16_f32 v14, v116, v117
	v_cvt_pk_bf16_f32 v15, v118, v119
	v_cvt_pk_bf16_f32 v16, v120, v121
	v_cvt_pk_bf16_f32 v17, v122, v123
	v_mul_f32_e32 v100, v100, v100
	v_mul_f32_e32 v101, v101, v101
	v_mul_f32_e32 v102, v102, v102
	v_mul_f32_e32 v103, v103, v103
	v_mul_f32_e32 v104, v104, v104
	v_mul_f32_e32 v105, v105, v105
	v_mul_f32_e32 v106, v106, v106
	v_mul_f32_e32 v107, v107, v107
	v_add_f32_e32 v100, v100, v101
	v_add_f32_e32 v102, v102, v103
	v_add_f32_e32 v100, v100, v102
	v_add_f32_e32 v104, v104, v105
	v_add_f32_e32 v100, v100, v104
	v_add_f32_e32 v106, v106, v107
	v_add_f32_e32 v100, v100, v106
	v_add_f32_e32 v2, v2, v100
	v_mfma_f32_16x16x32_bf16 v[6:9], v[10:13], v[14:17], v[6:9]
	global_load_dwordx4 v[100:103], v[4:5], off offset:512
	global_load_dwordx4 v[104:107], v[4:5], off offset:528
	global_load_dwordx4 v[108:111], v64, s[26:27] offset:512
	global_load_dwordx4 v[112:115], v64, s[26:27] offset:528
	global_load_dword v116, v26, s[28:29]
	global_load_dword v117, v27, s[28:29]
	global_load_dword v118, v28, s[28:29]
	global_load_dword v119, v29, s[28:29]
	global_load_dword v120, v30, s[28:29]
	global_load_dword v121, v31, s[28:29]
	global_load_dword v122, v32, s[28:29]
	global_load_dword v123, v33, s[28:29]
	s_add_u32 s28, s28, 0xc0800
	s_addc_u32 s29, s29, 0
	s_waitcnt vmcnt(36)
; __device__ __forceinline__ unsigned cvt_pk_bf16(float lo, float hi) { unsigned r; asm volatile("v_cvt_pk_bf16_f32 %0, %1, %2" : "=v"(r) : "v"(lo), "v"(hi)); return r; }
; __device__ __forceinline__ void x_half(KA a, int grp, int half, int lane, f32x4& acc, float& ss) {
;     ...
;     for (int k0 = 0; k0 < 1024; k0 += 32) {
;         const f32x4 a0 = *(const f32x4*)(xr + k0), a1 = *(const f32x4*)(xr + k0 + 4);
;         ss += (a0[0] * a0[0] + a0[1] * a0[1]) + (a0[2] * a0[2] + a0[3] * a0[3]) + (a1[0] * a1[0] + a1[1] * a1[1]) + (a1[2] * a1[2] + a1[3] * a1[3]);
;         u32x4 aw; aw.x = cvt_pk_bf16(a0[0], a0[1]); aw.y = cvt_pk_bf16(a0[2], a0[3]); aw.z = cvt_pk_bf16(a1[0], a1[1]); aw.w = cvt_pk_bf16(a1[2], a1[3]);
;         *(u32x4*)(br + k0) = aw;
;         const f32x4 g0 = *(const f32x4*)(gp + k0), g1 = *(const f32x4*)(gp + k0 + 4);
;         const float* w = wp + (size_t)k0 * 6160;
;         u32x4 bw; bw.x = cvt_pk_bf16(w[0] * g0[0], w[6160] * g0[1]); bw.y = cvt_pk_bf16(w[2 * 6160] * g0[2], w[3 * 6160] * g0[3]);
;         bw.z = cvt_pk_bf16(w[4 * 6160] * g1[0], w[5 * 6160] * g1[1]); bw.w = cvt_pk_bf16(w[6 * 6160] * g1[2], w[7 * 6160] * g1[3]);
;         acc = __builtin_amdgcn_mfma_f32_16x16x32_bf16(__builtin_bit_cast(bf16x8, aw), __builtin_bit_cast(bf16x8, bw), acc, 0, 0, 0);
;     }
	v_cvt_pk_bf16_f32 v18, v124, v125
	v_cvt_pk_bf16_f32 v19, v126, v127
	v_cvt_pk_bf16_f32 v20, v128, v129
	v_cvt_pk_bf16_f32 v21, v130, v131
	global_store_dwordx4 v[70:71], v[18:21], off offset:-64
	v_mul_f32_e32 v140, v140, v132
	v_mul_f32_e32 v141, v141, v133
	v_mul_f32_e32 v142, v142, v134
	v_mul_f32_e32 v143, v143, v135
	v_mul_f32_e32 v144, v144, v136
	v_mul_f32_e32 v145, v145, v137
	v_mul_f32_e32 v146, v146, v138
	v_mul_f32_e32 v147, v147, v139
	v_cvt_pk_bf16_f32 v22, v140, v141
	v_cvt_pk_bf16_f32 v23, v142, v143
	v_cvt_pk_bf16_f32 v24, v144, v145
	v_cvt_pk_bf16_f32 v25, v146, v147
	v_mul_f32_e32 v124, v124, v124
	v_mul_f32_e32 v125, v125, v125
	v_mul_f32_e32 v126, v126, v126
	v_mul_f32_e32 v127, v127, v127
	v_mul_f32_e32 v128, v128, v128
	v_mul_f32_e32 v129, v129, v129
	v_mul_f32_e32 v130, v130, v130
	v_mul_f32_e32 v131, v131, v131
	v_add_f32_e32 v124, v124, v125
	v_add_f32_e32 v126, v126, v127
	v_add_f32_e32 v124, v124, v126
	v_add_f32_e32 v128, v128, v129
	v_add_f32_e32 v124, v124, v128
	v_add_f32_e32 v130, v130, v131
	v_add_f32_e32 v124, v124, v130
	v_add_f32_e32 v2, v2, v124
	v_mfma_f32_16x16x32_bf16 v[6:9], v[18:21], v[22:25], v[6:9]
	global_load_dwordx4 v[124:127], v[4:5], off offset:640
	global_load_dwordx4 v[128:131], v[4:5], off offset:656
	global_load_dwordx4 v[132:135], v64, s[26:27] offset:640
	global_load_dwordx4 v[136:139], v64, s[26:27] offset:656
	global_load_dword v140, v26, s[28:29]
	global_load_dword v141, v27, s[28:29]
	global_load_dword v142, v28, s[28:29]
	global_load_dword v143, v29, s[28:29]
	global_load_dword v144, v30, s[28:29]
	global_load_dword v145, v31, s[28:29]
	global_load_dword v146, v32, s[28:29]
	global_load_dword v147, v33, s[28:29]
	s_add_u32 s28, s28, 0xc0800
	s_addc_u32 s29, s29, 0
	s_waitcnt vmcnt(36)
	v_cvt_pk_bf16_f32 v10, v168, v169
	v_cvt_pk_bf16_f32 v11, v170, v171
	v_cvt_pk_bf16_f32 v12, v172, v173
	v_cvt_pk_bf16_f32 v13, v174, v175
	global_store_dwordx4 v[70:71], v[10:13], off
	v_mul_f32_e32 v184, v184, v176
	v_mul_f32_e32 v185, v185, v177
	v_mul_f32_e32 v186, v186, v178
	v_mul_f32_e32 v187, v187, v179
	v_mul_f32_e32 v188, v188, v180
	v_mul_f32_e32 v189, v189, v181
	v_mul_f32_e32 v190, v190, v182
	v_mul_f32_e32 v191, v191, v183
	v_cvt_pk_bf16_f32 v14, v184, v185
	v_cvt_pk_bf16_f32 v15, v186, v187
	v_cvt_pk_bf16_f32 v16, v188, v189
	v_cvt_pk_bf16_f32 v17, v190, v191
	v_mul_f32_e32 v168, v168, v168
	v_mul_f32_e32 v169, v169, v169
	v_mul_f32_e32 v170, v170, v170
	v_mul_f32_e32 v171, v171, v171
	v_mul_f32_e32 v172, v172, v172
	v_mul_f32_e32 v173, v173, v173
	v_mul_f32_e32 v174, v174, v174
	v_mul_f32_e32 v175, v175, v175
	v_add_f32_e32 v168, v168, v169
	v_add_f32_e32 v170, v170, v171
	v_add_f32_e32 v168, v168, v170
	v_add_f32_e32 v172, v172, v173
	v_add_f32_e32 v168, v168, v172
	v_add_f32_e32 v174, v174, v175
	v_add_f32_e32 v168, v168, v174
	v_add_f32_e32 v2, v2, v168
	v_mfma_f32_16x16x32_bf16 v[6:9], v[10:13], v[14:17], v[6:9]
	global_load_dwordx4 v[168:171], v[4:5], off offset:768
	global_load_dwordx4 v[172:175], v[4:5], off offset:784
	global_load_dwordx4 v[176:179], v64, s[26:27] offset:768
	global_load_dwordx4 v[180:183], v64, s[26:27] offset:784
	global_load_dword v184, v26, s[28:29]
	global_load_dword v185, v27, s[28:29]
	global_load_dword v186, v28, s[28:29]
	global_load_dword v187, v29, s[28:29]
	global_load_dword v188, v30, s[28:29]
	global_load_dword v189, v31, s[28:29]
	global_load_dword v190, v32, s[28:29]
	global_load_dword v191, v33, s[28:29]
	s_add_u32 s28, s28, 0xc0800
	s_addc_u32 s29, s29, 0
	s_waitcnt vmcnt(36)
	v_cvt_pk_bf16_f32 v18, v192, v193
	v_cvt_pk_bf16_f32 v19, v194, v195
	v_cvt_pk_bf16_f32 v20, v196, v197
	v_cvt_pk_bf16_f32 v21, v198, v199
	global_store_dwordx4 v[70:71], v[18:21], off offset:64
	v_mul_f32_e32 v208, v208, v200
	v_mul_f32_e32 v209, v209, v201
	v_mul_f32_e32 v210, v210, v202
	v_mul_f32_e32 v211, v211, v203
	v_mul_f32_e32 v212, v212, v204
	v_mul_f32_e32 v213, v213, v205
	v_mul_f32_e32 v214, v214, v206
	v_mul_f32_e32 v215, v215, v207
	v_cvt_pk_bf16_f32 v22, v208, v209
	v_cvt_pk_bf16_f32 v23, v210, v211
	v_cvt_pk_bf16_f32 v24, v212, v213
	v_cvt_pk_bf16_f32 v25, v214, v215
	v_mul_f32_e32 v192, v192, v192
	v_mul_f32_e32 v193, v193, v193
	v_mul_f32_e32 v194, v194, v194
	v_mul_f32_e32 v195, v195, v195
	v_mul_f32_e32 v196, v196, v196
	v_mul_f32_e32 v197, v197, v197
	v_mul_f32_e32 v198, v198, v198
	v_mul_f32_e32 v199, v199, v199
	v_add_f32_e32 v192, v192, v193
	v_add_f32_e32 v194, v194, v195
	v_add_f32_e32 v192, v192, v194
	v_add_f32_e32 v196, v196, v197
	v_add_f32_e32 v192, v192, v196
	v_add_f32_e32 v198, v198, v199
	v_add_f32_e32 v192, v192, v198
	v_add_f32_e32 v2, v2, v192
	v_mfma_f32_16x16x32_bf16 v[6:9], v[18:21], v[22:25], v[6:9]
	global_load_dwordx4 v[192:195], v[4:5], off offset:896
	global_load_dwordx4 v[196:199], v[4:5], off offset:912
	global_load_dwordx4 v[200:203], v64, s[26:27] offset:896
	global_load_dwordx4 v[204:207], v64, s[26:27] offset:912
	global_load_dword v208, v26, s[28:29]
	global_load_dword v209, v27, s[28:29]
	global_load_dword v210, v28, s[28:29]
	global_load_dword v211, v29, s[28:29]
	global_load_dword v212, v30, s[28:29]
	global_load_dword v213, v31, s[28:29]
	global_load_dword v214, v32, s[28:29]
	global_load_dword v215, v33, s[28:29]
	s_add_u32 s28, s28, 0xc0800
	s_addc_u32 s29, s29, 0
	v_lshl_add_u64 v[4:5], v[4:5], 0, s[14:15]
	s_add_u32 s26, s26, 0x200
	s_addc_u32 s27, s27, 0
	v_lshl_add_u64 v[70:71], v[70:71], 0, s[22:23]
	s_waitcnt vmcnt(36)
; __device__ __forceinline__ unsigned cvt_pk_bf16(float lo, float hi) { unsigned r; asm volatile("v_cvt_pk_bf16_f32 %0, %1, %2" : "=v"(r) : "v"(lo), "v"(hi)); return r; }
; __device__ __forceinline__ void x_half(KA a, int grp, int half, int lane, f32x4& acc, float& ss) {
;     ...
;     for (int k0 = 0; k0 < 1024; k0 += 32) {
;         const f32x4 a0 = *(const f32x4*)(xr + k0), a1 = *(const f32x4*)(xr + k0 + 4);
;         ss += (a0[0] * a0[0] + a0[1] * a0[1]) + (a0[2] * a0[2] + a0[3] * a0[3]) + (a1[0] * a1[0] + a1[1] * a1[1]) + (a1[2] * a1[2] + a1[3] * a1[3]);
;         u32x4 aw; aw.x = cvt_pk_bf16(a0[0], a0[1]); aw.y = cvt_pk_bf16(a0[2], a0[3]); aw.z = cvt_pk_bf16(a1[0], a1[1]); aw.w = cvt_pk_bf16(a1[2], a1[3]);
;         *(u32x4*)(br + k0) = aw;
;         const f32x4 g0 = *(const f32x4*)(gp + k0), g1 = *(const f32x4*)(gp + k0 + 4);
;         const float* w = wp + (size_t)k0 * 6160;
;         u32x4 bw; bw.x = cvt_pk_bf16(w[0] * g0[0], w[6160] * g0[1]); bw.y = cvt_pk_bf16(w[2 * 6160] * g0[2], w[3 * 6160] * g0[3]);
;         bw.z = cvt_pk_bf16(w[4 * 6160] * g1[0], w[5 * 6160] * g1[1]); bw.w = cvt_pk_bf16(w[6 * 6160] * g1[2], w[7 * 6160] * g1[3]);
;         acc = __builtin_amdgcn_mfma_f32_16x16x32_bf16(__builtin_bit_cast(bf16x8, aw), __builtin_bit_cast(bf16x8, bw), acc, 0, 0, 0);
;     }
	v_cvt_pk_bf16_f32 v10, v100, v101
	v_cvt_pk_bf16_f32 v11, v102, v103
	v_cvt_pk_bf16_f32 v12, v104, v105
	v_cvt_pk_bf16_f32 v13, v106, v107
	global_store_dwordx4 v[70:71], v[10:13], off offset:-128
	v_mul_f32_e32 v116, v116, v108
	v_mul_f32_e32 v117, v117, v109
	v_mul_f32_e32 v118, v118, v110
	v_mul_f32_e32 v119, v119, v111
	v_mul_f32_e32 v120, v120, v112
	v_mul_f32_e32 v121, v121, v113
	v_mul_f32_e32 v122, v122, v114
	v_mul_f32_e32 v123, v123, v115
	v_cvt_pk_bf16_f32 v14, v116, v117
	v_cvt_pk_bf16_f32 v15, v118, v119
	v_cvt_pk_bf16_f32 v16, v120, v121
	v_cvt_pk_bf16_f32 v17, v122, v123
	v_mul_f32_e32 v100, v100, v100
	v_mul_f32_e32 v101, v101, v101
	v_mul_f32_e32 v102, v102, v102
	v_mul_f32_e32 v103, v103, v103
	v_mul_f32_e32 v104, v104, v104
	v_mul_f32_e32 v105, v105, v105
	v_mul_f32_e32 v106, v106, v106
	v_mul_f32_e32 v107, v107, v107
	v_add_f32_e32 v100, v100, v101
	v_add_f32_e32 v102, v102, v103
	v_add_f32_e32 v100, v100, v102
	v_add_f32_e32 v104, v104, v105
	v_add_f32_e32 v100, v100, v104
	v_add_f32_e32 v106, v106, v107
	v_add_f32_e32 v100, v100, v106
	v_add_f32_e32 v2, v2, v100
	v_mfma_f32_16x16x32_bf16 v[6:9], v[10:13], v[14:17], v[6:9]
	global_load_dwordx4 v[100:103], v[4:5], off offset:512
	global_load_dwordx4 v[104:107], v[4:5], off offset:528
	global_load_dwordx4 v[108:111], v64, s[26:27] offset:512
	global_load_dwordx4 v[112:115], v64, s[26:27] offset:528
	global_load_dword v116, v26, s[28:29]
	global_load_dword v117, v27, s[28:29]
	global_load_dword v118, v28, s[28:29]
	global_load_dword v119, v29, s[28:29]
	global_load_dword v120, v30, s[28:29]
	global_load_dword v121, v31, s[28:29]
	global_load_dword v122, v32, s[28:29]
	global_load_dword v123, v33, s[28:29]
	s_add_u32 s28, s28, 0xc0800
	s_addc_u32 s29, s29, 0
	s_waitcnt vmcnt(36)
	v_cvt_pk_bf16_f32 v18, v124, v125
	v_cvt_pk_bf16_f32 v19, v126, v127
	v_cvt_pk_bf16_f32 v20, v128, v129
	v_cvt_pk_bf16_f32 v21, v130, v131
	global_store_dwordx4 v[70:71], v[18:21], off offset:-64
	v_mul_f32_e32 v140, v140, v132
	v_mul_f32_e32 v141, v141, v133
	v_mul_f32_e32 v142, v142, v134
	v_mul_f32_e32 v143, v143, v135
	v_mul_f32_e32 v144, v144, v136
	v_mul_f32_e32 v145, v145, v137
	v_mul_f32_e32 v146, v146, v138
	v_mul_f32_e32 v147, v147, v139
	v_cvt_pk_bf16_f32 v22, v140, v141
	v_cvt_pk_bf16_f32 v23, v142, v143
	v_cvt_pk_bf16_f32 v24, v144, v145
	v_cvt_pk_bf16_f32 v25, v146, v147
	v_mul_f32_e32 v124, v124, v124
	v_mul_f32_e32 v125, v125, v125
	v_mul_f32_e32 v126, v126, v126
	v_mul_f32_e32 v127, v127, v127
	v_mul_f32_e32 v128, v128, v128
	v_mul_f32_e32 v129, v129, v129
	v_mul_f32_e32 v130, v130, v130
	v_mul_f32_e32 v131, v131, v131
	v_add_f32_e32 v124, v124, v125
	v_add_f32_e32 v126, v126, v127
	v_add_f32_e32 v124, v124, v126
	v_add_f32_e32 v128, v128, v129
	v_add_f32_e32 v124, v124, v128
	v_add_f32_e32 v130, v130, v131
	v_add_f32_e32 v124, v124, v130
	v_add_f32_e32 v2, v2, v124
	v_mfma_f32_16x16x32_bf16 v[6:9], v[18:21], v[22:25], v[6:9]
	global_load_dwordx4 v[124:127], v[4:5], off offset:640
	global_load_dwordx4 v[128:131], v[4:5], off offset:656
	global_load_dwordx4 v[132:135], v64, s[26:27] offset:640
	global_load_dwordx4 v[136:139], v64, s[26:27] offset:656
	global_load_dword v140, v26, s[28:29]
	global_load_dword v141, v27, s[28:29]
	global_load_dword v142, v28, s[28:29]
	global_load_dword v143, v29, s[28:29]
	global_load_dword v144, v30, s[28:29]
	global_load_dword v145, v31, s[28:29]
	global_load_dword v146, v32, s[28:29]
	global_load_dword v147, v33, s[28:29]
	s_add_u32 s28, s28, 0xc0800
	s_addc_u32 s29, s29, 0
	s_waitcnt vmcnt(36)
	v_cvt_pk_bf16_f32 v10, v168, v169
	v_cvt_pk_bf16_f32 v11, v170, v171
	v_cvt_pk_bf16_f32 v12, v172, v173
	v_cvt_pk_bf16_f32 v13, v174, v175
	global_store_dwordx4 v[70:71], v[10:13], off
	v_mul_f32_e32 v184, v184, v176
	v_mul_f32_e32 v185, v185, v177
	v_mul_f32_e32 v186, v186, v178
	v_mul_f32_e32 v187, v187, v179
	v_mul_f32_e32 v188, v188, v180
	v_mul_f32_e32 v189, v189, v181
	v_mul_f32_e32 v190, v190, v182
	v_mul_f32_e32 v191, v191, v183
	v_cvt_pk_bf16_f32 v14, v184, v185
	v_cvt_pk_bf16_f32 v15, v186, v187
	v_cvt_pk_bf16_f32 v16, v188, v189
	v_cvt_pk_bf16_f32 v17, v190, v191
	v_mul_f32_e32 v168, v168, v168
	v_mul_f32_e32 v169, v169, v169
	v_mul_f32_e32 v170, v170, v170
	v_mul_f32_e32 v171, v171, v171
	v_mul_f32_e32 v172, v172, v172
	v_mul_f32_e32 v173, v173, v173
	v_mul_f32_e32 v174, v174, v174
	v_mul_f32_e32 v175, v175, v175
	v_add_f32_e32 v168, v168, v169
	v_add_f32_e32 v170, v170, v171
	v_add_f32_e32 v168, v168, v170
	v_add_f32_e32 v172, v172, v173
	v_add_f32_e32 v168, v168, v172
	v_add_f32_e32 v174, v174, v175
	v_add_f32_e32 v168, v168, v174
	v_add_f32_e32 v2, v2, v168
	v_mfma_f32_16x16x32_bf16 v[6:9], v[10:13], v[14:17], v[6:9]
	global_load_dwordx4 v[168:171], v[4:5], off offset:768
	global_load_dwordx4 v[172:175], v[4:5], off offset:784
	global_load_dwordx4 v[176:179], v64, s[26:27] offset:768
	global_load_dwordx4 v[180:183], v64, s[26:27] offset:784
	global_load_dword v184, v26, s[28:29]
	global_load_dword v185, v27, s[28:29]
	global_load_dword v186, v28, s[28:29]
	global_load_dword v187, v29, s[28:29]
	global_load_dword v188, v30, s[28:29]
	global_load_dword v189, v31, s[28:29]
	global_load_dword v190, v32, s[28:29]
	global_load_dword v191, v33, s[28:29]
	s_add_u32 s28, s28, 0xc0800
	s_addc_u32 s29, s29, 0
	s_waitcnt vmcnt(36)
; __device__ __forceinline__ unsigned cvt_pk_bf16(float lo, float hi) { unsigned r; asm volatile("v_cvt_pk_bf16_f32 %0, %1, %2" : "=v"(r) : "v"(lo), "v"(hi)); return r; }
; __device__ __forceinline__ void x_half(KA a, int grp, int half, int lane, f32x4& acc, float& ss) {
;     ...
;     for (int k0 = 0; k0 < 1024; k0 += 32) {
;         const f32x4 a0 = *(const f32x4*)(xr + k0), a1 = *(const f32x4*)(xr + k0 + 4);
;         ss += (a0[0] * a0[0] + a0[1] * a0[1]) + (a0[2] * a0[2] + a0[3] * a0[3]) + (a1[0] * a1[0] + a1[1] * a1[1]) + (a1[2] * a1[2] + a1[3] * a1[3]);
;         u32x4 aw; aw.x = cvt_pk_bf16(a0[0], a0[1]); aw.y = cvt_pk_bf16(a0[2], a0[3]); aw.z = cvt_pk_bf16(a1[0], a1[1]); aw.w = cvt_pk_bf16(a1[2], a1[3]);
;         *(u32x4*)(br + k0) = aw;
;         const f32x4 g0 = *(const f32x4*)(gp + k0), g1 = *(const f32x4*)(gp + k0 + 4);
;         const float* w = wp + (size_t)k0 * 6160;
;         u32x4 bw; bw.x = cvt_pk_bf16(w[0] * g0[0], w[6160] * g0[1]); bw.y = cvt_pk_bf16(w[2 * 6160] * g0[2], w[3 * 6160] * g0[3]);
;         bw.z = cvt_pk_bf16(w[4 * 6160] * g1[0], w[5 * 6160] * g1[1]); bw.w = cvt_pk_bf16(w[6 * 6160] * g1[2], w[7 * 6160] * g1[3]);
;         acc = __builtin_amdgcn_mfma_f32_16x16x32_bf16(__builtin_bit_cast(bf16x8, aw), __builtin_bit_cast(bf16x8, bw), acc, 0, 0, 0);
;     }
	v_cvt_pk_bf16_f32 v18, v192, v193
	v_cvt_pk_bf16_f32 v19, v194, v195
	v_cvt_pk_bf16_f32 v20, v196, v197
	v_cvt_pk_bf16_f32 v21, v198, v199
	global_store_dwordx4 v[70:71], v[18:21], off offset:64
	v_mul_f32_e32 v208, v208, v200
	v_mul_f32_e32 v209, v209, v201
	v_mul_f32_e32 v210, v210, v202
	v_mul_f32_e32 v211, v211, v203
	v_mul_f32_e32 v212, v212, v204
	v_mul_f32_e32 v213, v213, v205
	v_mul_f32_e32 v214, v214, v206
	v_mul_f32_e32 v215, v215, v207
	v_cvt_pk_bf16_f32 v22, v208, v209
	v_cvt_pk_bf16_f32 v23, v210, v211
	v_cvt_pk_bf16_f32 v24, v212, v213
	v_cvt_pk_bf16_f32 v25, v214, v215
	v_mul_f32_e32 v192, v192, v192
	v_mul_f32_e32 v193, v193, v193
	v_mul_f32_e32 v194, v194, v194
	v_mul_f32_e32 v195, v195, v195
	v_mul_f32_e32 v196, v196, v196
	v_mul_f32_e32 v197, v197, v197
	v_mul_f32_e32 v198, v198, v198
	v_mul_f32_e32 v199, v199, v199
	v_add_f32_e32 v192, v192, v193
	v_add_f32_e32 v194, v194, v195
	v_add_f32_e32 v192, v192, v194
	v_add_f32_e32 v196, v196, v197
	v_add_f32_e32 v192, v192, v196
	v_add_f32_e32 v198, v198, v199
	v_add_f32_e32 v192, v192, v198
	v_add_f32_e32 v2, v2, v192
	v_mfma_f32_16x16x32_bf16 v[6:9], v[18:21], v[22:25], v[6:9]
	global_load_dwordx4 v[192:195], v[4:5], off offset:896
	global_load_dwordx4 v[196:199], v[4:5], off offset:912
	global_load_dwordx4 v[200:203], v64, s[26:27] offset:896
	global_load_dwordx4 v[204:207], v64, s[26:27] offset:912
	global_load_dword v208, v26, s[28:29]
	global_load_dword v209, v27, s[28:29]
	global_load_dword v210, v28, s[28:29]
	global_load_dword v211, v29, s[28:29]
	global_load_dword v212, v30, s[28:29]
	global_load_dword v213, v31, s[28:29]
	global_load_dword v214, v32, s[28:29]
	global_load_dword v215, v33, s[28:29]
	s_add_u32 s28, s28, 0xc0800
	s_addc_u32 s29, s29, 0
	v_lshl_add_u64 v[4:5], v[4:5], 0, s[14:15]
	s_add_u32 s26, s26, 0x200
	s_addc_u32 s27, s27, 0
	v_lshl_add_u64 v[70:71], v[70:71], 0, s[22:23]
	s_waitcnt vmcnt(36)
	v_cvt_pk_bf16_f32 v10, v100, v101
	v_cvt_pk_bf16_f32 v11, v102, v103
	v_cvt_pk_bf16_f32 v12, v104, v105
	v_cvt_pk_bf16_f32 v13, v106, v107
	global_store_dwordx4 v[70:71], v[10:13], off offset:-128
	v_mul_f32_e32 v116, v116, v108
	v_mul_f32_e32 v117, v117, v109
	v_mul_f32_e32 v118, v118, v110
	v_mul_f32_e32 v119, v119, v111
	v_mul_f32_e32 v120, v120, v112
	v_mul_f32_e32 v121, v121, v113
	v_mul_f32_e32 v122, v122, v114
	v_mul_f32_e32 v123, v123, v115
	v_cvt_pk_bf16_f32 v14, v116, v117
	v_cvt_pk_bf16_f32 v15, v118, v119
	v_cvt_pk_bf16_f32 v16, v120, v121
	v_cvt_pk_bf16_f32 v17, v122, v123
	v_mul_f32_e32 v100, v100, v100
	v_mul_f32_e32 v101, v101, v101
	v_mul_f32_e32 v102, v102, v102
	v_mul_f32_e32 v103, v103, v103
	v_mul_f32_e32 v104, v104, v104
	v_mul_f32_e32 v105, v105, v105
	v_mul_f32_e32 v106, v106, v106
	v_mul_f32_e32 v107, v107, v107
	v_add_f32_e32 v100, v100, v101
	v_add_f32_e32 v102, v102, v103
	v_add_f32_e32 v100, v100, v102
	v_add_f32_e32 v104, v104, v105
	v_add_f32_e32 v100, v100, v104
	v_add_f32_e32 v106, v106, v107
	v_add_f32_e32 v100, v100, v106
	v_add_f32_e32 v2, v2, v100
	v_mfma_f32_16x16x32_bf16 v[6:9], v[10:13], v[14:17], v[6:9]
	global_load_dwordx4 v[100:103], v[4:5], off offset:512
	global_load_dwordx4 v[104:107], v[4:5], off offset:528
	global_load_dwordx4 v[108:111], v64, s[26:27] offset:512
	global_load_dwordx4 v[112:115], v64, s[26:27] offset:528
	global_load_dword v116, v26, s[28:29]
	global_load_dword v117, v27, s[28:29]
	global_load_dword v118, v28, s[28:29]
	global_load_dword v119, v29, s[28:29]
	global_load_dword v120, v30, s[28:29]
	global_load_dword v121, v31, s[28:29]
	global_load_dword v122, v32, s[28:29]
	global_load_dword v123, v33, s[28:29]
	s_add_u32 s28, s28, 0xc0800
	s_addc_u32 s29, s29, 0
	s_waitcnt vmcnt(36)
	v_cvt_pk_bf16_f32 v18, v124, v125
	v_cvt_pk_bf16_f32 v19, v126, v127
	v_cvt_pk_bf16_f32 v20, v128, v129
	v_cvt_pk_bf16_f32 v21, v130, v131
	global_store_dwordx4 v[70:71], v[18:21], off offset:-64
	v_mul_f32_e32 v140, v140, v132
	v_mul_f32_e32 v141, v141, v133
	v_mul_f32_e32 v142, v142, v134
	v_mul_f32_e32 v143, v143, v135
	v_mul_f32_e32 v144, v144, v136
	v_mul_f32_e32 v145, v145, v137
	v_mul_f32_e32 v146, v146, v138
	v_mul_f32_e32 v147, v147, v139
	v_cvt_pk_bf16_f32 v22, v140, v141
	v_cvt_pk_bf16_f32 v23, v142, v143
	v_cvt_pk_bf16_f32 v24, v144, v145
	v_cvt_pk_bf16_f32 v25, v146, v147
	v_mul_f32_e32 v124, v124, v124
	v_mul_f32_e32 v125, v125, v125
	v_mul_f32_e32 v126, v126, v126
	v_mul_f32_e32 v127, v127, v127
	v_mul_f32_e32 v128, v128, v128
	v_mul_f32_e32 v129, v129, v129
	v_mul_f32_e32 v130, v130, v130
	v_mul_f32_e32 v131, v131, v131
	v_add_f32_e32 v124, v124, v125
	v_add_f32_e32 v126, v126, v127
	v_add_f32_e32 v124, v124, v126
	v_add_f32_e32 v128, v128, v129
	v_add_f32_e32 v124, v124, v128
	v_add_f32_e32 v130, v130, v131
	v_add_f32_e32 v124, v124, v130
	v_add_f32_e32 v2, v2, v124
	v_mfma_f32_16x16x32_bf16 v[6:9], v[18:21], v[22:25], v[6:9]
	global_load_dwordx4 v[124:127], v[4:5], off offset:640
	global_load_dwordx4 v[128:131], v[4:5], off offset:656
	global_load_dwordx4 v[132:135], v64, s[26:27] offset:640
	global_load_dwordx4 v[136:139], v64, s[26:27] offset:656
	global_load_dword v140, v26, s[28:29]
	global_load_dword v141, v27, s[28:29]
	global_load_dword v142, v28, s[28:29]
	global_load_dword v143, v29, s[28:29]
	global_load_dword v144, v30, s[28:29]
	global_load_dword v145, v31, s[28:29]
	global_load_dword v146, v32, s[28:29]
	global_load_dword v147, v33, s[28:29]
	s_add_u32 s28, s28, 0xc0800
	s_addc_u32 s29, s29, 0
	s_waitcnt vmcnt(36)
; __device__ __forceinline__ unsigned cvt_pk_bf16(float lo, float hi) { unsigned r; asm volatile("v_cvt_pk_bf16_f32 %0, %1, %2" : "=v"(r) : "v"(lo), "v"(hi)); return r; }
; __device__ __forceinline__ void x_half(KA a, int grp, int half, int lane, f32x4& acc, float& ss) {
;     ...
;     for (int k0 = 0; k0 < 1024; k0 += 32) {
;         const f32x4 a0 = *(const f32x4*)(xr + k0), a1 = *(const f32x4*)(xr + k0 + 4);
;         ss += (a0[0] * a0[0] + a0[1] * a0[1]) + (a0[2] * a0[2] + a0[3] * a0[3]) + (a1[0] * a1[0] + a1[1] * a1[1]) + (a1[2] * a1[2] + a1[3] * a1[3]);
;         u32x4 aw; aw.x = cvt_pk_bf16(a0[0], a0[1]); aw.y = cvt_pk_bf16(a0[2], a0[3]); aw.z = cvt_pk_bf16(a1[0], a1[1]); aw.w = cvt_pk_bf16(a1[2], a1[3]);
;         *(u32x4*)(br + k0) = aw;
;         const f32x4 g0 = *(const f32x4*)(gp + k0), g1 = *(const f32x4*)(gp + k0 + 4);
;         const float* w = wp + (size_t)k0 * 6160;
;         u32x4 bw; bw.x = cvt_pk_bf16(w[0] * g0[0], w[6160] * g0[1]); bw.y = cvt_pk_bf16(w[2 * 6160] * g0[2], w[3 * 6160] * g0[3]);
;         bw.z = cvt_pk_bf16(w[4 * 6160] * g1[0], w[5 * 6160] * g1[1]); bw.w = cvt_pk_bf16(w[6 * 6160] * g1[2], w[7 * 6160] * g1[3]);
;         acc = __builtin_amdgcn_mfma_f32_16x16x32_bf16(__builtin_bit_cast(bf16x8, aw), __builtin_bit_cast(bf16x8, bw), acc, 0, 0, 0);
;     }
	v_cvt_pk_bf16_f32 v10, v168, v169
	v_cvt_pk_bf16_f32 v11, v170, v171
	v_cvt_pk_bf16_f32 v12, v172, v173
	v_cvt_pk_bf16_f32 v13, v174, v175
	global_store_dwordx4 v[70:71], v[10:13], off
	v_mul_f32_e32 v184, v184, v176
	v_mul_f32_e32 v185, v185, v177
	v_mul_f32_e32 v186, v186, v178
	v_mul_f32_e32 v187, v187, v179
	v_mul_f32_e32 v188, v188, v180
	v_mul_f32_e32 v189, v189, v181
	v_mul_f32_e32 v190, v190, v182
	v_mul_f32_e32 v191, v191, v183
	v_cvt_pk_bf16_f32 v14, v184, v185
	v_cvt_pk_bf16_f32 v15, v186, v187
	v_cvt_pk_bf16_f32 v16, v188, v189
	v_cvt_pk_bf16_f32 v17, v190, v191
	v_mul_f32_e32 v168, v168, v168
	v_mul_f32_e32 v169, v169, v169
	v_mul_f32_e32 v170, v170, v170
	v_mul_f32_e32 v171, v171, v171
	v_mul_f32_e32 v172, v172, v172
	v_mul_f32_e32 v173, v173, v173
	v_mul_f32_e32 v174, v174, v174
	v_mul_f32_e32 v175, v175, v175
	v_add_f32_e32 v168, v168, v169
	v_add_f32_e32 v170, v170, v171
	v_add_f32_e32 v168, v168, v170
	v_add_f32_e32 v172, v172, v173
	v_add_f32_e32 v168, v168, v172
	v_add_f32_e32 v174, v174, v175
	v_add_f32_e32 v168, v168, v174
	v_add_f32_e32 v2, v2, v168
	v_mfma_f32_16x16x32_bf16 v[6:9], v[10:13], v[14:17], v[6:9]
	global_load_dwordx4 v[168:171], v[4:5], off offset:768
	global_load_dwordx4 v[172:175], v[4:5], off offset:784
	global_load_dwordx4 v[176:179], v64, s[26:27] offset:768
	global_load_dwordx4 v[180:183], v64, s[26:27] offset:784
	global_load_dword v184, v26, s[28:29]
	global_load_dword v185, v27, s[28:29]
	global_load_dword v186, v28, s[28:29]
	global_load_dword v187, v29, s[28:29]
	global_load_dword v188, v30, s[28:29]
	global_load_dword v189, v31, s[28:29]
	global_load_dword v190, v32, s[28:29]
	global_load_dword v191, v33, s[28:29]
	s_add_u32 s28, s28, 0xc0800
	s_addc_u32 s29, s29, 0
	s_waitcnt vmcnt(36)
	v_cvt_pk_bf16_f32 v18, v192, v193
	v_cvt_pk_bf16_f32 v19, v194, v195
	v_cvt_pk_bf16_f32 v20, v196, v197
	v_cvt_pk_bf16_f32 v21, v198, v199
	global_store_dwordx4 v[70:71], v[18:21], off offset:64
	v_mul_f32_e32 v208, v208, v200
	v_mul_f32_e32 v209, v209, v201
	v_mul_f32_e32 v210, v210, v202
	v_mul_f32_e32 v211, v211, v203
	v_mul_f32_e32 v212, v212, v204
	v_mul_f32_e32 v213, v213, v205
	v_mul_f32_e32 v214, v214, v206
	v_mul_f32_e32 v215, v215, v207
	v_cvt_pk_bf16_f32 v22, v208, v209
	v_cvt_pk_bf16_f32 v23, v210, v211
	v_cvt_pk_bf16_f32 v24, v212, v213
	v_cvt_pk_bf16_f32 v25, v214, v215
	v_mul_f32_e32 v192, v192, v192
	v_mul_f32_e32 v193, v193, v193
	v_mul_f32_e32 v194, v194, v194
	v_mul_f32_e32 v195, v195, v195
	v_mul_f32_e32 v196, v196, v196
	v_mul_f32_e32 v197, v197, v197
	v_mul_f32_e32 v198, v198, v198
	v_mul_f32_e32 v199, v199, v199
	v_add_f32_e32 v192, v192, v193
	v_add_f32_e32 v194, v194, v195
	v_add_f32_e32 v192, v192, v194
	v_add_f32_e32 v196, v196, v197
	v_add_f32_e32 v192, v192, v196
	v_add_f32_e32 v198, v198, v199
	v_add_f32_e32 v192, v192, v198
	v_add_f32_e32 v2, v2, v192
	v_mfma_f32_16x16x32_bf16 v[6:9], v[18:21], v[22:25], v[6:9]
	global_load_dwordx4 v[192:195], v[4:5], off offset:896
	global_load_dwordx4 v[196:199], v[4:5], off offset:912
	global_load_dwordx4 v[200:203], v64, s[26:27] offset:896
	global_load_dwordx4 v[204:207], v64, s[26:27] offset:912
	global_load_dword v208, v26, s[28:29]
	global_load_dword v209, v27, s[28:29]
	global_load_dword v210, v28, s[28:29]
	global_load_dword v211, v29, s[28:29]
	global_load_dword v212, v30, s[28:29]
	global_load_dword v213, v31, s[28:29]
	global_load_dword v214, v32, s[28:29]
	global_load_dword v215, v33, s[28:29]
	s_add_u32 s28, s28, 0xc0800
	s_addc_u32 s29, s29, 0
	v_lshl_add_u64 v[4:5], v[4:5], 0, s[14:15]
	s_add_u32 s26, s26, 0x200
	s_addc_u32 s27, s27, 0
	v_lshl_add_u64 v[70:71], v[70:71], 0, s[22:23]
	s_waitcnt vmcnt(36)
	v_cvt_pk_bf16_f32 v10, v100, v101
	v_cvt_pk_bf16_f32 v11, v102, v103
	v_cvt_pk_bf16_f32 v12, v104, v105
	v_cvt_pk_bf16_f32 v13, v106, v107
	global_store_dwordx4 v[70:71], v[10:13], off offset:-128
	v_mul_f32_e32 v116, v116, v108
	v_mul_f32_e32 v117, v117, v109
	v_mul_f32_e32 v118, v118, v110
	v_mul_f32_e32 v119, v119, v111
	v_mul_f32_e32 v120, v120, v112
	v_mul_f32_e32 v121, v121, v113
	v_mul_f32_e32 v122, v122, v114
	v_mul_f32_e32 v123, v123, v115
	v_cvt_pk_bf16_f32 v14, v116, v117
	v_cvt_pk_bf16_f32 v15, v118, v119
	v_cvt_pk_bf16_f32 v16, v120, v121
	v_cvt_pk_bf16_f32 v17, v122, v123
	v_mul_f32_e32 v100, v100, v100
	v_mul_f32_e32 v101, v101, v101
	v_mul_f32_e32 v102, v102, v102
	v_mul_f32_e32 v103, v103, v103
	v_mul_f32_e32 v104, v104, v104
	v_mul_f32_e32 v105, v105, v105
	v_mul_f32_e32 v106, v106, v106
	v_mul_f32_e32 v107, v107, v107
	v_add_f32_e32 v100, v100, v101
	v_add_f32_e32 v102, v102, v103
	v_add_f32_e32 v100, v100, v102
	v_add_f32_e32 v104, v104, v105
	v_add_f32_e32 v100, v100, v104
	v_add_f32_e32 v106, v106, v107
	v_add_f32_e32 v100, v100, v106
	v_add_f32_e32 v2, v2, v100
	v_mfma_f32_16x16x32_bf16 v[6:9], v[10:13], v[14:17], v[6:9]
	global_load_dwordx4 v[100:103], v[4:5], off offset:512
	global_load_dwordx4 v[104:107], v[4:5], off offset:528
	global_load_dwordx4 v[108:111], v64, s[26:27] offset:512
	global_load_dwordx4 v[112:115], v64, s[26:27] offset:528
	global_load_dword v116, v26, s[28:29]
	global_load_dword v117, v27, s[28:29]
	global_load_dword v118, v28, s[28:29]
	global_load_dword v119, v29, s[28:29]
	global_load_dword v120, v30, s[28:29]
	global_load_dword v121, v31, s[28:29]
	global_load_dword v122, v32, s[28:29]
	global_load_dword v123, v33, s[28:29]
	s_add_u32 s28, s28, 0xc0800
	s_addc_u32 s29, s29, 0
	s_waitcnt vmcnt(36)
; __device__ __forceinline__ unsigned cvt_pk_bf16(float lo, float hi) { unsigned r; asm volatile("v_cvt_pk_bf16_f32 %0, %1, %2" : "=v"(r) : "v"(lo), "v"(hi)); return r; }
; __device__ __forceinline__ void x_half(KA a, int grp, int half, int lane, f32x4& acc, float& ss) {
;     ...
;     for (int k0 = 0; k0 < 1024; k0 += 32) {
;         const f32x4 a0 = *(const f32x4*)(xr + k0), a1 = *(const f32x4*)(xr + k0 + 4);
;         ss += (a0[0] * a0[0] + a0[1] * a0[1]) + (a0[2] * a0[2] + a0[3] * a0[3]) + (a1[0] * a1[0] + a1[1] * a1[1]) + (a1[2] * a1[2] + a1[3] * a1[3]);
;         u32x4 aw; aw.x = cvt_pk_bf16(a0[0], a0[1]); aw.y = cvt_pk_bf16(a0[2], a0[3]); aw.z = cvt_pk_bf16(a1[0], a1[1]); aw.w = cvt_pk_bf16(a1[2], a1[3]);
;         *(u32x4*)(br + k0) = aw;
;         const f32x4 g0 = *(const f32x4*)(gp + k0), g1 = *(const f32x4*)(gp + k0 + 4);
;         const float* w = wp + (size_t)k0 * 6160;
;         u32x4 bw; bw.x = cvt_pk_bf16(w[0] * g0[0], w[6160] * g0[1]); bw.y = cvt_pk_bf16(w[2 * 6160] * g0[2], w[3 * 6160] * g0[3]);
;         bw.z = cvt_pk_bf16(w[4 * 6160] * g1[0], w[5 * 6160] * g1[1]); bw.w = cvt_pk_bf16(w[6 * 6160] * g1[2], w[7 * 6160] * g1[3]);
;         acc = __builtin_amdgcn_mfma_f32_16x16x32_bf16(__builtin_bit_cast(bf16x8, aw), __builtin_bit_cast(bf16x8, bw), acc, 0, 0, 0);
;     }
	v_cvt_pk_bf16_f32 v18, v124, v125
	v_cvt_pk_bf16_f32 v19, v126, v127
	v_cvt_pk_bf16_f32 v20, v128, v129
	v_cvt_pk_bf16_f32 v21, v130, v131
	global_store_dwordx4 v[70:71], v[18:21], off offset:-64
	v_mul_f32_e32 v140, v140, v132
	v_mul_f32_e32 v141, v141, v133
	v_mul_f32_e32 v142, v142, v134
	v_mul_f32_e32 v143, v143, v135
	v_mul_f32_e32 v144, v144, v136
	v_mul_f32_e32 v145, v145, v137
	v_mul_f32_e32 v146, v146, v138
	v_mul_f32_e32 v147, v147, v139
	v_cvt_pk_bf16_f32 v22, v140, v141
	v_cvt_pk_bf16_f32 v23, v142, v143
	v_cvt_pk_bf16_f32 v24, v144, v145
	v_cvt_pk_bf16_f32 v25, v146, v147
	v_mul_f32_e32 v124, v124, v124
	v_mul_f32_e32 v125, v125, v125
	v_mul_f32_e32 v126, v126, v126
	v_mul_f32_e32 v127, v127, v127
	v_mul_f32_e32 v128, v128, v128
	v_mul_f32_e32 v129, v129, v129
	v_mul_f32_e32 v130, v130, v130
	v_mul_f32_e32 v131, v131, v131
	v_add_f32_e32 v124, v124, v125
	v_add_f32_e32 v126, v126, v127
	v_add_f32_e32 v124, v124, v126
	v_add_f32_e32 v128, v128, v129
	v_add_f32_e32 v124, v124, v128
	v_add_f32_e32 v130, v130, v131
	v_add_f32_e32 v124, v124, v130
	v_add_f32_e32 v2, v2, v124
	v_mfma_f32_16x16x32_bf16 v[6:9], v[18:21], v[22:25], v[6:9]
	global_load_dwordx4 v[124:127], v[4:5], off offset:640
	global_load_dwordx4 v[128:131], v[4:5], off offset:656
	global_load_dwordx4 v[132:135], v64, s[26:27] offset:640
	global_load_dwordx4 v[136:139], v64, s[26:27] offset:656
	global_load_dword v140, v26, s[28:29]
	global_load_dword v141, v27, s[28:29]
	global_load_dword v142, v28, s[28:29]
	global_load_dword v143, v29, s[28:29]
	global_load_dword v144, v30, s[28:29]
	global_load_dword v145, v31, s[28:29]
	global_load_dword v146, v32, s[28:29]
	global_load_dword v147, v33, s[28:29]
	s_add_u32 s28, s28, 0xc0800
	s_addc_u32 s29, s29, 0
	s_waitcnt vmcnt(36)
	v_cvt_pk_bf16_f32 v10, v168, v169
	v_cvt_pk_bf16_f32 v11, v170, v171
	v_cvt_pk_bf16_f32 v12, v172, v173
	v_cvt_pk_bf16_f32 v13, v174, v175
	global_store_dwordx4 v[70:71], v[10:13], off
	v_mul_f32_e32 v184, v184, v176
	v_mul_f32_e32 v185, v185, v177
	v_mul_f32_e32 v186, v186, v178
	v_mul_f32_e32 v187, v187, v179
	v_mul_f32_e32 v188, v188, v180
	v_mul_f32_e32 v189, v189, v181
	v_mul_f32_e32 v190, v190, v182
	v_mul_f32_e32 v191, v191, v183
	v_cvt_pk_bf16_f32 v14, v184, v185
	v_cvt_pk_bf16_f32 v15, v186, v187
	v_cvt_pk_bf16_f32 v16, v188, v189
	v_cvt_pk_bf16_f32 v17, v190, v191
	v_mul_f32_e32 v168, v168, v168
	v_mul_f32_e32 v169, v169, v169
	v_mul_f32_e32 v170, v170, v170
	v_mul_f32_e32 v171, v171, v171
	v_mul_f32_e32 v172, v172, v172
	v_mul_f32_e32 v173, v173, v173
	v_mul_f32_e32 v174, v174, v174
	v_mul_f32_e32 v175, v175, v175
	v_add_f32_e32 v168, v168, v169
	v_add_f32_e32 v170, v170, v171
	v_add_f32_e32 v168, v168, v170
	v_add_f32_e32 v172, v172, v173
	v_add_f32_e32 v168, v168, v172
	v_add_f32_e32 v174, v174, v175
	v_add_f32_e32 v168, v168, v174
	v_add_f32_e32 v2, v2, v168
	v_mfma_f32_16x16x32_bf16 v[6:9], v[10:13], v[14:17], v[6:9]
	global_load_dwordx4 v[168:171], v[4:5], off offset:768
	global_load_dwordx4 v[172:175], v[4:5], off offset:784
	global_load_dwordx4 v[176:179], v64, s[26:27] offset:768
	global_load_dwordx4 v[180:183], v64, s[26:27] offset:784
	global_load_dword v184, v26, s[28:29]
	global_load_dword v185, v27, s[28:29]
	global_load_dword v186, v28, s[28:29]
	global_load_dword v187, v29, s[28:29]
	global_load_dword v188, v30, s[28:29]
	global_load_dword v189, v31, s[28:29]
	global_load_dword v190, v32, s[28:29]
	global_load_dword v191, v33, s[28:29]
	s_add_u32 s28, s28, 0xc0800
	s_addc_u32 s29, s29, 0
	s_waitcnt vmcnt(36)
	v_cvt_pk_bf16_f32 v18, v192, v193
	v_cvt_pk_bf16_f32 v19, v194, v195
	v_cvt_pk_bf16_f32 v20, v196, v197
	v_cvt_pk_bf16_f32 v21, v198, v199
	global_store_dwordx4 v[70:71], v[18:21], off offset:64
	v_mul_f32_e32 v208, v208, v200
	v_mul_f32_e32 v209, v209, v201
	v_mul_f32_e32 v210, v210, v202
	v_mul_f32_e32 v211, v211, v203
	v_mul_f32_e32 v212, v212, v204
	v_mul_f32_e32 v213, v213, v205
	v_mul_f32_e32 v214, v214, v206
	v_mul_f32_e32 v215, v215, v207
	v_cvt_pk_bf16_f32 v22, v208, v209
	v_cvt_pk_bf16_f32 v23, v210, v211
	v_cvt_pk_bf16_f32 v24, v212, v213
	v_cvt_pk_bf16_f32 v25, v214, v215
	v_mul_f32_e32 v192, v192, v192
	v_mul_f32_e32 v193, v193, v193
	v_mul_f32_e32 v194, v194, v194
	v_mul_f32_e32 v195, v195, v195
	v_mul_f32_e32 v196, v196, v196
	v_mul_f32_e32 v197, v197, v197
	v_mul_f32_e32 v198, v198, v198
	v_mul_f32_e32 v199, v199, v199
	v_add_f32_e32 v192, v192, v193
	v_add_f32_e32 v194, v194, v195
	v_add_f32_e32 v192, v192, v194
	v_add_f32_e32 v196, v196, v197
	v_add_f32_e32 v192, v192, v196
	v_add_f32_e32 v198, v198, v199
	v_add_f32_e32 v192, v192, v198
	v_add_f32_e32 v2, v2, v192
	v_mfma_f32_16x16x32_bf16 v[6:9], v[18:21], v[22:25], v[6:9]
	global_load_dwordx4 v[192:195], v[4:5], off offset:896
	global_load_dwordx4 v[196:199], v[4:5], off offset:912
	global_load_dwordx4 v[200:203], v64, s[26:27] offset:896
	global_load_dwordx4 v[204:207], v64, s[26:27] offset:912
	global_load_dword v208, v26, s[28:29]
	global_load_dword v209, v27, s[28:29]
	global_load_dword v210, v28, s[28:29]
	global_load_dword v211, v29, s[28:29]
	global_load_dword v212, v30, s[28:29]
	global_load_dword v213, v31, s[28:29]
	global_load_dword v214, v32, s[28:29]
	global_load_dword v215, v33, s[28:29]
	s_add_u32 s28, s28, 0xc0800
	s_addc_u32 s29, s29, 0
	v_lshl_add_u64 v[4:5], v[4:5], 0, s[14:15]
	s_add_u32 s26, s26, 0x200
	s_addc_u32 s27, s27, 0
	v_lshl_add_u64 v[70:71], v[70:71], 0, s[22:23]
	s_waitcnt vmcnt(36)
; __device__ __forceinline__ unsigned cvt_pk_bf16(float lo, float hi) { unsigned r; asm volatile("v_cvt_pk_bf16_f32 %0, %1, %2" : "=v"(r) : "v"(lo), "v"(hi)); return r; }
; #define LAS __attribute__((address_space(3)))
; __device__ __forceinline__ void x_half(KA a, int grp, int half, int lane, f32x4& acc, float& ss) {
;     ...
;     for (int k0 = 0; k0 < 1024; k0 += 32) {
;         const f32x4 a0 = *(const f32x4*)(xr + k0), a1 = *(const f32x4*)(xr + k0 + 4);
;         ss += (a0[0] * a0[0] + a0[1] * a0[1]) + (a0[2] * a0[2] + a0[3] * a0[3]) + (a1[0] * a1[0] + a1[1] * a1[1]) + (a1[2] * a1[2] + a1[3] * a1[3]);
;         u32x4 aw; aw.x = cvt_pk_bf16(a0[0], a0[1]); aw.y = cvt_pk_bf16(a0[2], a0[3]); aw.z = cvt_pk_bf16(a1[0], a1[1]); aw.w = cvt_pk_bf16(a1[2], a1[3]);
;         *(u32x4*)(br + k0) = aw;
;         const f32x4 g0 = *(const f32x4*)(gp + k0), g1 = *(const f32x4*)(gp + k0 + 4);
;         const float* w = wp + (size_t)k0 * 6160;
;         u32x4 bw; bw.x = cvt_pk_bf16(w[0] * g0[0], w[6160] * g0[1]); bw.y = cvt_pk_bf16(w[2 * 6160] * g0[2], w[3 * 6160] * g0[3]);
;         bw.z = cvt_pk_bf16(w[4 * 6160] * g1[0], w[5 * 6160] * g1[1]); bw.w = cvt_pk_bf16(w[6 * 6160] * g1[2], w[7 * 6160] * g1[3]);
;         acc = __builtin_amdgcn_mfma_f32_16x16x32_bf16(__builtin_bit_cast(bf16x8, aw), __builtin_bit_cast(bf16x8, bw), acc, 0, 0, 0);
;     }
; __device__ __forceinline__ void prologue(KA a, LAS unsigned char* lds, int bid, int G, int lane, int wave) {
;     ...
;         LAS float* xs = (LAS float*)(lds + (wave & 3) * 16384 + 12288) + lane * 5;
;         if (wave >= 4) { xs[0] = acc[0]; xs[1] = acc[1]; xs[2] = acc[2]; xs[3] = acc[3]; xs[4] = ss; }
	v_cvt_pk_bf16_f32 v10, v100, v101
	v_cvt_pk_bf16_f32 v11, v102, v103
	v_cvt_pk_bf16_f32 v12, v104, v105
	v_cvt_pk_bf16_f32 v13, v106, v107
	global_store_dwordx4 v[70:71], v[10:13], off offset:-128
	v_mul_f32_e32 v116, v116, v108
	v_mul_f32_e32 v117, v117, v109
	v_mul_f32_e32 v118, v118, v110
	v_mul_f32_e32 v119, v119, v111
	v_mul_f32_e32 v120, v120, v112
	v_mul_f32_e32 v121, v121, v113
	v_mul_f32_e32 v122, v122, v114
	v_mul_f32_e32 v123, v123, v115
	v_cvt_pk_bf16_f32 v14, v116, v117
	v_cvt_pk_bf16_f32 v15, v118, v119
	v_cvt_pk_bf16_f32 v16, v120, v121
	v_cvt_pk_bf16_f32 v17, v122, v123
	v_mul_f32_e32 v100, v100, v100
	v_mul_f32_e32 v101, v101, v101
	v_mul_f32_e32 v102, v102, v102
	v_mul_f32_e32 v103, v103, v103
	v_mul_f32_e32 v104, v104, v104
	v_mul_f32_e32 v105, v105, v105
	v_mul_f32_e32 v106, v106, v106
	v_mul_f32_e32 v107, v107, v107
	v_add_f32_e32 v100, v100, v101
	v_add_f32_e32 v102, v102, v103
	v_add_f32_e32 v100, v100, v102
	v_add_f32_e32 v104, v104, v105
	v_add_f32_e32 v100, v100, v104
	v_add_f32_e32 v106, v106, v107
	v_add_f32_e32 v100, v100, v106
	v_add_f32_e32 v2, v2, v100
	v_mfma_f32_16x16x32_bf16 v[6:9], v[10:13], v[14:17], v[6:9]
	s_waitcnt vmcnt(24)
	v_cvt_pk_bf16_f32 v18, v124, v125
	v_cvt_pk_bf16_f32 v19, v126, v127
	v_cvt_pk_bf16_f32 v20, v128, v129
	v_cvt_pk_bf16_f32 v21, v130, v131
	global_store_dwordx4 v[70:71], v[18:21], off offset:-64
	v_mul_f32_e32 v140, v140, v132
	v_mul_f32_e32 v141, v141, v133
	v_mul_f32_e32 v142, v142, v134
	v_mul_f32_e32 v143, v143, v135
	v_mul_f32_e32 v144, v144, v136
	v_mul_f32_e32 v145, v145, v137
	v_mul_f32_e32 v146, v146, v138
	v_mul_f32_e32 v147, v147, v139
	v_cvt_pk_bf16_f32 v22, v140, v141
	v_cvt_pk_bf16_f32 v23, v142, v143
	v_cvt_pk_bf16_f32 v24, v144, v145
	v_cvt_pk_bf16_f32 v25, v146, v147
	v_mul_f32_e32 v124, v124, v124
	v_mul_f32_e32 v125, v125, v125
	v_mul_f32_e32 v126, v126, v126
	v_mul_f32_e32 v127, v127, v127
	v_mul_f32_e32 v128, v128, v128
	v_mul_f32_e32 v129, v129, v129
	v_mul_f32_e32 v130, v130, v130
	v_mul_f32_e32 v131, v131, v131
	v_add_f32_e32 v124, v124, v125
	v_add_f32_e32 v126, v126, v127
	v_add_f32_e32 v124, v124, v126
	v_add_f32_e32 v128, v128, v129
	v_add_f32_e32 v124, v124, v128
	v_add_f32_e32 v130, v130, v131
	v_add_f32_e32 v124, v124, v130
	v_add_f32_e32 v2, v2, v124
	v_mfma_f32_16x16x32_bf16 v[6:9], v[18:21], v[22:25], v[6:9]
	s_waitcnt vmcnt(12)
	v_cvt_pk_bf16_f32 v10, v168, v169
	v_cvt_pk_bf16_f32 v11, v170, v171
	v_cvt_pk_bf16_f32 v12, v172, v173
	v_cvt_pk_bf16_f32 v13, v174, v175
	global_store_dwordx4 v[70:71], v[10:13], off
	v_mul_f32_e32 v184, v184, v176
	v_mul_f32_e32 v185, v185, v177
	v_mul_f32_e32 v186, v186, v178
	v_mul_f32_e32 v187, v187, v179
	v_mul_f32_e32 v188, v188, v180
	v_mul_f32_e32 v189, v189, v181
	v_mul_f32_e32 v190, v190, v182
	v_mul_f32_e32 v191, v191, v183
	v_cvt_pk_bf16_f32 v14, v184, v185
	v_cvt_pk_bf16_f32 v15, v186, v187
	v_cvt_pk_bf16_f32 v16, v188, v189
	v_cvt_pk_bf16_f32 v17, v190, v191
	v_mul_f32_e32 v168, v168, v168
	v_mul_f32_e32 v169, v169, v169
	v_mul_f32_e32 v170, v170, v170
	v_mul_f32_e32 v171, v171, v171
	v_mul_f32_e32 v172, v172, v172
	v_mul_f32_e32 v173, v173, v173
	v_mul_f32_e32 v174, v174, v174
	v_mul_f32_e32 v175, v175, v175
	v_add_f32_e32 v168, v168, v169
	v_add_f32_e32 v170, v170, v171
	v_add_f32_e32 v168, v168, v170
	v_add_f32_e32 v172, v172, v173
	v_add_f32_e32 v168, v168, v172
	v_add_f32_e32 v174, v174, v175
	v_add_f32_e32 v168, v168, v174
	v_add_f32_e32 v2, v2, v168
	v_mfma_f32_16x16x32_bf16 v[6:9], v[10:13], v[14:17], v[6:9]
	s_waitcnt vmcnt(0)
	v_cvt_pk_bf16_f32 v18, v192, v193
	v_cvt_pk_bf16_f32 v19, v194, v195
	v_cvt_pk_bf16_f32 v20, v196, v197
	v_cvt_pk_bf16_f32 v21, v198, v199
	global_store_dwordx4 v[70:71], v[18:21], off offset:64
	v_mul_f32_e32 v208, v208, v200
	v_mul_f32_e32 v209, v209, v201
	v_mul_f32_e32 v210, v210, v202
	v_mul_f32_e32 v211, v211, v203
	v_mul_f32_e32 v212, v212, v204
	v_mul_f32_e32 v213, v213, v205
	v_mul_f32_e32 v214, v214, v206
	v_mul_f32_e32 v215, v215, v207
	v_cvt_pk_bf16_f32 v22, v208, v209
	v_cvt_pk_bf16_f32 v23, v210, v211
	v_cvt_pk_bf16_f32 v24, v212, v213
	v_cvt_pk_bf16_f32 v25, v214, v215
	v_mul_f32_e32 v192, v192, v192
	v_mul_f32_e32 v193, v193, v193
	v_mul_f32_e32 v194, v194, v194
	v_mul_f32_e32 v195, v195, v195
	v_mul_f32_e32 v196, v196, v196
	v_mul_f32_e32 v197, v197, v197
	v_mul_f32_e32 v198, v198, v198
	v_mul_f32_e32 v199, v199, v199
	v_add_f32_e32 v192, v192, v193
	v_add_f32_e32 v194, v194, v195
	v_add_f32_e32 v192, v192, v194
	v_add_f32_e32 v196, v196, v197
	v_add_f32_e32 v192, v192, v196
	v_add_f32_e32 v198, v198, v199
	v_add_f32_e32 v192, v192, v198
	v_add_f32_e32 v2, v2, v192
	v_mfma_f32_16x16x32_bf16 v[6:9], v[18:21], v[22:25], v[6:9]
	s_nop 7
	s_andn2_b64 vcc, exec, s[18:19]
	v_add_u32_e32 v12, 0x3000, v92
	v_add_u32_e32 v4, 0x3008, v92
	s_cbranch_vccnz .LBB0_13
	s_nop 2
	ds_write2_b32 v12, v6, v7 offset1:1
	ds_write2_b32 v4, v8, v9 offset1:1
	ds_write_b32 v92, v2 offset:12304

; __device__ __forceinline__ float logsigmoidf_(float x) { const float e = __expf(-fabsf(x)), u = 1.0f + e, d = u - 1.0f; const float l = (d == 0.f) ? e : __logf(u) * (e * __builtin_amdgcn_rcpf(d)); return fminf(x, 0.f) - l; }
;     __device__ __forceinline__ void operator()(const f32x4 (&acc)[2][2][4][2], const Unit& u, int wr, int wc, int fr, int fq) const {
;         const int row0 = u.pm * BM + wr * 64 + fr, blk = u.pn >> 1, lh = u.pn & 1;
;         const int chb = 128 * lh + 32 * wc + 8 * fq, chg = blk * 256 + chb;
;         f32x4 br[2], bi[2], ls[2];
;         constexpr float NL2E = -1.4426950408889634f;
; #pragma unroll
;         for (int n = 0; n < 2; ++n) { br[n] = *(const f32x4*)(gate_b + blk * 512 + chb + 4 * n) * NL2E; bi[n] = *(const f32x4*)(gate_b + blk * 512 + 256 + chb + 4 * n) * NL2E;
;             const f32x4 ap = *(const f32x4*)(a_param + chg + 4 * n);
; #pragma unroll
;             for (int j = 0; j < 4; ++j) ls[n][j] = 8.0f * logsigmoidf_(ap[j]); }
; #pragma unroll
;         for (int ai = 0; ai < 2; ++ai)
; #pragma unroll
;             for (int m = 0; m < 4; ++m) { const size_t rowoff = (size_t)(row0 + ai * HALF + m * 16) * 2048 + chg;
;                 const u32x4 xw = *(const u32x4*)(XC + rowoff);
.LBB0_1043:
	v_and_b32_e32 v240, 15, v167
	v_lshrrev_b32_e32 v241, 4, v167
	s_lshl_b32 s4, s10, 8
	s_add_i32 s4, s4, s78
	v_or_b32_e32 v240, s4, v240
	s_lshr_b32 s4, s83, 1
	s_lshl_b32 s4, s4, 8
	s_and_b32 s5, s83, 1
	s_lshl_b32 s5, s5, 7
	s_add_i32 s4, s4, s5
	s_add_i32 s4, s4, s82
	v_lshl_add_u32 v241, v241, 3, s4
	v_lshlrev_b32_e32 v241, 1, v241
	v_lshl_add_u32 v241, v240, 12, v241
	v_add_u32_e32 v242, 0x10000, v241
	v_add_u32_e32 v243, 0x20000, v241
	v_add_u32_e32 v244, 0x30000, v241
	v_add_u32_e32 v245, 0x80000, v241
	v_add_u32_e32 v246, 0x90000, v241
	v_add_u32_e32 v247, 0xa0000, v241
	v_add_u32_e32 v248, 0xb0000, v241
	global_load_dwordx4 v[208:211], v241, s[20:21]
	global_load_dwordx4 v[212:215], v242, s[20:21]
	global_load_dwordx4 v[216:219], v243, s[20:21]
	global_load_dwordx4 v[220:223], v244, s[20:21]
	global_load_dwordx4 v[224:227], v245, s[20:21]
	global_load_dwordx4 v[228:231], v246, s[20:21]
	global_load_dwordx4 v[232:235], v247, s[20:21]
	global_load_dwordx4 v[236:239], v248, s[20:21]
	v_mov_b32_e32 v160, v167
	s_lshl_b32 s5, s83, 7
	s_and_b32 s5, s5, 0x80
	v_ashrrev_i32_e32 v128, 1, v160
	s_or_b32 s5, s5, s82
	v_and_b32_e32 v128, -8, v128
	s_ashr_i32 s4, s83, 1
	v_add_u32_e32 v128, s5, v128
	v_lshl_add_u32 v162, s4, 8, v128
	s_lshl_b32 s4, s4, 9
	s_lshl_b32 s61, s10, 8
	s_ashr_i32 s5, s4, 31
	s_add_i32 s61, s61, s78
	s_lshl_b64 s[4:5], s[4:5], 2
	s_add_u32 s4, s16, s4
	s_addc_u32 s5, s17, s5
	v_ashrrev_i32_e32 v129, 31, v128
	v_lshl_add_u64 v[128:129], v[128:129], 2, s[4:5]
	global_load_dwordx4 v[144:147], v[128:129], off
	global_load_dwordx4 v[152:155], v[128:129], off offset:1024
	v_ashrrev_i32_e32 v163, 31, v162
	v_lshl_add_u64 v[130:131], v[162:163], 2, s[18:19]
	global_load_dwordx4 v[156:159], v[130:131], off
	global_load_dwordx4 v[176:179], v[128:129], off offset:16
	global_load_dwordx4 v[180:183], v[128:129], off offset:1040
	s_nop 0
	global_load_dwordx4 v[128:131], v[130:131], off offset:16
	s_waitcnt vmcnt(0)
	v_pk_mul_f32 v[150:151], v[144:145], s[40:41] op_sel_hi:[1,0]
	v_pk_mul_f32 v[148:149], v[152:153], s[40:41] op_sel_hi:[1,0]
	v_mul_f32_e64 v152, |v156|, s40
	v_pk_mul_f32 v[144:145], v[154:155], s[40:41] op_sel_hi:[1,0]
	v_mul_f32_e64 v154, |v157|, s40
	v_exp_f32_e32 v152, v152
	v_max_f32_e32 v153, v156, v156
	v_mul_f32_e64 v156, |v158|, s40
	v_exp_f32_e32 v154, v154
	v_exp_f32_e32 v156, v156
	v_add_f32_e32 v161, 1.0, v152
	v_cmp_gt_f32_e32 vcc, s75, v161
	v_add_f32_e32 v164, 1.0, v154
	v_add_f32_e32 v165, 1.0, v156
	v_cndmask_b32_e64 v174, 0, 32, vcc
	v_cmp_gt_f32_e64 s[10:11], s75, v164
	v_add_f32_e32 v172, -1.0, v161
	v_cmp_gt_f32_e64 s[12:13], s75, v165
	v_cndmask_b32_e64 v184, 0, 32, s[10:11]
	v_ldexp_f32 v161, v161, v174
	v_add_f32_e32 v175, -1.0, v164
	v_cndmask_b32_e64 v186, 0, 32, s[12:13]
	v_ldexp_f32 v164, v164, v184
	v_log_f32_e32 v161, v161
	v_add_f32_e32 v185, -1.0, v165
	v_ldexp_f32 v165, v165, v186
	v_log_f32_e32 v164, v164
	v_log_f32_e32 v165, v165
	v_max_f32_e32 v155, v157, v157
	v_max_f32_e32 v157, v158, v158
	v_mul_f32_e64 v158, |v159|, s40
	v_mul_f32_e32 v191, 0x3f317217, v161
	v_exp_f32_e32 v158, v158
	v_rcp_f32_e32 v188, v172
	v_mul_f32_e32 v192, 0x3f317217, v164
	v_fma_f32 v191, v161, s76, -v191
	v_mul_f32_e32 v193, 0x3f317217, v165
	v_fma_f32 v192, v164, s76, -v192
	v_fmac_f32_e32 v191, 0x3377d1cf, v161
	v_cndmask_b32_e32 v174, 0, v171, vcc
	v_fma_f32 v193, v165, s76, -v193
	v_fmac_f32_e32 v192, 0x3377d1cf, v164
	v_fmac_f32_e32 v191, 0x3f317217, v161
	v_cmp_lt_f32_e64 vcc, |v161|, s77
	v_rcp_f32_e32 v189, v175
	v_fmac_f32_e32 v193, 0x3377d1cf, v165
	v_fmac_f32_e32 v192, 0x3f317217, v164
	v_cndmask_b32_e32 v161, v161, v191, vcc
	v_cmp_lt_f32_e64 vcc, |v164|, s77
	v_add_f32_e32 v173, 1.0, v158
	v_rcp_f32_e32 v190, v185
	v_mul_f32_e32 v188, v152, v188
	v_fmac_f32_e32 v193, 0x3f317217, v165
	v_cndmask_b32_e32 v164, v164, v192, vcc
	v_cmp_lt_f32_e64 vcc, |v165|, s77
	v_sub_f32_e32 v161, v161, v174
	v_cmp_gt_f32_e64 s[14:15], s75, v173
	v_cndmask_b32_e32 v165, v165, v193, vcc
	v_mul_f32_e32 v161, v161, v188
	v_cmp_eq_f32_e32 vcc, 0, v172
	v_min_f32_e32 v153, 0, v153
	v_cndmask_b32_e64 v187, 0, 32, s[14:15]
	v_cndmask_b32_e64 v184, 0, v171, s[10:11]
	v_cndmask_b32_e32 v152, v161, v152, vcc
	v_cndmask_b32_e64 v186, 0, v171, s[12:13]
	v_ldexp_f32 v187, v173, v187
	v_mul_f32_e32 v189, v154, v189
	v_sub_f32_e32 v164, v164, v184
	v_sub_f32_e32 v152, v153, v152
	v_mul_f32_e32 v190, v156, v190
	v_sub_f32_e32 v165, v165, v186
	v_mul_f32_e32 v164, v164, v189
	v_cmp_eq_f32_e32 vcc, 0, v175
	v_mul_f32_e32 v175, 0x41000000, v152
	v_log_f32_e32 v152, v187
	v_min_f32_e32 v155, 0, v155
	v_mul_f32_e32 v165, v165, v190
	v_cndmask_b32_e32 v154, v164, v154, vcc
	v_cmp_eq_f32_e32 vcc, 0, v185
	v_min_f32_e32 v157, 0, v157
	v_sub_f32_e32 v153, v155, v154
	v_cndmask_b32_e32 v156, v165, v156, vcc
	v_mul_f32_e32 v174, 0x41000000, v153
	v_sub_f32_e32 v153, v157, v156
	v_mul_f32_e32 v172, 0x41000000, v153
	v_add_f32_e32 v153, -1.0, v173
	v_mul_f32_e32 v154, 0x3f317217, v152
	v_fma_f32 v154, v152, s76, -v154
	v_rcp_f32_e32 v155, v153
	v_fmac_f32_e32 v154, 0x3377d1cf, v152
	v_fmac_f32_e32 v154, 0x3f317217, v152
	v_cmp_lt_f32_e64 vcc, |v152|, s77
	v_pk_mul_f32 v[156:157], v[176:177], s[40:41] op_sel_hi:[1,0]
	v_fmamk_f32 v120, v120, 0xbfb8aa3b, v150
	v_cndmask_b32_e32 v152, v152, v154, vcc
	v_cndmask_b32_e64 v154, 0, v171, s[14:15]
	v_sub_f32_e32 v152, v152, v154
	v_mul_f32_e32 v154, v158, v155
	v_mul_f32_e32 v152, v152, v154
	v_cmp_eq_f32_e32 vcc, 0, v153
	v_max_f32_e32 v153, v159, v159
	v_min_f32_e32 v153, 0, v153
	v_cndmask_b32_e32 v152, v152, v158, vcc
	v_sub_f32_e32 v152, v153, v152
	v_mul_f32_e64 v153, |v128|, s40
; __device__ __forceinline__ unsigned cvt_pk_bf16(float lo, float hi) { unsigned r; asm volatile("v_cvt_pk_bf16_f32 %0, %1, %2" : "=v"(r) : "v"(lo), "v"(hi)); return r; }
; __device__ __forceinline__ float logsigmoidf_(float x) { const float e = __expf(-fabsf(x)), u = 1.0f + e, d = u - 1.0f; const float l = (d == 0.f) ? e : __logf(u) * (e * __builtin_amdgcn_rcpf(d)); return fminf(x, 0.f) - l; }
; __device__ __forceinline__ float bf_lo(unsigned w) { return __uint_as_float(w << 16); }
;     __device__ __forceinline__ void operator()(const f32x4 (&acc)[2][2][4][2], const Unit& u, int wr, int wc, int fr, int fq) const {
;     ...
;         for (int n = 0; n < 2; ++n) { br[n] = *(const f32x4*)(gate_b + blk * 512 + chb + 4 * n) * NL2E; bi[n] = *(const f32x4*)(gate_b + blk * 512 + 256 + chb + 4 * n) * NL2E;
;             const f32x4 ap = *(const f32x4*)(a_param + chg + 4 * n);
; #pragma unroll
;             for (int j = 0; j < 4; ++j) ls[n][j] = 8.0f * logsigmoidf_(ap[j]); }
; #pragma unroll
;         for (int ai = 0; ai < 2; ++ai)
; #pragma unroll
;             for (int m = 0; m < 4; ++m) { const size_t rowoff = (size_t)(row0 + ai * HALF + m * 16) * 2048 + chg;
;                 const u32x4 xw = *(const u32x4*)(XC + rowoff);
;                 const float xc[8] = {bf_lo(xw.x), bf_hi(xw.x), bf_lo(xw.y), bf_hi(xw.y), bf_lo(xw.z), bf_hi(xw.z), bf_lo(xw.w), bf_hi(xw.w)}; float la[8], uu[8];
; #pragma unroll
;                 for (int n = 0; n < 2; ++n)
; #pragma unroll
;                     for (int j = 0; j < 4; ++j) { const float r = __builtin_amdgcn_rcpf(1.0f + __builtin_amdgcn_exp2f(__builtin_fmaf(acc[ai][0][m][n][j], NL2E, br[n][j])));
;                         const float ig = __builtin_amdgcn_rcpf(1.0f + __builtin_amdgcn_exp2f(__builtin_fmaf(acc[ai][1][m][n][j], NL2E, bi[n][j])));
;                         const float l = r * ls[n][j]; la[4 * n + j] = l;
;                         uu[4 * n + j] = __builtin_amdgcn_sqrtf(1.0f - __builtin_amdgcn_exp2f(l * 2.8853900817779268f)) * ig * xc[4 * n + j]; }
;                 u32x4 w; w.x = cvt_pk_bf16(la[0], la[1]); w.y = cvt_pk_bf16(la[2], la[3]); w.z = cvt_pk_bf16(la[4], la[5]); w.w = cvt_pk_bf16(la[6], la[7]); *(u32x4*)(LA + rowoff) = w;
;                 w.x = cvt_pk_bf16(uu[0], uu[1]); w.y = cvt_pk_bf16(uu[2], uu[3]); w.z = cvt_pk_bf16(uu[4], uu[5]); w.w = cvt_pk_bf16(uu[6], uu[7]); *(u32x4*)(U + rowoff) = w;
	v_exp_f32_e32 v184, v153
	v_pk_mul_f32 v[158:159], v[180:181], s[40:41] op_sel_hi:[1,0]
	v_mul_f32_e32 v173, 0x41000000, v152
	v_pk_mul_f32 v[152:153], v[178:179], s[40:41] op_sel_hi:[1,0]
	v_add_f32_e32 v161, 1.0, v184
	v_cmp_gt_f32_e32 vcc, s75, v161
	v_add_f32_e32 v180, -1.0, v161
	v_rcp_f32_e32 v165, v180
	v_cndmask_b32_e64 v154, 0, 32, vcc
	v_ldexp_f32 v154, v161, v154
	v_log_f32_e32 v164, v154
	v_pk_mul_f32 v[154:155], v[182:183], s[40:41] op_sel_hi:[1,0]
	v_max_f32_e32 v128, v128, v128
	v_min_f32_e32 v128, 0, v128
	v_mul_f32_e32 v161, 0x3f317217, v164
	v_fma_f32 v161, v164, s76, -v161
	v_fmac_f32_e32 v161, 0x3377d1cf, v164
	v_fmac_f32_e32 v161, 0x3f317217, v164
	v_cmp_lt_f32_e64 s[10:11], |v164|, s77
	v_exp_f32_e32 v120, v120
	v_pk_mul_f32 v[146:147], v[146:147], s[40:41] op_sel_hi:[1,0]
	v_cndmask_b32_e64 v161, v164, v161, s[10:11]
	v_cndmask_b32_e32 v164, 0, v171, vcc
	v_sub_f32_e32 v161, v161, v164
	v_mul_f32_e32 v164, v184, v165
	v_mul_f32_e32 v181, v161, v164
	v_and_or_b32 v164, v160, 15, s61
	v_mul_f32_e64 v161, |v129|, s40
	v_ashrrev_i32_e32 v165, 31, v164
	v_exp_f32_e32 v182, v161
	v_lshlrev_b64 v[160:161], 11, v[164:165]
	v_lshl_add_u64 v[160:161], v[160:161], 0, v[162:163]
	v_lshlrev_b64 v[160:161], 1, v[160:161]
	v_lshl_add_u64 v[176:177], s[20:21], 0, v[160:161]
	s_nop 1
	v_mov_b32_e32 v176, v208
	v_mov_b32_e32 v177, v209
	v_mov_b32_e32 v178, v210
	v_mov_b32_e32 v179, v211
	v_cmp_eq_f32_e32 vcc, 0, v180
	v_add_f32_e32 v180, 1.0, v182
	v_max_f32_e32 v129, v129, v129
	v_cndmask_b32_e32 v165, v181, v184, vcc
	v_cmp_gt_f32_e32 vcc, s75, v180
	v_sub_f32_e32 v128, v128, v165
	v_add_f32_e32 v165, -1.0, v180
	v_cndmask_b32_e64 v181, 0, 32, vcc
	v_ldexp_f32 v181, v180, v181
	v_log_f32_e32 v181, v181
	v_rcp_f32_e32 v183, v165
	v_min_f32_e32 v129, 0, v129
	v_add_f32_e32 v120, 1.0, v120
	v_mul_f32_e32 v180, 0x3f317217, v181
	v_fma_f32 v180, v181, s76, -v180
	v_fmac_f32_e32 v180, 0x3377d1cf, v181
	v_fmac_f32_e32 v180, 0x3f317217, v181
	v_cmp_lt_f32_e64 s[10:11], |v181|, s77
	v_rcp_f32_e32 v120, v120
	v_fmamk_f32 v124, v124, 0xbfb8aa3b, v148
	v_cndmask_b32_e64 v180, v181, v180, s[10:11]
	v_cndmask_b32_e32 v181, 0, v171, vcc
	v_sub_f32_e32 v180, v180, v181
	v_mul_f32_e32 v181, v182, v183
	v_mul_f32_e32 v180, v180, v181
	v_mul_f32_e64 v181, |v130|, s40
	v_exp_f32_e32 v181, v181
	v_cmp_eq_f32_e32 vcc, 0, v165
	v_max_f32_e32 v130, v130, v130
	v_min_f32_e32 v130, 0, v130
	v_cndmask_b32_e32 v165, v180, v182, vcc
	v_add_f32_e32 v180, 1.0, v181
	v_cmp_gt_f32_e32 vcc, s75, v180
	v_sub_f32_e32 v129, v129, v165
	v_add_f32_e32 v165, -1.0, v180
	v_cndmask_b32_e64 v182, 0, 32, vcc
	v_ldexp_f32 v182, v180, v182
	v_log_f32_e32 v182, v182
	v_rcp_f32_e32 v183, v165
	v_mul_f32_e32 v120, v120, v175
	v_fmamk_f32 v122, v122, 0xbfb8aa3b, v146
	v_mul_f32_e32 v180, 0x3f317217, v182
	v_fma_f32 v180, v182, s76, -v180
	v_fmac_f32_e32 v180, 0x3377d1cf, v182
	v_fmac_f32_e32 v180, 0x3f317217, v182
	v_cmp_lt_f32_e64 s[10:11], |v182|, s77
	v_exp_f32_e32 v124, v124
	v_exp_f32_e32 v122, v122
	v_cndmask_b32_e64 v180, v182, v180, s[10:11]
	v_cndmask_b32_e32 v182, 0, v171, vcc
	v_sub_f32_e32 v180, v180, v182
	v_mul_f32_e32 v182, v181, v183
	v_mul_f32_e32 v180, v180, v182
	v_mul_f32_e64 v182, |v131|, s40
	v_exp_f32_e32 v182, v182
	v_cmp_eq_f32_e32 vcc, 0, v165
	v_add_f32_e32 v124, 1.0, v124
	v_add_f32_e32 v122, 1.0, v122
	v_cndmask_b32_e32 v165, v180, v181, vcc
	v_add_f32_e32 v180, 1.0, v182
	v_cmp_gt_f32_e32 vcc, s75, v180
	v_sub_f32_e32 v130, v130, v165
	v_mul_f32_e32 v165, 0x41000000, v130
	v_cndmask_b32_e64 v181, 0, 32, vcc
	v_ldexp_f32 v181, v180, v181
	v_log_f32_e32 v181, v181
	v_add_f32_e32 v130, -1.0, v180
	v_rcp_f32_e32 v183, v130
	v_rcp_f32_e32 v124, v124
	v_mul_f32_e32 v180, 0x3f317217, v181
	v_fma_f32 v180, v181, s76, -v180
	v_fmac_f32_e32 v180, 0x3377d1cf, v181
	v_fmac_f32_e32 v180, 0x3f317217, v181
	v_cmp_lt_f32_e64 s[10:11], |v181|, s77
	v_rcp_f32_e32 v122, v122
	v_max_f32_e32 v131, v131, v131
	v_cndmask_b32_e64 v180, v181, v180, s[10:11]
	v_cndmask_b32_e32 v181, 0, v171, vcc
	v_sub_f32_e32 v180, v180, v181
	v_mul_f32_e32 v181, v182, v183
	v_mul_f32_e32 v183, 0x4038aa3b, v120
	v_exp_f32_e32 v183, v183
	v_mul_f32_e32 v180, v180, v181
	v_cmp_eq_f32_e32 vcc, 0, v130
	v_min_f32_e32 v131, 0, v131
	v_sub_f32_e32 v183, 1.0, v183
	v_sqrt_f32_e32 v183, v183
	v_cndmask_b32_e32 v130, v180, v182, vcc
	v_sub_f32_e32 v130, v131, v130
	v_lshlrev_b32_e32 v131, 16, v176
	v_mul_f32_e32 v124, v124, v183
	v_mul_f32_e32 v122, v122, v172
	v_fmamk_f32 v123, v123, 0xbfb8aa3b, v147
	v_fmamk_f32 v126, v126, 0xbfb8aa3b, v144
	v_mul_f32_e32 v124, v124, v131
	v_mul_f32_e32 v131, 0x4038aa3b, v122
	v_exp_f32_e32 v123, v123
	v_exp_f32_e32 v126, v126
	v_exp_f32_e32 v131, v131
	v_fmamk_f32 v127, v127, 0xbfb8aa3b, v145
	v_add_f32_e32 v123, 1.0, v123
	v_add_f32_e32 v126, 1.0, v126
	v_sub_f32_e32 v131, 1.0, v131
	v_rcp_f32_e32 v123, v123
	v_rcp_f32_e32 v126, v126
	v_sqrt_f32_e32 v131, v131
	v_fmamk_f32 v112, v112, 0xbfb8aa3b, v156
	v_mul_f32_e32 v123, v123, v173
	v_exp_f32_e32 v127, v127
	v_mul_f32_e32 v126, v126, v131
	v_mul_f32_e32 v131, 0x4038aa3b, v123
	v_exp_f32_e32 v131, v131
	v_exp_f32_e32 v112, v112
	v_add_f32_e32 v127, 1.0, v127
	v_rcp_f32_e32 v127, v127
	v_sub_f32_e32 v131, 1.0, v131
	v_add_f32_e32 v112, 1.0, v112
	v_sqrt_f32_e32 v131, v131
	v_rcp_f32_e32 v112, v112
	v_mul_f32_e32 v128, 0x41000000, v128
	v_fmamk_f32 v121, v121, 0xbfb8aa3b, v151
	v_mul_f32_e32 v127, v127, v131
	v_mul_f32_e32 v131, v112, v128
	v_exp_f32_e32 v121, v121
	v_fmamk_f32 v116, v116, 0xbfb8aa3b, v158
	v_mul_f32_e32 v112, 0x4038aa3b, v131
	v_fmamk_f32 v113, v113, 0xbfb8aa3b, v157
	v_exp_f32_e32 v116, v116
; __device__ __forceinline__ unsigned cvt_pk_bf16(float lo, float hi) { unsigned r; asm volatile("v_cvt_pk_bf16_f32 %0, %1, %2" : "=v"(r) : "v"(lo), "v"(hi)); return r; }
; __device__ __forceinline__ float bf_lo(unsigned w) { return __uint_as_float(w << 16); }
; __device__ __forceinline__ float bf_hi(unsigned w) { return __uint_as_float(w & 0xffff0000u); }
;     __device__ __forceinline__ void operator()(const f32x4 (&acc)[2][2][4][2], const Unit& u, int wr, int wc, int fr, int fq) const {
;     ...
;             for (int m = 0; m < 4; ++m) { const size_t rowoff = (size_t)(row0 + ai * HALF + m * 16) * 2048 + chg;
;                 const u32x4 xw = *(const u32x4*)(XC + rowoff);
;                 const float xc[8] = {bf_lo(xw.x), bf_hi(xw.x), bf_lo(xw.y), bf_hi(xw.y), bf_lo(xw.z), bf_hi(xw.z), bf_lo(xw.w), bf_hi(xw.w)}; float la[8], uu[8];
; #pragma unroll
;                 for (int n = 0; n < 2; ++n)
; #pragma unroll
;                     for (int j = 0; j < 4; ++j) { const float r = __builtin_amdgcn_rcpf(1.0f + __builtin_amdgcn_exp2f(__builtin_fmaf(acc[ai][0][m][n][j], NL2E, br[n][j])));
;                         const float ig = __builtin_amdgcn_rcpf(1.0f + __builtin_amdgcn_exp2f(__builtin_fmaf(acc[ai][1][m][n][j], NL2E, bi[n][j])));
;                         const float l = r * ls[n][j]; la[4 * n + j] = l;
;                         uu[4 * n + j] = __builtin_amdgcn_sqrtf(1.0f - __builtin_amdgcn_exp2f(l * 2.8853900817779268f)) * ig * xc[4 * n + j]; }
;                 u32x4 w; w.x = cvt_pk_bf16(la[0], la[1]); w.y = cvt_pk_bf16(la[2], la[3]); w.z = cvt_pk_bf16(la[4], la[5]); w.w = cvt_pk_bf16(la[6], la[7]); *(u32x4*)(LA + rowoff) = w;
;                 w.x = cvt_pk_bf16(uu[0], uu[1]); w.y = cvt_pk_bf16(uu[2], uu[3]); w.z = cvt_pk_bf16(uu[4], uu[5]); w.w = cvt_pk_bf16(uu[6], uu[7]); *(u32x4*)(U + rowoff) = w;
;                 asm volatile("" ::: "memory"); }
	v_exp_f32_e32 v112, v112
	v_exp_f32_e32 v113, v113
	v_add_f32_e32 v121, 1.0, v121
	v_rcp_f32_e32 v121, v121
	v_add_f32_e32 v116, 1.0, v116
	v_sub_f32_e32 v112, 1.0, v112
	v_add_f32_e32 v113, 1.0, v113
	v_fmamk_f32 v117, v117, 0xbfb8aa3b, v159
	v_rcp_f32_e32 v116, v116
	v_sqrt_f32_e32 v112, v112
	v_exp_f32_e32 v117, v117
	v_rcp_f32_e32 v113, v113
	v_mul_f32_e32 v129, 0x41000000, v129
	v_mul_f32_e32 v121, v121, v174
	v_fmamk_f32 v125, v125, 0xbfb8aa3b, v149
	v_mul_f32_e32 v183, 0x4038aa3b, v121
	v_mul_f32_e32 v112, v116, v112
	v_add_f32_e32 v116, 1.0, v117
	v_mul_f32_e32 v117, v113, v129
	v_exp_f32_e32 v125, v125
	v_exp_f32_e32 v183, v183
	v_mul_f32_e32 v113, 0x4038aa3b, v117
	v_fmamk_f32 v114, v114, 0xbfb8aa3b, v152
	v_exp_f32_e32 v113, v113
	v_exp_f32_e32 v114, v114
	v_add_f32_e32 v125, 1.0, v125
	v_sub_f32_e32 v183, 1.0, v183
	v_rcp_f32_e32 v125, v125
	v_sqrt_f32_e32 v183, v183
	v_sub_f32_e32 v113, 1.0, v113
	v_add_f32_e32 v114, 1.0, v114
	v_rcp_f32_e32 v116, v116
	v_sqrt_f32_e32 v113, v113
	v_rcp_f32_e32 v114, v114
	v_and_b32_e32 v176, 0xffff0000, v176
	v_lshlrev_b32_e32 v181, 16, v178
	v_mul_f32_e32 v125, v125, v183
	v_mul_f32_e32 v125, v125, v176
	v_mul_f32_e32 v176, v112, v181
	v_mul_f32_e32 v112, v116, v113
	v_mul_f32_e32 v116, v114, v165
	v_fmamk_f32 v114, v115, 0xbfb8aa3b, v153
	v_exp_f32_e32 v114, v114
	v_fmamk_f32 v118, v118, 0xbfb8aa3b, v154
	v_exp_f32_e32 v118, v118
	v_mul_f32_e32 v130, 0x41000000, v130
	v_add_f32_e32 v114, 1.0, v114
	v_rcp_f32_e32 v114, v114
	v_add_f32_e32 v113, 1.0, v118
	v_mul_f32_e32 v115, 0x4038aa3b, v116
	v_fmamk_f32 v118, v119, 0xbfb8aa3b, v155
	v_mul_f32_e32 v119, v114, v130
	v_exp_f32_e32 v115, v115
	v_mul_f32_e32 v114, 0x4038aa3b, v119
	v_exp_f32_e32 v118, v118
	v_exp_f32_e32 v114, v114
	v_sub_f32_e32 v115, 1.0, v115
	v_rcp_f32_e32 v113, v113
	v_sqrt_f32_e32 v115, v115
	v_add_f32_e32 v118, 1.0, v118
	v_sub_f32_e32 v114, 1.0, v114
	v_rcp_f32_e32 v118, v118
	v_sqrt_f32_e32 v114, v114
	v_lshlrev_b32_e32 v180, 16, v177
	v_and_b32_e32 v177, 0xffff0000, v177
	v_and_b32_e32 v178, 0xffff0000, v178
	v_lshlrev_b32_e32 v182, 16, v179
	v_mul_f32_e32 v127, v127, v177
	v_mul_f32_e32 v177, v112, v178
	v_mul_f32_e32 v112, v113, v115
	v_and_b32_e32 v179, 0xffff0000, v179
	v_mul_f32_e32 v178, v112, v182
	v_mul_f32_e32 v112, v118, v114
	v_mul_f32_e32 v118, v112, v179
	v_cvt_pk_bf16_f32 v112, v120, v121
	v_cvt_pk_bf16_f32 v113, v122, v123
	v_cvt_pk_bf16_f32 v114, v131, v117
	v_cvt_pk_bf16_f32 v115, v116, v119
	v_lshl_add_u64 v[116:117], s[26:27], 0, v[160:161]
	global_store_dwordx4 v[116:117], v[112:115], off
	v_lshl_add_u64 v[116:117], s[28:29], 0, v[160:161]
	v_mul_f32_e32 v126, v126, v180
	v_cvt_pk_bf16_f32 v112, v124, v125
	v_cvt_pk_bf16_f32 v113, v126, v127
	v_cvt_pk_bf16_f32 v114, v176, v177
	v_cvt_pk_bf16_f32 v115, v178, v118
	global_store_dwordx4 v[116:117], v[112:115], off
	v_fmamk_f32 v104, v104, 0xbfb8aa3b, v150
	v_exp_f32_e32 v104, v104
	v_or_b32_e32 v112, 16, v164
	v_ashrrev_i32_e32 v113, 31, v112
	v_lshlrev_b64 v[112:113], 11, v[112:113]
	v_lshl_add_u64 v[112:113], v[112:113], 0, v[162:163]
	v_lshlrev_b64 v[116:117], 1, v[112:113]
	v_lshl_add_u64 v[112:113], s[20:21], 0, v[116:117]
	s_nop 1
	v_mov_b32_e32 v112, v212
	v_mov_b32_e32 v113, v213
	v_mov_b32_e32 v114, v214
	v_mov_b32_e32 v115, v215
	v_add_f32_e32 v104, 1.0, v104
	v_rcp_f32_e32 v104, v104
	v_fmamk_f32 v105, v105, 0xbfb8aa3b, v151
	v_fmamk_f32 v108, v108, 0xbfb8aa3b, v148
	v_exp_f32_e32 v105, v105
	v_mul_f32_e32 v104, v104, v175
	v_mul_f32_e32 v122, 0x4038aa3b, v104
	v_exp_f32_e32 v108, v108
	v_exp_f32_e32 v122, v122
	v_add_f32_e32 v105, 1.0, v105
	v_rcp_f32_e32 v105, v105
	v_add_f32_e32 v108, 1.0, v108
	v_sub_f32_e32 v122, 1.0, v122
	v_rcp_f32_e32 v108, v108
	v_sqrt_f32_e32 v122, v122
	v_mul_f32_e32 v105, v105, v174
	v_fmamk_f32 v109, v109, 0xbfb8aa3b, v149
	v_fmamk_f32 v107, v107, 0xbfb8aa3b, v147
	v_mul_f32_e32 v108, v108, v122
	v_mul_f32_e32 v122, 0x4038aa3b, v105
	v_exp_f32_e32 v109, v109
	v_exp_f32_e32 v122, v122
	v_exp_f32_e32 v107, v107
	v_fmamk_f32 v111, v111, 0xbfb8aa3b, v145
	v_add_f32_e32 v109, 1.0, v109
	v_sub_f32_e32 v122, 1.0, v122
	v_add_f32_e32 v107, 1.0, v107
	v_rcp_f32_e32 v109, v109
	v_sqrt_f32_e32 v122, v122
	v_rcp_f32_e32 v107, v107
	v_fmamk_f32 v96, v96, 0xbfb8aa3b, v156
	v_exp_f32_e32 v111, v111
	v_mul_f32_e32 v109, v109, v122
	v_mul_f32_e32 v107, v107, v173
	v_exp_f32_e32 v96, v96
	v_add_f32_e32 v111, 1.0, v111
	v_rcp_f32_e32 v111, v111
	v_fmamk_f32 v100, v100, 0xbfb8aa3b, v158
	v_add_f32_e32 v96, 1.0, v96
	v_rcp_f32_e32 v96, v96
	v_fmamk_f32 v97, v97, 0xbfb8aa3b, v157
	v_exp_f32_e32 v100, v100
	v_exp_f32_e32 v97, v97
	v_fmamk_f32 v101, v101, 0xbfb8aa3b, v159
	v_exp_f32_e32 v101, v101
	v_add_f32_e32 v100, 1.0, v100
	v_add_f32_e32 v97, 1.0, v97
	v_rcp_f32_e32 v100, v100
	v_rcp_f32_e32 v97, v97
	v_fmamk_f32 v98, v98, 0xbfb8aa3b, v152
	v_exp_f32_e32 v98, v98
	v_fmamk_f32 v106, v106, 0xbfb8aa3b, v146
	v_exp_f32_e32 v106, v106
	v_fmamk_f32 v102, v102, 0xbfb8aa3b, v154
	v_add_f32_e32 v98, 1.0, v98
	v_rcp_f32_e32 v98, v98
	v_add_f32_e32 v106, 1.0, v106
	v_rcp_f32_e32 v106, v106
	v_exp_f32_e32 v102, v102
	v_fmamk_f32 v110, v110, 0xbfb8aa3b, v144
	v_exp_f32_e32 v110, v110
	v_mul_f32_e32 v106, v106, v172
	v_fmamk_f32 v88, v88, 0xbfb8aa3b, v150
	v_exp_f32_e32 v88, v88
	v_add_f32_e32 v110, 1.0, v110
	v_rcp_f32_e32 v110, v110
	v_fmamk_f32 v89, v89, 0xbfb8aa3b, v151
	v_add_f32_e32 v88, 1.0, v88
	v_rcp_f32_e32 v88, v88
	v_fmamk_f32 v92, v92, 0xbfb8aa3b, v148
	v_exp_f32_e32 v89, v89
	v_exp_f32_e32 v92, v92
	v_mul_f32_e32 v88, v88, v175
	v_fmamk_f32 v93, v93, 0xbfb8aa3b, v149
	v_add_f32_e32 v89, 1.0, v89
	v_add_f32_e32 v92, 1.0, v92
; __device__ __forceinline__ unsigned cvt_pk_bf16(float lo, float hi) { unsigned r; asm volatile("v_cvt_pk_bf16_f32 %0, %1, %2" : "=v"(r) : "v"(lo), "v"(hi)); return r; }
; __device__ __forceinline__ float bf_lo(unsigned w) { return __uint_as_float(w << 16); }
; __device__ __forceinline__ float bf_hi(unsigned w) { return __uint_as_float(w & 0xffff0000u); }
;     __device__ __forceinline__ void operator()(const f32x4 (&acc)[2][2][4][2], const Unit& u, int wr, int wc, int fr, int fq) const {
;     ...
;             for (int m = 0; m < 4; ++m) { const size_t rowoff = (size_t)(row0 + ai * HALF + m * 16) * 2048 + chg;
;                 const u32x4 xw = *(const u32x4*)(XC + rowoff);
;                 const float xc[8] = {bf_lo(xw.x), bf_hi(xw.x), bf_lo(xw.y), bf_hi(xw.y), bf_lo(xw.z), bf_hi(xw.z), bf_lo(xw.w), bf_hi(xw.w)}; float la[8], uu[8];
; #pragma unroll
;                 for (int n = 0; n < 2; ++n)
; #pragma unroll
;                     for (int j = 0; j < 4; ++j) { const float r = __builtin_amdgcn_rcpf(1.0f + __builtin_amdgcn_exp2f(__builtin_fmaf(acc[ai][0][m][n][j], NL2E, br[n][j])));
;                         const float ig = __builtin_amdgcn_rcpf(1.0f + __builtin_amdgcn_exp2f(__builtin_fmaf(acc[ai][1][m][n][j], NL2E, bi[n][j])));
;                         const float l = r * ls[n][j]; la[4 * n + j] = l;
;                         uu[4 * n + j] = __builtin_amdgcn_sqrtf(1.0f - __builtin_amdgcn_exp2f(l * 2.8853900817779268f)) * ig * xc[4 * n + j]; }
;                 u32x4 w; w.x = cvt_pk_bf16(la[0], la[1]); w.y = cvt_pk_bf16(la[2], la[3]); w.z = cvt_pk_bf16(la[4], la[5]); w.w = cvt_pk_bf16(la[6], la[7]); *(u32x4*)(LA + rowoff) = w;
;                 w.x = cvt_pk_bf16(uu[0], uu[1]); w.y = cvt_pk_bf16(uu[2], uu[3]); w.z = cvt_pk_bf16(uu[4], uu[5]); w.w = cvt_pk_bf16(uu[6], uu[7]); *(u32x4*)(U + rowoff) = w;
	v_rcp_f32_e32 v89, v89
	v_rcp_f32_e32 v92, v92
	v_fmamk_f32 v91, v91, 0xbfb8aa3b, v147
	v_lshlrev_b32_e32 v118, 16, v112
	v_and_b32_e32 v112, 0xffff0000, v112
	v_mul_f32_e32 v109, v109, v112
	v_mul_f32_e32 v112, 0x4038aa3b, v107
	v_exp_f32_e32 v112, v112
	v_lshlrev_b32_e32 v119, 16, v113
	v_and_b32_e32 v113, 0xffff0000, v113
	v_lshlrev_b32_e32 v120, 16, v114
	v_sub_f32_e32 v112, 1.0, v112
	v_sqrt_f32_e32 v112, v112
	v_mul_f32_e32 v108, v108, v118
	v_mul_f32_e32 v118, 0x4038aa3b, v106
	v_exp_f32_e32 v118, v118
	v_mul_f32_e32 v111, v111, v112
	v_mul_f32_e32 v112, v96, v128
	v_mul_f32_e32 v96, 0x4038aa3b, v112
	v_exp_f32_e32 v96, v96
	v_mul_f32_e32 v111, v111, v113
	v_sub_f32_e32 v118, 1.0, v118
	v_sqrt_f32_e32 v118, v118
	v_sub_f32_e32 v96, 1.0, v96
	v_sqrt_f32_e32 v96, v96
	v_and_b32_e32 v114, 0xffff0000, v114
	v_lshlrev_b32_e32 v121, 16, v115
	v_and_b32_e32 v115, 0xffff0000, v115
	v_mul_f32_e32 v96, v100, v96
	v_add_f32_e32 v100, 1.0, v101
	v_mul_f32_e32 v101, v97, v129
	v_mul_f32_e32 v97, 0x4038aa3b, v101
	v_exp_f32_e32 v97, v97
	v_rcp_f32_e32 v100, v100
	v_mul_f32_e32 v113, v96, v120
	v_mul_f32_e32 v110, v110, v118
	v_sub_f32_e32 v97, 1.0, v97
	v_sqrt_f32_e32 v97, v97
	v_mul_f32_e32 v110, v110, v119
	v_mul_f32_e32 v89, v89, v174
	v_exp_f32_e32 v93, v93
	v_mul_f32_e32 v96, v100, v97
	v_mul_f32_e32 v100, v98, v165
	v_fmamk_f32 v98, v99, 0xbfb8aa3b, v153
	v_exp_f32_e32 v98, v98
	v_add_f32_e32 v97, 1.0, v102
	v_mul_f32_e32 v99, 0x4038aa3b, v100
	v_fmamk_f32 v102, v103, 0xbfb8aa3b, v155
	v_add_f32_e32 v98, 1.0, v98
	v_rcp_f32_e32 v98, v98
	v_exp_f32_e32 v99, v99
	v_exp_f32_e32 v102, v102
	v_rcp_f32_e32 v97, v97
	v_mul_f32_e32 v103, v98, v130
	v_mul_f32_e32 v98, 0x4038aa3b, v103
	v_exp_f32_e32 v98, v98
	v_sub_f32_e32 v99, 1.0, v99
	v_sqrt_f32_e32 v99, v99
	v_add_f32_e32 v102, 1.0, v102
	v_sub_f32_e32 v98, 1.0, v98
	v_rcp_f32_e32 v102, v102
	v_sqrt_f32_e32 v98, v98
	v_mul_f32_e32 v114, v96, v114
	v_mul_f32_e32 v96, v97, v99
	v_mul_f32_e32 v118, v96, v121
	v_mul_f32_e32 v96, v102, v98
	v_mul_f32_e32 v102, v96, v115
	v_cvt_pk_bf16_f32 v96, v104, v105
	v_cvt_pk_bf16_f32 v97, v106, v107
	v_cvt_pk_bf16_f32 v98, v112, v101
	v_cvt_pk_bf16_f32 v99, v100, v103
	v_lshl_add_u64 v[100:101], s[26:27], 0, v[116:117]
	global_store_dwordx4 v[100:101], v[96:99], off
	v_lshl_add_u64 v[100:101], s[28:29], 0, v[116:117]
	v_mul_f32_e32 v106, 0x4038aa3b, v88
	v_cvt_pk_bf16_f32 v96, v108, v109
	v_cvt_pk_bf16_f32 v97, v110, v111
	v_cvt_pk_bf16_f32 v98, v113, v114
	v_cvt_pk_bf16_f32 v99, v118, v102
	global_store_dwordx4 v[100:101], v[96:99], off
	v_exp_f32_e32 v106, v106
	v_exp_f32_e32 v91, v91
	v_or_b32_e32 v96, 32, v164
	v_ashrrev_i32_e32 v97, 31, v96
	v_lshlrev_b64 v[96:97], 11, v[96:97]
	v_lshl_add_u64 v[96:97], v[96:97], 0, v[162:163]
	v_lshlrev_b64 v[100:101], 1, v[96:97]
	v_lshl_add_u64 v[96:97], s[20:21], 0, v[100:101]
	s_nop 1
	v_mov_b32_e32 v96, v216
	v_mov_b32_e32 v97, v217
	v_mov_b32_e32 v98, v218
	v_mov_b32_e32 v99, v219
	v_sub_f32_e32 v106, 1.0, v106
	v_sqrt_f32_e32 v106, v106
	v_add_f32_e32 v93, 1.0, v93
	v_add_f32_e32 v91, 1.0, v91
	v_rcp_f32_e32 v93, v93
	v_mul_f32_e32 v92, v92, v106
	v_mul_f32_e32 v106, 0x4038aa3b, v89
	v_exp_f32_e32 v106, v106
	v_rcp_f32_e32 v91, v91
	v_fmamk_f32 v95, v95, 0xbfb8aa3b, v145
	v_fmamk_f32 v80, v80, 0xbfb8aa3b, v156
	v_sub_f32_e32 v106, 1.0, v106
	v_sqrt_f32_e32 v106, v106
	v_mul_f32_e32 v91, v91, v173
	v_exp_f32_e32 v95, v95
	v_exp_f32_e32 v80, v80
	v_mul_f32_e32 v93, v93, v106
	v_fmamk_f32 v84, v84, 0xbfb8aa3b, v158
	v_add_f32_e32 v95, 1.0, v95
	v_add_f32_e32 v80, 1.0, v80
	v_rcp_f32_e32 v95, v95
	v_rcp_f32_e32 v80, v80
	v_fmamk_f32 v81, v81, 0xbfb8aa3b, v157
	v_exp_f32_e32 v84, v84
	v_exp_f32_e32 v81, v81
	v_fmamk_f32 v85, v85, 0xbfb8aa3b, v159
	v_exp_f32_e32 v85, v85
	v_add_f32_e32 v84, 1.0, v84
	v_add_f32_e32 v81, 1.0, v81
	v_rcp_f32_e32 v84, v84
	v_rcp_f32_e32 v81, v81
	v_fmamk_f32 v82, v82, 0xbfb8aa3b, v152
	v_exp_f32_e32 v82, v82
	v_fmamk_f32 v90, v90, 0xbfb8aa3b, v146
	v_exp_f32_e32 v90, v90
	v_fmamk_f32 v86, v86, 0xbfb8aa3b, v154
	v_add_f32_e32 v82, 1.0, v82
	v_rcp_f32_e32 v82, v82
	v_add_f32_e32 v90, 1.0, v90
	v_rcp_f32_e32 v90, v90
	v_exp_f32_e32 v86, v86
	v_fmamk_f32 v94, v94, 0xbfb8aa3b, v144
	v_exp_f32_e32 v94, v94
	v_mul_f32_e32 v90, v90, v172
	v_fmamk_f32 v72, v72, 0xbfb8aa3b, v150
	v_exp_f32_e32 v72, v72
	v_add_f32_e32 v94, 1.0, v94
	v_rcp_f32_e32 v94, v94
	v_fmamk_f32 v73, v73, 0xbfb8aa3b, v151
	v_add_f32_e32 v72, 1.0, v72
	v_rcp_f32_e32 v72, v72
	v_fmamk_f32 v76, v76, 0xbfb8aa3b, v148
	v_exp_f32_e32 v73, v73
	v_exp_f32_e32 v76, v76
	v_mul_f32_e32 v72, v72, v175
	v_fmamk_f32 v77, v77, 0xbfb8aa3b, v149
	v_add_f32_e32 v73, 1.0, v73
	v_add_f32_e32 v76, 1.0, v76
	v_rcp_f32_e32 v73, v73
	v_rcp_f32_e32 v76, v76
	v_fmamk_f32 v75, v75, 0xbfb8aa3b, v147
	v_exp_f32_e32 v77, v77
	v_mul_f32_e32 v73, v73, v174
	v_exp_f32_e32 v75, v75
	v_fmamk_f32 v79, v79, 0xbfb8aa3b, v145
	v_add_f32_e32 v77, 1.0, v77
	v_rcp_f32_e32 v77, v77
	v_add_f32_e32 v75, 1.0, v75
	v_rcp_f32_e32 v75, v75
	v_fmamk_f32 v64, v64, 0xbfb8aa3b, v156
	v_exp_f32_e32 v79, v79
	v_exp_f32_e32 v64, v64
	v_mul_f32_e32 v75, v75, v173
	v_fmamk_f32 v68, v68, 0xbfb8aa3b, v158
	v_add_f32_e32 v79, 1.0, v79
	v_add_f32_e32 v64, 1.0, v64
	v_rcp_f32_e32 v79, v79
	v_rcp_f32_e32 v64, v64
	v_fmamk_f32 v65, v65, 0xbfb8aa3b, v157
	v_lshlrev_b32_e32 v102, 16, v96
	v_and_b32_e32 v96, 0xffff0000, v96
	v_mul_f32_e32 v93, v93, v96
	v_mul_f32_e32 v96, 0x4038aa3b, v91
	v_exp_f32_e32 v96, v96
	v_lshlrev_b32_e32 v103, 16, v97
	v_and_b32_e32 v97, 0xffff0000, v97
	v_lshlrev_b32_e32 v104, 16, v98
	v_sub_f32_e32 v96, 1.0, v96
	v_sqrt_f32_e32 v96, v96
	v_mul_f32_e32 v92, v92, v102
; __device__ __forceinline__ unsigned cvt_pk_bf16(float lo, float hi) { unsigned r; asm volatile("v_cvt_pk_bf16_f32 %0, %1, %2" : "=v"(r) : "v"(lo), "v"(hi)); return r; }
; __device__ __forceinline__ float bf_lo(unsigned w) { return __uint_as_float(w << 16); }
; __device__ __forceinline__ float bf_hi(unsigned w) { return __uint_as_float(w & 0xffff0000u); }
;     __device__ __forceinline__ void operator()(const f32x4 (&acc)[2][2][4][2], const Unit& u, int wr, int wc, int fr, int fq) const {
;     ...
;             for (int m = 0; m < 4; ++m) { const size_t rowoff = (size_t)(row0 + ai * HALF + m * 16) * 2048 + chg;
;                 const u32x4 xw = *(const u32x4*)(XC + rowoff);
;                 const float xc[8] = {bf_lo(xw.x), bf_hi(xw.x), bf_lo(xw.y), bf_hi(xw.y), bf_lo(xw.z), bf_hi(xw.z), bf_lo(xw.w), bf_hi(xw.w)}; float la[8], uu[8];
; #pragma unroll
;                 for (int n = 0; n < 2; ++n)
; #pragma unroll
;                     for (int j = 0; j < 4; ++j) { const float r = __builtin_amdgcn_rcpf(1.0f + __builtin_amdgcn_exp2f(__builtin_fmaf(acc[ai][0][m][n][j], NL2E, br[n][j])));
;                         const float ig = __builtin_amdgcn_rcpf(1.0f + __builtin_amdgcn_exp2f(__builtin_fmaf(acc[ai][1][m][n][j], NL2E, bi[n][j])));
;                         const float l = r * ls[n][j]; la[4 * n + j] = l;
;                         uu[4 * n + j] = __builtin_amdgcn_sqrtf(1.0f - __builtin_amdgcn_exp2f(l * 2.8853900817779268f)) * ig * xc[4 * n + j]; }
;                 u32x4 w; w.x = cvt_pk_bf16(la[0], la[1]); w.y = cvt_pk_bf16(la[2], la[3]); w.z = cvt_pk_bf16(la[4], la[5]); w.w = cvt_pk_bf16(la[6], la[7]); *(u32x4*)(LA + rowoff) = w;
;                 w.x = cvt_pk_bf16(uu[0], uu[1]); w.y = cvt_pk_bf16(uu[2], uu[3]); w.z = cvt_pk_bf16(uu[4], uu[5]); w.w = cvt_pk_bf16(uu[6], uu[7]); *(u32x4*)(U + rowoff) = w;
	v_mul_f32_e32 v102, 0x4038aa3b, v90
	v_exp_f32_e32 v102, v102
	v_mul_f32_e32 v95, v95, v96
	v_mul_f32_e32 v96, v80, v128
	v_mul_f32_e32 v80, 0x4038aa3b, v96
	v_exp_f32_e32 v80, v80
	v_mul_f32_e32 v95, v95, v97
	v_sub_f32_e32 v102, 1.0, v102
	v_sqrt_f32_e32 v102, v102
	v_sub_f32_e32 v80, 1.0, v80
	v_sqrt_f32_e32 v80, v80
	v_and_b32_e32 v98, 0xffff0000, v98
	v_lshlrev_b32_e32 v105, 16, v99
	v_and_b32_e32 v99, 0xffff0000, v99
	v_mul_f32_e32 v80, v84, v80
	v_add_f32_e32 v84, 1.0, v85
	v_mul_f32_e32 v85, v81, v129
	v_mul_f32_e32 v81, 0x4038aa3b, v85
	v_exp_f32_e32 v81, v81
	v_rcp_f32_e32 v84, v84
	v_mul_f32_e32 v97, v80, v104
	v_mul_f32_e32 v94, v94, v102
	v_sub_f32_e32 v81, 1.0, v81
	v_sqrt_f32_e32 v81, v81
	v_mul_f32_e32 v94, v94, v103
	v_exp_f32_e32 v68, v68
	v_exp_f32_e32 v65, v65
	v_mul_f32_e32 v80, v84, v81
	v_mul_f32_e32 v84, v82, v165
	v_fmamk_f32 v82, v83, 0xbfb8aa3b, v153
	v_exp_f32_e32 v82, v82
	v_add_f32_e32 v81, 1.0, v86
	v_mul_f32_e32 v83, 0x4038aa3b, v84
	v_fmamk_f32 v86, v87, 0xbfb8aa3b, v155
	v_add_f32_e32 v82, 1.0, v82
	v_rcp_f32_e32 v82, v82
	v_exp_f32_e32 v83, v83
	v_exp_f32_e32 v86, v86
	v_rcp_f32_e32 v81, v81
	v_mul_f32_e32 v87, v82, v130
	v_mul_f32_e32 v82, 0x4038aa3b, v87
	v_exp_f32_e32 v82, v82
	v_sub_f32_e32 v83, 1.0, v83
	v_sqrt_f32_e32 v83, v83
	v_add_f32_e32 v86, 1.0, v86
	v_sub_f32_e32 v82, 1.0, v82
	v_rcp_f32_e32 v86, v86
	v_sqrt_f32_e32 v82, v82
	v_mul_f32_e32 v98, v80, v98
	v_mul_f32_e32 v80, v81, v83
	v_mul_f32_e32 v102, v80, v105
	v_mul_f32_e32 v80, v86, v82
	v_mul_f32_e32 v86, v80, v99
	v_cvt_pk_bf16_f32 v80, v88, v89
	v_cvt_pk_bf16_f32 v81, v90, v91
	v_cvt_pk_bf16_f32 v82, v96, v85
	v_cvt_pk_bf16_f32 v83, v84, v87
	v_lshl_add_u64 v[84:85], s[26:27], 0, v[100:101]
	global_store_dwordx4 v[84:85], v[80:83], off
	v_lshl_add_u64 v[84:85], s[28:29], 0, v[100:101]
	v_mul_f32_e32 v90, 0x4038aa3b, v72
	v_cvt_pk_bf16_f32 v80, v92, v93
	v_cvt_pk_bf16_f32 v81, v94, v95
	v_cvt_pk_bf16_f32 v82, v97, v98
	v_cvt_pk_bf16_f32 v83, v102, v86
	global_store_dwordx4 v[84:85], v[80:83], off
	v_exp_f32_e32 v90, v90
	v_add_f32_e32 v68, 1.0, v68
	v_or_b32_e32 v80, 48, v164
	v_ashrrev_i32_e32 v81, 31, v80
	v_lshlrev_b64 v[80:81], 11, v[80:81]
	v_lshl_add_u64 v[80:81], v[80:81], 0, v[162:163]
	v_lshlrev_b64 v[84:85], 1, v[80:81]
	v_lshl_add_u64 v[80:81], s[20:21], 0, v[84:85]
	s_nop 1
	v_mov_b32_e32 v80, v220
	v_mov_b32_e32 v81, v221
	v_mov_b32_e32 v82, v222
	v_mov_b32_e32 v83, v223
	v_sub_f32_e32 v90, 1.0, v90
	v_sqrt_f32_e32 v90, v90
	v_add_f32_e32 v65, 1.0, v65
	v_fmamk_f32 v69, v69, 0xbfb8aa3b, v159
	v_rcp_f32_e32 v68, v68
	v_mul_f32_e32 v76, v76, v90
	v_mul_f32_e32 v90, 0x4038aa3b, v73
	v_exp_f32_e32 v90, v90
	v_exp_f32_e32 v69, v69
	v_rcp_f32_e32 v65, v65
	v_fmamk_f32 v66, v66, 0xbfb8aa3b, v152
	v_sub_f32_e32 v90, 1.0, v90
	v_sqrt_f32_e32 v90, v90
	v_exp_f32_e32 v66, v66
	v_fmamk_f32 v74, v74, 0xbfb8aa3b, v146
	v_exp_f32_e32 v74, v74
	v_mul_f32_e32 v77, v77, v90
	v_add_f32_e32 v66, 1.0, v66
	v_rcp_f32_e32 v66, v66
	v_add_f32_e32 v74, 1.0, v74
	v_fmamk_f32 v70, v70, 0xbfb8aa3b, v154
	v_rcp_f32_e32 v74, v74
	v_exp_f32_e32 v70, v70
	v_fmamk_f32 v78, v78, 0xbfb8aa3b, v144
	v_exp_f32_e32 v78, v78
	v_mul_f32_e32 v74, v74, v172
	v_fmamk_f32 v56, v56, 0xbfb8aa3b, v150
	v_exp_f32_e32 v56, v56
	v_add_f32_e32 v78, 1.0, v78
	v_rcp_f32_e32 v78, v78
	v_fmamk_f32 v57, v57, 0xbfb8aa3b, v151
	v_add_f32_e32 v56, 1.0, v56
	v_rcp_f32_e32 v56, v56
	v_fmamk_f32 v60, v60, 0xbfb8aa3b, v148
	v_exp_f32_e32 v57, v57
	v_exp_f32_e32 v60, v60
	v_mul_f32_e32 v56, v56, v175
	v_fmamk_f32 v61, v61, 0xbfb8aa3b, v149
	v_add_f32_e32 v57, 1.0, v57
	v_add_f32_e32 v60, 1.0, v60
	v_rcp_f32_e32 v57, v57
	v_rcp_f32_e32 v60, v60
	v_fmamk_f32 v59, v59, 0xbfb8aa3b, v147
	v_exp_f32_e32 v61, v61
	v_mul_f32_e32 v57, v57, v174
	v_exp_f32_e32 v59, v59
	v_fmamk_f32 v63, v63, 0xbfb8aa3b, v145
	v_add_f32_e32 v61, 1.0, v61
	v_rcp_f32_e32 v61, v61
	v_add_f32_e32 v59, 1.0, v59
	v_rcp_f32_e32 v59, v59
	v_fmamk_f32 v48, v48, 0xbfb8aa3b, v156
	v_exp_f32_e32 v63, v63
	v_exp_f32_e32 v48, v48
	v_mul_f32_e32 v59, v59, v173
	v_fmamk_f32 v52, v52, 0xbfb8aa3b, v158
	v_add_f32_e32 v63, 1.0, v63
	v_add_f32_e32 v48, 1.0, v48
	v_rcp_f32_e32 v63, v63
	v_rcp_f32_e32 v48, v48
	v_fmamk_f32 v49, v49, 0xbfb8aa3b, v157
	v_exp_f32_e32 v52, v52
	v_exp_f32_e32 v49, v49
	v_fmamk_f32 v53, v53, 0xbfb8aa3b, v159
	v_exp_f32_e32 v53, v53
	v_add_f32_e32 v52, 1.0, v52
	v_add_f32_e32 v49, 1.0, v49
	v_rcp_f32_e32 v52, v52
	v_rcp_f32_e32 v49, v49
	v_fmamk_f32 v50, v50, 0xbfb8aa3b, v152
	v_exp_f32_e32 v50, v50
	v_fmamk_f32 v58, v58, 0xbfb8aa3b, v146
	v_exp_f32_e32 v58, v58
	v_fmamk_f32 v54, v54, 0xbfb8aa3b, v154
	v_add_f32_e32 v50, 1.0, v50
	v_rcp_f32_e32 v50, v50
	v_add_f32_e32 v58, 1.0, v58
	v_rcp_f32_e32 v58, v58
	v_exp_f32_e32 v54, v54
	v_lshlrev_b32_e32 v86, 16, v80
	v_and_b32_e32 v80, 0xffff0000, v80
	v_mul_f32_e32 v77, v77, v80
	v_mul_f32_e32 v80, 0x4038aa3b, v75
	v_exp_f32_e32 v80, v80
	v_lshlrev_b32_e32 v87, 16, v81
	v_and_b32_e32 v81, 0xffff0000, v81
	v_lshlrev_b32_e32 v88, 16, v82
	v_sub_f32_e32 v80, 1.0, v80
	v_sqrt_f32_e32 v80, v80
	v_mul_f32_e32 v76, v76, v86
	v_mul_f32_e32 v86, 0x4038aa3b, v74
	v_exp_f32_e32 v86, v86
	v_mul_f32_e32 v79, v79, v80
	v_mul_f32_e32 v80, v64, v128
	v_mul_f32_e32 v64, 0x4038aa3b, v80
	v_exp_f32_e32 v64, v64
	v_mul_f32_e32 v79, v79, v81
	v_sub_f32_e32 v86, 1.0, v86
	v_sqrt_f32_e32 v86, v86
	v_sub_f32_e32 v64, 1.0, v64
	v_sqrt_f32_e32 v64, v64
	v_and_b32_e32 v82, 0xffff0000, v82
	v_lshlrev_b32_e32 v89, 16, v83
	v_and_b32_e32 v83, 0xffff0000, v83
	v_mul_f32_e32 v64, v68, v64
	v_add_f32_e32 v68, 1.0, v69
	v_mul_f32_e32 v69, v65, v129
	v_mul_f32_e32 v65, 0x4038aa3b, v69
; __device__ __forceinline__ unsigned cvt_pk_bf16(float lo, float hi) { unsigned r; asm volatile("v_cvt_pk_bf16_f32 %0, %1, %2" : "=v"(r) : "v"(lo), "v"(hi)); return r; }
; __device__ __forceinline__ float bf_lo(unsigned w) { return __uint_as_float(w << 16); }
; __device__ __forceinline__ float bf_hi(unsigned w) { return __uint_as_float(w & 0xffff0000u); }
;     __device__ __forceinline__ void operator()(const f32x4 (&acc)[2][2][4][2], const Unit& u, int wr, int wc, int fr, int fq) const {
;     ...
;             for (int m = 0; m < 4; ++m) { const size_t rowoff = (size_t)(row0 + ai * HALF + m * 16) * 2048 + chg;
;                 const u32x4 xw = *(const u32x4*)(XC + rowoff);
;                 const float xc[8] = {bf_lo(xw.x), bf_hi(xw.x), bf_lo(xw.y), bf_hi(xw.y), bf_lo(xw.z), bf_hi(xw.z), bf_lo(xw.w), bf_hi(xw.w)}; float la[8], uu[8];
; #pragma unroll
;                 for (int n = 0; n < 2; ++n)
; #pragma unroll
;                     for (int j = 0; j < 4; ++j) { const float r = __builtin_amdgcn_rcpf(1.0f + __builtin_amdgcn_exp2f(__builtin_fmaf(acc[ai][0][m][n][j], NL2E, br[n][j])));
;                         const float ig = __builtin_amdgcn_rcpf(1.0f + __builtin_amdgcn_exp2f(__builtin_fmaf(acc[ai][1][m][n][j], NL2E, bi[n][j])));
;                         const float l = r * ls[n][j]; la[4 * n + j] = l;
;                         uu[4 * n + j] = __builtin_amdgcn_sqrtf(1.0f - __builtin_amdgcn_exp2f(l * 2.8853900817779268f)) * ig * xc[4 * n + j]; }
;                 u32x4 w; w.x = cvt_pk_bf16(la[0], la[1]); w.y = cvt_pk_bf16(la[2], la[3]); w.z = cvt_pk_bf16(la[4], la[5]); w.w = cvt_pk_bf16(la[6], la[7]); *(u32x4*)(LA + rowoff) = w;
;                 w.x = cvt_pk_bf16(uu[0], uu[1]); w.y = cvt_pk_bf16(uu[2], uu[3]); w.z = cvt_pk_bf16(uu[4], uu[5]); w.w = cvt_pk_bf16(uu[6], uu[7]); *(u32x4*)(U + rowoff) = w;
	v_exp_f32_e32 v65, v65
	v_rcp_f32_e32 v68, v68
	v_mul_f32_e32 v81, v64, v88
	v_mul_f32_e32 v78, v78, v86
	v_sub_f32_e32 v65, 1.0, v65
	v_sqrt_f32_e32 v65, v65
	v_mul_f32_e32 v78, v78, v87
	v_mul_f32_e32 v58, v58, v172
	v_fmamk_f32 v62, v62, 0xbfb8aa3b, v144
	v_mul_f32_e32 v64, v68, v65
	v_mul_f32_e32 v68, v66, v165
	v_fmamk_f32 v66, v67, 0xbfb8aa3b, v153
	v_exp_f32_e32 v66, v66
	v_add_f32_e32 v65, 1.0, v70
	v_mul_f32_e32 v67, 0x4038aa3b, v68
	v_fmamk_f32 v70, v71, 0xbfb8aa3b, v155
	v_add_f32_e32 v66, 1.0, v66
	v_rcp_f32_e32 v66, v66
	v_exp_f32_e32 v67, v67
	v_exp_f32_e32 v70, v70
	v_rcp_f32_e32 v65, v65
	v_mul_f32_e32 v71, v66, v130
	v_mul_f32_e32 v66, 0x4038aa3b, v71
	v_exp_f32_e32 v66, v66
	v_sub_f32_e32 v67, 1.0, v67
	v_sqrt_f32_e32 v67, v67
	v_add_f32_e32 v70, 1.0, v70
	v_sub_f32_e32 v66, 1.0, v66
	v_rcp_f32_e32 v70, v70
	v_sqrt_f32_e32 v66, v66
	v_mul_f32_e32 v82, v64, v82
	v_mul_f32_e32 v64, v65, v67
	v_mul_f32_e32 v86, v64, v89
	v_mul_f32_e32 v64, v70, v66
	v_mul_f32_e32 v70, v64, v83
	v_cvt_pk_bf16_f32 v64, v72, v73
	v_cvt_pk_bf16_f32 v65, v74, v75
	v_cvt_pk_bf16_f32 v66, v80, v69
	v_cvt_pk_bf16_f32 v67, v68, v71
	v_lshl_add_u64 v[68:69], s[26:27], 0, v[84:85]
	global_store_dwordx4 v[68:69], v[64:67], off
	v_lshl_add_u64 v[68:69], s[28:29], 0, v[84:85]
	v_mul_f32_e32 v74, 0x4038aa3b, v56
	v_cvt_pk_bf16_f32 v64, v76, v77
	v_cvt_pk_bf16_f32 v65, v78, v79
	v_cvt_pk_bf16_f32 v66, v81, v82
	v_cvt_pk_bf16_f32 v67, v86, v70
	global_store_dwordx4 v[68:69], v[64:67], off
	v_lshl_add_u64 v[68:69], v[160:161], 0, s[22:23]
	v_exp_f32_e32 v74, v74
	v_lshl_add_u64 v[64:65], s[20:21], 0, v[68:69]
	s_nop 1
	v_mov_b32_e32 v64, v224
	v_mov_b32_e32 v65, v225
	v_mov_b32_e32 v66, v226
	v_mov_b32_e32 v67, v227
	v_exp_f32_e32 v62, v62
	v_sub_f32_e32 v74, 1.0, v74
	v_sqrt_f32_e32 v74, v74
	v_fmamk_f32 v40, v40, 0xbfb8aa3b, v150
	v_add_f32_e32 v62, 1.0, v62
	v_rcp_f32_e32 v62, v62
	v_mul_f32_e32 v60, v60, v74
	v_mul_f32_e32 v74, 0x4038aa3b, v57
	v_exp_f32_e32 v74, v74
	v_exp_f32_e32 v40, v40
	v_fmamk_f32 v41, v41, 0xbfb8aa3b, v151
	v_fmamk_f32 v44, v44, 0xbfb8aa3b, v148
	v_sub_f32_e32 v74, 1.0, v74
	v_sqrt_f32_e32 v74, v74
	v_add_f32_e32 v40, 1.0, v40
	v_rcp_f32_e32 v40, v40
	v_exp_f32_e32 v41, v41
	v_mul_f32_e32 v61, v61, v74
	v_exp_f32_e32 v44, v44
	v_mul_f32_e32 v40, v40, v175
	v_add_f32_e32 v41, 1.0, v41
	v_rcp_f32_e32 v41, v41
	v_add_f32_e32 v44, 1.0, v44
	v_rcp_f32_e32 v44, v44
	v_fmamk_f32 v45, v45, 0xbfb8aa3b, v149
	v_mul_f32_e32 v41, v41, v174
	v_fmamk_f32 v43, v43, 0xbfb8aa3b, v147
	v_exp_f32_e32 v45, v45
	v_exp_f32_e32 v43, v43
	v_fmamk_f32 v47, v47, 0xbfb8aa3b, v145
	v_fmamk_f32 v32, v32, 0xbfb8aa3b, v156
	v_add_f32_e32 v45, 1.0, v45
	v_add_f32_e32 v43, 1.0, v43
	v_rcp_f32_e32 v45, v45
	v_rcp_f32_e32 v43, v43
	v_exp_f32_e32 v47, v47
	v_exp_f32_e32 v32, v32
	v_fmamk_f32 v36, v36, 0xbfb8aa3b, v158
	v_mul_f32_e32 v43, v43, v173
	v_add_f32_e32 v47, 1.0, v47
	v_add_f32_e32 v32, 1.0, v32
	v_rcp_f32_e32 v47, v47
	v_rcp_f32_e32 v32, v32
	v_fmamk_f32 v33, v33, 0xbfb8aa3b, v157
	v_exp_f32_e32 v36, v36
	v_exp_f32_e32 v33, v33
	v_fmamk_f32 v37, v37, 0xbfb8aa3b, v159
	v_exp_f32_e32 v37, v37
	v_add_f32_e32 v36, 1.0, v36
	v_add_f32_e32 v33, 1.0, v33
	v_rcp_f32_e32 v36, v36
	v_rcp_f32_e32 v33, v33
	v_fmamk_f32 v34, v34, 0xbfb8aa3b, v152
	v_exp_f32_e32 v34, v34
	v_fmamk_f32 v42, v42, 0xbfb8aa3b, v146
	v_exp_f32_e32 v42, v42
	v_fmamk_f32 v38, v38, 0xbfb8aa3b, v154
	v_add_f32_e32 v34, 1.0, v34
	v_rcp_f32_e32 v34, v34
	v_add_f32_e32 v42, 1.0, v42
	v_rcp_f32_e32 v42, v42
	v_exp_f32_e32 v38, v38
	v_fmamk_f32 v46, v46, 0xbfb8aa3b, v144
	v_exp_f32_e32 v46, v46
	v_mul_f32_e32 v42, v42, v172
	v_fmamk_f32 v24, v24, 0xbfb8aa3b, v150
	v_exp_f32_e32 v24, v24
	v_add_f32_e32 v46, 1.0, v46
	v_rcp_f32_e32 v46, v46
	v_fmamk_f32 v25, v25, 0xbfb8aa3b, v151
	v_add_f32_e32 v24, 1.0, v24
	v_rcp_f32_e32 v24, v24
	v_fmamk_f32 v28, v28, 0xbfb8aa3b, v148
	v_exp_f32_e32 v25, v25
	v_exp_f32_e32 v28, v28
	v_mul_f32_e32 v24, v24, v175
	v_fmamk_f32 v29, v29, 0xbfb8aa3b, v149
	v_add_f32_e32 v25, 1.0, v25
	v_add_f32_e32 v28, 1.0, v28
	v_lshlrev_b32_e32 v70, 16, v64
	v_and_b32_e32 v64, 0xffff0000, v64
	v_mul_f32_e32 v61, v61, v64
	v_mul_f32_e32 v64, 0x4038aa3b, v59
	v_exp_f32_e32 v64, v64
	v_lshlrev_b32_e32 v71, 16, v65
	v_and_b32_e32 v65, 0xffff0000, v65
	v_lshlrev_b32_e32 v72, 16, v66
	v_sub_f32_e32 v64, 1.0, v64
	v_sqrt_f32_e32 v64, v64
	v_mul_f32_e32 v60, v60, v70
	v_mul_f32_e32 v70, 0x4038aa3b, v58
	v_exp_f32_e32 v70, v70
	v_mul_f32_e32 v63, v63, v64
	v_mul_f32_e32 v64, v48, v128
	v_mul_f32_e32 v48, 0x4038aa3b, v64
	v_exp_f32_e32 v48, v48
	v_mul_f32_e32 v63, v63, v65
	v_sub_f32_e32 v70, 1.0, v70
	v_sqrt_f32_e32 v70, v70
	v_sub_f32_e32 v48, 1.0, v48
	v_sqrt_f32_e32 v48, v48
	v_and_b32_e32 v66, 0xffff0000, v66
	v_lshlrev_b32_e32 v73, 16, v67
	v_and_b32_e32 v67, 0xffff0000, v67
	v_mul_f32_e32 v48, v52, v48
	v_add_f32_e32 v52, 1.0, v53
	v_mul_f32_e32 v53, v49, v129
	v_mul_f32_e32 v49, 0x4038aa3b, v53
	v_exp_f32_e32 v49, v49
	v_rcp_f32_e32 v52, v52
	v_mul_f32_e32 v65, v48, v72
	v_mul_f32_e32 v62, v62, v70
	v_sub_f32_e32 v49, 1.0, v49
	v_sqrt_f32_e32 v49, v49
	v_mul_f32_e32 v62, v62, v71
	v_rcp_f32_e32 v25, v25
	v_rcp_f32_e32 v28, v28
	v_mul_f32_e32 v48, v52, v49
	v_mul_f32_e32 v52, v50, v165
	v_fmamk_f32 v50, v51, 0xbfb8aa3b, v153
	v_exp_f32_e32 v50, v50
	v_add_f32_e32 v49, 1.0, v54
	v_mul_f32_e32 v51, 0x4038aa3b, v52
	v_fmamk_f32 v54, v55, 0xbfb8aa3b, v155
	v_add_f32_e32 v50, 1.0, v50
	v_rcp_f32_e32 v50, v50
	v_exp_f32_e32 v51, v51
	v_exp_f32_e32 v54, v54
	v_rcp_f32_e32 v49, v49
	v_mul_f32_e32 v55, v50, v130
	v_mul_f32_e32 v50, 0x4038aa3b, v55
	v_exp_f32_e32 v50, v50
	v_sub_f32_e32 v51, 1.0, v51
; __device__ __forceinline__ unsigned cvt_pk_bf16(float lo, float hi) { unsigned r; asm volatile("v_cvt_pk_bf16_f32 %0, %1, %2" : "=v"(r) : "v"(lo), "v"(hi)); return r; }
; __device__ __forceinline__ float bf_lo(unsigned w) { return __uint_as_float(w << 16); }
; __device__ __forceinline__ float bf_hi(unsigned w) { return __uint_as_float(w & 0xffff0000u); }
;     __device__ __forceinline__ void operator()(const f32x4 (&acc)[2][2][4][2], const Unit& u, int wr, int wc, int fr, int fq) const {
;     ...
;             for (int m = 0; m < 4; ++m) { const size_t rowoff = (size_t)(row0 + ai * HALF + m * 16) * 2048 + chg;
;                 const u32x4 xw = *(const u32x4*)(XC + rowoff);
;                 const float xc[8] = {bf_lo(xw.x), bf_hi(xw.x), bf_lo(xw.y), bf_hi(xw.y), bf_lo(xw.z), bf_hi(xw.z), bf_lo(xw.w), bf_hi(xw.w)}; float la[8], uu[8];
; #pragma unroll
;                 for (int n = 0; n < 2; ++n)
; #pragma unroll
;                     for (int j = 0; j < 4; ++j) { const float r = __builtin_amdgcn_rcpf(1.0f + __builtin_amdgcn_exp2f(__builtin_fmaf(acc[ai][0][m][n][j], NL2E, br[n][j])));
;                         const float ig = __builtin_amdgcn_rcpf(1.0f + __builtin_amdgcn_exp2f(__builtin_fmaf(acc[ai][1][m][n][j], NL2E, bi[n][j])));
;                         const float l = r * ls[n][j]; la[4 * n + j] = l;
;                         uu[4 * n + j] = __builtin_amdgcn_sqrtf(1.0f - __builtin_amdgcn_exp2f(l * 2.8853900817779268f)) * ig * xc[4 * n + j]; }
;                 u32x4 w; w.x = cvt_pk_bf16(la[0], la[1]); w.y = cvt_pk_bf16(la[2], la[3]); w.z = cvt_pk_bf16(la[4], la[5]); w.w = cvt_pk_bf16(la[6], la[7]); *(u32x4*)(LA + rowoff) = w;
;                 w.x = cvt_pk_bf16(uu[0], uu[1]); w.y = cvt_pk_bf16(uu[2], uu[3]); w.z = cvt_pk_bf16(uu[4], uu[5]); w.w = cvt_pk_bf16(uu[6], uu[7]); *(u32x4*)(U + rowoff) = w;
	v_sqrt_f32_e32 v51, v51
	v_add_f32_e32 v54, 1.0, v54
	v_sub_f32_e32 v50, 1.0, v50
	v_rcp_f32_e32 v54, v54
	v_sqrt_f32_e32 v50, v50
	v_mul_f32_e32 v66, v48, v66
	v_mul_f32_e32 v48, v49, v51
	v_mul_f32_e32 v70, v48, v73
	v_mul_f32_e32 v48, v54, v50
	v_mul_f32_e32 v54, v48, v67
	v_cvt_pk_bf16_f32 v48, v56, v57
	v_cvt_pk_bf16_f32 v49, v58, v59
	v_cvt_pk_bf16_f32 v50, v64, v53
	v_cvt_pk_bf16_f32 v51, v52, v55
	v_lshl_add_u64 v[52:53], s[26:27], 0, v[68:69]
	global_store_dwordx4 v[52:53], v[48:51], off
	v_lshl_add_u64 v[52:53], s[28:29], 0, v[68:69]
	v_mul_f32_e32 v58, 0x4038aa3b, v40
	v_cvt_pk_bf16_f32 v48, v60, v61
	v_cvt_pk_bf16_f32 v49, v62, v63
	v_cvt_pk_bf16_f32 v50, v65, v66
	v_cvt_pk_bf16_f32 v51, v70, v54
	global_store_dwordx4 v[52:53], v[48:51], off
	v_lshl_add_u64 v[52:53], v[160:161], 0, s[54:55]
	v_exp_f32_e32 v58, v58
	v_lshl_add_u64 v[48:49], s[20:21], 0, v[52:53]
	s_nop 1
	v_mov_b32_e32 v48, v228
	v_mov_b32_e32 v49, v229
	v_mov_b32_e32 v50, v230
	v_mov_b32_e32 v51, v231
	v_mul_f32_e32 v25, v25, v174
	v_sub_f32_e32 v58, 1.0, v58
	v_sqrt_f32_e32 v58, v58
	v_fmamk_f32 v27, v27, 0xbfb8aa3b, v147
	v_exp_f32_e32 v29, v29
	v_exp_f32_e32 v27, v27
	v_mul_f32_e32 v44, v44, v58
	v_mul_f32_e32 v58, 0x4038aa3b, v41
	v_exp_f32_e32 v58, v58
	v_add_f32_e32 v29, 1.0, v29
	v_add_f32_e32 v27, 1.0, v27
	v_rcp_f32_e32 v29, v29
	v_sub_f32_e32 v58, 1.0, v58
	v_sqrt_f32_e32 v58, v58
	v_rcp_f32_e32 v27, v27
	v_fmamk_f32 v31, v31, 0xbfb8aa3b, v145
	v_fmamk_f32 v16, v16, 0xbfb8aa3b, v156
	v_mul_f32_e32 v45, v45, v58
	v_mul_f32_e32 v27, v27, v173
	v_exp_f32_e32 v31, v31
	v_exp_f32_e32 v16, v16
	v_fmamk_f32 v20, v20, 0xbfb8aa3b, v158
	v_fmamk_f32 v17, v17, 0xbfb8aa3b, v157
	v_add_f32_e32 v31, 1.0, v31
	v_add_f32_e32 v16, 1.0, v16
	v_rcp_f32_e32 v31, v31
	v_rcp_f32_e32 v16, v16
	v_exp_f32_e32 v20, v20
	v_exp_f32_e32 v17, v17
	v_fmamk_f32 v21, v21, 0xbfb8aa3b, v159
	v_exp_f32_e32 v21, v21
	v_add_f32_e32 v20, 1.0, v20
	v_add_f32_e32 v17, 1.0, v17
	v_rcp_f32_e32 v20, v20
	v_rcp_f32_e32 v17, v17
	v_fmamk_f32 v18, v18, 0xbfb8aa3b, v152
	v_exp_f32_e32 v18, v18
	v_fmamk_f32 v26, v26, 0xbfb8aa3b, v146
	v_exp_f32_e32 v26, v26
	v_fmamk_f32 v22, v22, 0xbfb8aa3b, v154
	v_add_f32_e32 v18, 1.0, v18
	v_rcp_f32_e32 v18, v18
	v_add_f32_e32 v26, 1.0, v26
	v_rcp_f32_e32 v26, v26
	v_exp_f32_e32 v22, v22
	v_fmamk_f32 v30, v30, 0xbfb8aa3b, v144
	v_exp_f32_e32 v30, v30
	v_mul_f32_e32 v26, v26, v172
	v_fmamk_f32 v8, v8, 0xbfb8aa3b, v150
	v_exp_f32_e32 v8, v8
	v_add_f32_e32 v30, 1.0, v30
	v_rcp_f32_e32 v30, v30
	v_fmac_f32_e32 v151, 0xbfb8aa3b, v9
	v_add_f32_e32 v8, 1.0, v8
	v_rcp_f32_e32 v8, v8
	v_fmamk_f32 v12, v12, 0xbfb8aa3b, v148
	v_exp_f32_e32 v9, v151
	v_exp_f32_e32 v12, v12
	v_mul_f32_e32 v8, v8, v175
	v_fmac_f32_e32 v149, 0xbfb8aa3b, v13
	v_add_f32_e32 v9, 1.0, v9
	v_add_f32_e32 v12, 1.0, v12
	v_rcp_f32_e32 v9, v9
	v_rcp_f32_e32 v12, v12
	v_fmac_f32_e32 v147, 0xbfb8aa3b, v11
	v_exp_f32_e32 v13, v149
	v_mul_f32_e32 v9, v9, v174
	v_exp_f32_e32 v11, v147
	v_fmac_f32_e32 v145, 0xbfb8aa3b, v15
	v_add_f32_e32 v13, 1.0, v13
	v_rcp_f32_e32 v13, v13
	v_add_f32_e32 v11, 1.0, v11
	v_rcp_f32_e32 v11, v11
	v_fmamk_f32 v0, v0, 0xbfb8aa3b, v156
	v_exp_f32_e32 v15, v145
	v_exp_f32_e32 v0, v0
	v_mul_f32_e32 v11, v11, v173
	v_fmamk_f32 v4, v4, 0xbfb8aa3b, v158
	v_add_f32_e32 v15, 1.0, v15
	v_lshlrev_b32_e32 v54, 16, v48
	v_and_b32_e32 v48, 0xffff0000, v48
	v_mul_f32_e32 v45, v45, v48
	v_mul_f32_e32 v48, 0x4038aa3b, v43
	v_exp_f32_e32 v48, v48
	v_lshlrev_b32_e32 v55, 16, v49
	v_and_b32_e32 v49, 0xffff0000, v49
	v_lshlrev_b32_e32 v56, 16, v50
	v_sub_f32_e32 v48, 1.0, v48
	v_sqrt_f32_e32 v48, v48
	v_mul_f32_e32 v44, v44, v54
	v_mul_f32_e32 v54, 0x4038aa3b, v42
	v_exp_f32_e32 v54, v54
	v_mul_f32_e32 v47, v47, v48
	v_mul_f32_e32 v48, v32, v128
	v_mul_f32_e32 v32, 0x4038aa3b, v48
	v_exp_f32_e32 v32, v32
	v_mul_f32_e32 v47, v47, v49
	v_sub_f32_e32 v54, 1.0, v54
	v_sqrt_f32_e32 v54, v54
	v_sub_f32_e32 v32, 1.0, v32
	v_sqrt_f32_e32 v32, v32
	v_and_b32_e32 v50, 0xffff0000, v50
	v_lshlrev_b32_e32 v57, 16, v51
	v_and_b32_e32 v51, 0xffff0000, v51
	v_mul_f32_e32 v32, v36, v32
	v_add_f32_e32 v36, 1.0, v37
	v_mul_f32_e32 v37, v33, v129
	v_mul_f32_e32 v33, 0x4038aa3b, v37
	v_exp_f32_e32 v33, v33
	v_rcp_f32_e32 v36, v36
	v_mul_f32_e32 v49, v32, v56
	v_mul_f32_e32 v46, v46, v54
	v_sub_f32_e32 v33, 1.0, v33
	v_sqrt_f32_e32 v33, v33
	v_mul_f32_e32 v46, v46, v55
	v_add_f32_e32 v0, 1.0, v0
	v_rcp_f32_e32 v15, v15
	v_mul_f32_e32 v32, v36, v33
	v_mul_f32_e32 v36, v34, v165
	v_fmamk_f32 v34, v35, 0xbfb8aa3b, v153
	v_exp_f32_e32 v34, v34
	v_add_f32_e32 v33, 1.0, v38
	v_mul_f32_e32 v35, 0x4038aa3b, v36
	v_fmamk_f32 v38, v39, 0xbfb8aa3b, v155
	v_add_f32_e32 v34, 1.0, v34
	v_rcp_f32_e32 v34, v34
	v_exp_f32_e32 v35, v35
	v_exp_f32_e32 v38, v38
	v_rcp_f32_e32 v33, v33
	v_mul_f32_e32 v39, v34, v130
	v_mul_f32_e32 v34, 0x4038aa3b, v39
	v_exp_f32_e32 v34, v34
	v_sub_f32_e32 v35, 1.0, v35
	v_sqrt_f32_e32 v35, v35
	v_add_f32_e32 v38, 1.0, v38
	v_sub_f32_e32 v34, 1.0, v34
	v_rcp_f32_e32 v38, v38
	v_sqrt_f32_e32 v34, v34
	v_mul_f32_e32 v50, v32, v50
	v_mul_f32_e32 v32, v33, v35
	v_mul_f32_e32 v54, v32, v57
	v_mul_f32_e32 v32, v38, v34
	v_mul_f32_e32 v38, v32, v51
	v_cvt_pk_bf16_f32 v32, v40, v41
	v_cvt_pk_bf16_f32 v33, v42, v43
	v_cvt_pk_bf16_f32 v34, v48, v37
	v_cvt_pk_bf16_f32 v35, v36, v39
	v_lshl_add_u64 v[36:37], s[26:27], 0, v[52:53]
	global_store_dwordx4 v[36:37], v[32:35], off
	v_lshl_add_u64 v[36:37], s[28:29], 0, v[52:53]
	v_mul_f32_e32 v42, 0x4038aa3b, v24
	v_cvt_pk_bf16_f32 v32, v44, v45
	v_cvt_pk_bf16_f32 v33, v46, v47
	v_cvt_pk_bf16_f32 v34, v49, v50
	v_cvt_pk_bf16_f32 v35, v54, v38
	global_store_dwordx4 v[36:37], v[32:35], off
; template <class Epi, class Sched, bool ALIGN_EPI = false, bool SP2 = false>
; __device__ __forceinline__ void gemm_phase(PG8_LAS unsigned char* lds, const Gemm g, const Sched& S, const Epi& E) {
;     ...
;         if constexpr (ALIGN_EPI) { if (wr == 0) PG8_BAR; }
;         if constexpr (!Epi::AFTER_DRAIN) { int ln_ = __builtin_amdgcn_mbcnt_hi(~0u, __builtin_amdgcn_mbcnt_lo(~0u, 0u)); asm volatile("" : "+v"(ln_)); E(acc, cur, wr, wc, ln_ & 15, ln_ >> 4); S.done(cur); }
;         if (!has_next) break;
; #pragma unroll
;         for (int a = 0; a < 2; ++a)
; #pragma unroll
;             for (int b = 0; b < 2; ++b)
; #pragma unroll
;                 for (int m = 0; m < 4; ++m)
; #pragma unroll
;                     for (int n = 0; n < 2; ++n) acc[a][b][m][n] = (f32x4){0.f, 0.f, 0.f, 0.f};
;         cur = nxt; cA = nA; cB = nB; ++ui;
;     __device__ __forceinline__ void operator()(const f32x4 (&acc)[2][2][4][2], const Unit& u, int wr, int wc, int fr, int fq) const {
;     ...
;             for (int m = 0; m < 4; ++m) { const size_t rowoff = (size_t)(row0 + ai * HALF + m * 16) * 2048 + chg;
;                 const u32x4 xw = *(const u32x4*)(XC + rowoff);
;                 const float xc[8] = {bf_lo(xw.x), bf_hi(xw.x), bf_lo(xw.y), bf_hi(xw.y), bf_lo(xw.z), bf_hi(xw.z), bf_lo(xw.w), bf_hi(xw.w)}; float la[8], uu[8];
; #pragma unroll
;                 for (int n = 0; n < 2; ++n)
; #pragma unroll
;                     for (int j = 0; j < 4; ++j) { const float r = __builtin_amdgcn_rcpf(1.0f + __builtin_amdgcn_exp2f(__builtin_fmaf(acc[ai][0][m][n][j], NL2E, br[n][j])));
;                         const float ig = __builtin_amdgcn_rcpf(1.0f + __builtin_amdgcn_exp2f(__builtin_fmaf(acc[ai][1][m][n][j], NL2E, bi[n][j])));
;                         const float l = r * ls[n][j]; la[4 * n + j] = l;
;                         uu[4 * n + j] = __builtin_amdgcn_sqrtf(1.0f - __builtin_amdgcn_exp2f(l * 2.8853900817779268f)) * ig * xc[4 * n + j]; }
;                 u32x4 w; w.x = cvt_pk_bf16(la[0], la[1]); w.y = cvt_pk_bf16(la[2], la[3]); w.z = cvt_pk_bf16(la[4], la[5]); w.w = cvt_pk_bf16(la[6], la[7]); *(u32x4*)(LA + rowoff) = w;
;                 w.x = cvt_pk_bf16(uu[0], uu[1]); w.y = cvt_pk_bf16(uu[2], uu[3]); w.z = cvt_pk_bf16(uu[4], uu[5]); w.w = cvt_pk_bf16(uu[6], uu[7]); *(u32x4*)(U + rowoff) = w;
;                 asm volatile("" ::: "memory"); }
	v_lshl_add_u64 v[36:37], v[160:161], 0, s[56:57]
	v_exp_f32_e32 v42, v42
	v_lshl_add_u64 v[32:33], s[20:21], 0, v[36:37]
	s_nop 1
	v_mov_b32_e32 v32, v232
	v_mov_b32_e32 v33, v233
	v_mov_b32_e32 v34, v234
	v_mov_b32_e32 v35, v235
	v_rcp_f32_e32 v0, v0
	v_sub_f32_e32 v42, 1.0, v42
	v_sqrt_f32_e32 v42, v42
	v_fmac_f32_e32 v157, 0xbfb8aa3b, v1
	v_exp_f32_e32 v4, v4
	v_exp_f32_e32 v1, v157
	v_mul_f32_e32 v28, v28, v42
	v_mul_f32_e32 v42, 0x4038aa3b, v25
	v_exp_f32_e32 v42, v42
	v_add_f32_e32 v4, 1.0, v4
	v_add_f32_e32 v1, 1.0, v1
	v_fmac_f32_e32 v159, 0xbfb8aa3b, v5
	v_sub_f32_e32 v42, 1.0, v42
	v_sqrt_f32_e32 v42, v42
	v_rcp_f32_e32 v4, v4
	v_exp_f32_e32 v5, v159
	v_rcp_f32_e32 v1, v1
	v_mul_f32_e32 v29, v29, v42
	v_fmamk_f32 v2, v2, 0xbfb8aa3b, v152
	v_exp_f32_e32 v2, v2
	v_fmamk_f32 v10, v10, 0xbfb8aa3b, v146
	v_exp_f32_e32 v10, v10
	v_fmamk_f32 v6, v6, 0xbfb8aa3b, v154
	v_add_f32_e32 v2, 1.0, v2
	v_rcp_f32_e32 v2, v2
	v_add_f32_e32 v10, 1.0, v10
	v_rcp_f32_e32 v10, v10
	v_exp_f32_e32 v6, v6
	v_fmamk_f32 v14, v14, 0xbfb8aa3b, v144
	v_exp_f32_e32 v14, v14
	v_mul_f32_e32 v10, v10, v172
	s_andn2_b64 vcc, exec, s[8:9]
	s_mov_b64 s[8:9], -1
	v_add_f32_e32 v14, 1.0, v14
	v_rcp_f32_e32 v14, v14
	v_lshlrev_b32_e32 v38, 16, v32
	v_and_b32_e32 v32, 0xffff0000, v32
	v_mul_f32_e32 v29, v29, v32
	v_mul_f32_e32 v32, 0x4038aa3b, v27
	v_exp_f32_e32 v32, v32
	v_lshlrev_b32_e32 v39, 16, v33
	v_and_b32_e32 v33, 0xffff0000, v33
	v_lshlrev_b32_e32 v40, 16, v34
	v_sub_f32_e32 v32, 1.0, v32
	v_sqrt_f32_e32 v32, v32
	v_mul_f32_e32 v28, v28, v38
	v_mul_f32_e32 v38, 0x4038aa3b, v26
	v_exp_f32_e32 v38, v38
	v_mul_f32_e32 v31, v31, v32
	v_mul_f32_e32 v32, v16, v128
	v_mul_f32_e32 v16, 0x4038aa3b, v32
	v_exp_f32_e32 v16, v16
	v_mul_f32_e32 v31, v31, v33
	v_sub_f32_e32 v38, 1.0, v38
	v_sqrt_f32_e32 v38, v38
	v_sub_f32_e32 v16, 1.0, v16
	v_sqrt_f32_e32 v16, v16
	v_and_b32_e32 v34, 0xffff0000, v34
	v_lshlrev_b32_e32 v41, 16, v35
	v_and_b32_e32 v35, 0xffff0000, v35
	v_mul_f32_e32 v16, v20, v16
	v_add_f32_e32 v20, 1.0, v21
	v_mul_f32_e32 v21, v17, v129
	v_mul_f32_e32 v17, 0x4038aa3b, v21
	v_exp_f32_e32 v17, v17
	v_rcp_f32_e32 v20, v20
	v_mul_f32_e32 v33, v16, v40
	v_mul_f32_e32 v30, v30, v38
	v_sub_f32_e32 v17, 1.0, v17
	v_sqrt_f32_e32 v17, v17
	v_mul_f32_e32 v30, v30, v39
	v_mul_f32_e32 v16, v20, v17
	v_mul_f32_e32 v20, v18, v165
	v_fmamk_f32 v18, v19, 0xbfb8aa3b, v153
	v_exp_f32_e32 v18, v18
	v_add_f32_e32 v17, 1.0, v22
	v_mul_f32_e32 v19, 0x4038aa3b, v20
	v_fmamk_f32 v22, v23, 0xbfb8aa3b, v155
	v_add_f32_e32 v18, 1.0, v18
	v_rcp_f32_e32 v18, v18
	v_exp_f32_e32 v19, v19
	v_exp_f32_e32 v22, v22
	v_rcp_f32_e32 v17, v17
	v_mul_f32_e32 v23, v18, v130
	v_mul_f32_e32 v18, 0x4038aa3b, v23
	v_exp_f32_e32 v18, v18
	v_sub_f32_e32 v19, 1.0, v19
	v_sqrt_f32_e32 v19, v19
	v_add_f32_e32 v22, 1.0, v22
	v_sub_f32_e32 v18, 1.0, v18
	v_rcp_f32_e32 v22, v22
	v_sqrt_f32_e32 v18, v18
	v_mul_f32_e32 v34, v16, v34
	v_mul_f32_e32 v16, v17, v19
	v_mul_f32_e32 v38, v16, v41
	v_mul_f32_e32 v16, v22, v18
	v_mul_f32_e32 v22, v16, v35
	v_cvt_pk_bf16_f32 v16, v24, v25
	v_cvt_pk_bf16_f32 v17, v26, v27
	v_cvt_pk_bf16_f32 v18, v32, v21
	v_cvt_pk_bf16_f32 v19, v20, v23
	v_lshl_add_u64 v[20:21], s[26:27], 0, v[36:37]
	global_store_dwordx4 v[20:21], v[16:19], off
	v_lshl_add_u64 v[20:21], s[28:29], 0, v[36:37]
	v_mul_f32_e32 v26, 0x4038aa3b, v8
	v_cvt_pk_bf16_f32 v16, v28, v29
	v_cvt_pk_bf16_f32 v17, v30, v31
	v_cvt_pk_bf16_f32 v18, v33, v34
	v_cvt_pk_bf16_f32 v19, v38, v22
	global_store_dwordx4 v[20:21], v[16:19], off
	v_lshl_add_u64 v[20:21], v[160:161], 0, s[58:59]
	v_exp_f32_e32 v26, v26
	v_lshl_add_u64 v[16:17], s[20:21], 0, v[20:21]
	s_nop 1
	v_mov_b32_e32 v16, v236
	v_mov_b32_e32 v17, v237
	v_mov_b32_e32 v18, v238
	v_mov_b32_e32 v19, v239
	v_fmac_f32_e32 v153, 0xbfb8aa3b, v3
	v_sub_f32_e32 v26, 1.0, v26
	v_sqrt_f32_e32 v26, v26
	v_fmac_f32_e32 v155, 0xbfb8aa3b, v7
	v_mul_f32_e32 v12, v12, v26
	v_mul_f32_e32 v26, 0x4038aa3b, v9
	v_exp_f32_e32 v26, v26
	v_lshlrev_b32_e32 v22, 16, v16
	v_sub_f32_e32 v26, 1.0, v26
	v_sqrt_f32_e32 v26, v26
	v_and_b32_e32 v16, 0xffff0000, v16
	v_lshlrev_b32_e32 v23, 16, v17
	v_and_b32_e32 v17, 0xffff0000, v17
	v_mul_f32_e32 v13, v13, v26
	v_mul_f32_e32 v13, v13, v16
	v_mul_f32_e32 v16, 0x4038aa3b, v11
	v_exp_f32_e32 v16, v16
	v_lshlrev_b32_e32 v24, 16, v18
	v_mul_f32_e32 v12, v12, v22
	v_mul_f32_e32 v22, 0x4038aa3b, v10
	v_sub_f32_e32 v16, 1.0, v16
	v_sqrt_f32_e32 v16, v16
	v_exp_f32_e32 v22, v22
	v_and_b32_e32 v18, 0xffff0000, v18
	v_lshlrev_b32_e32 v25, 16, v19
	v_mul_f32_e32 v15, v15, v16
	v_mul_f32_e32 v16, v0, v128
	v_mul_f32_e32 v0, 0x4038aa3b, v16
	v_exp_f32_e32 v0, v0
	v_mul_f32_e32 v15, v15, v17
	v_sub_f32_e32 v22, 1.0, v22
	v_sqrt_f32_e32 v22, v22
	v_sub_f32_e32 v0, 1.0, v0
	v_sqrt_f32_e32 v0, v0
	v_and_b32_e32 v19, 0xffff0000, v19
	v_mul_f32_e32 v14, v14, v22
	v_mul_f32_e32 v14, v14, v23
	v_mul_f32_e32 v0, v4, v0
	v_add_f32_e32 v4, 1.0, v5
	v_mul_f32_e32 v5, v1, v129
	v_mul_f32_e32 v1, 0x4038aa3b, v5
	v_exp_f32_e32 v1, v1
	v_rcp_f32_e32 v4, v4
	v_mul_f32_e32 v17, v0, v24
	v_sub_f32_e32 v1, 1.0, v1
	v_sqrt_f32_e32 v1, v1
	s_nop 0
	v_mul_f32_e32 v0, v4, v1
	v_mul_f32_e32 v4, v2, v165
	v_exp_f32_e32 v2, v153
	v_mul_f32_e32 v3, 0x4038aa3b, v4
	v_exp_f32_e32 v3, v3
	v_add_f32_e32 v1, 1.0, v6
	v_add_f32_e32 v2, 1.0, v2
	v_rcp_f32_e32 v2, v2
	v_exp_f32_e32 v6, v155
	v_sub_f32_e32 v3, 1.0, v3
	v_rcp_f32_e32 v1, v1
	v_mul_f32_e32 v7, v2, v130
	v_mul_f32_e32 v2, 0x4038aa3b, v7
	v_exp_f32_e32 v2, v2
	v_sqrt_f32_e32 v3, v3
	v_add_f32_e32 v6, 1.0, v6
	v_rcp_f32_e32 v6, v6
	v_sub_f32_e32 v2, 1.0, v2
	v_sqrt_f32_e32 v2, v2
	v_mul_f32_e32 v18, v0, v18
	v_mul_f32_e32 v0, v1, v3
	v_mul_f32_e32 v22, v0, v25
	v_mul_f32_e32 v0, v6, v2
	v_mul_f32_e32 v6, v0, v19
	v_cvt_pk_bf16_f32 v0, v8, v9
	v_cvt_pk_bf16_f32 v1, v10, v11
	v_cvt_pk_bf16_f32 v2, v16, v5
	v_cvt_pk_bf16_f32 v3, v4, v7
	v_lshl_add_u64 v[4:5], s[26:27], 0, v[20:21]
	global_store_dwordx4 v[4:5], v[0:3], off
	v_lshl_add_u64 v[4:5], s[28:29], 0, v[20:21]
	s_nop 0
	v_cvt_pk_bf16_f32 v0, v12, v13
	v_cvt_pk_bf16_f32 v1, v14, v15
	v_cvt_pk_bf16_f32 v2, v17, v18
	v_cvt_pk_bf16_f32 v3, v22, v6
	global_store_dwordx4 v[4:5], v[0:3], off
	s_cbranch_vccnz .LBB0_1034
	v_readlane_b32 s4, v250, 11
	v_readlane_b32 s5, v250, 12
	s_and_b64 vcc, exec, s[4:5]
	s_cbranch_vccnz .LBB0_1033
	s_barrier
	s_branch .LBB0_1033
